# v7 + MFMA snake order inside each 8-MFMA k-block (operand reuse between consecutive MFMAs; same per-accumulator order)
# baseline (speedup 1.0000x reference)
; #define PG8_STAGE(bufoff, gbase, voff) do { _Pragma("unroll") for (int _i = 0; _i < 2; ++_i) \
;         __builtin_amdgcn_global_load_lds((const unsigned*)((const char*)(gbase) + (voff)[_i]), (PG8_LAS unsigned*)(lds + (bufoff) + ldsw + _i * 8192), 16, 0, 0); } while (0)
; #define PG8_LDA(dst, b, h) do { _Pragma("unroll") for (int m = 0; m < 4; ++m) _Pragma("unroll") for (int k = 0; k < 2; ++k) dst[m][k] = *(const PG8_LAS bf16x8*)(lds + PG8_SA(b, h) + aoff + m * 2048 + k * 1024); } while (0)
; #define PG8_MMA(ai, bj, At, Bt) do { __builtin_amdgcn_s_setprio(3); _Pragma("unroll") for (int m = 0; m < 4; ++m) _Pragma("unroll") for (int n = 0; n < 2; ++n) _Pragma("unroll") for (int k = 0; k < 2; ++k) \
;         acc[ai][bj][m][n] = __builtin_amdgcn_mfma_f32_16x16x32_bf16(Bt[n][k], At[m][k], acc[ai][bj][m][n], 0, 0, 0); __builtin_amdgcn_s_setprio(0); } while (0)
; #define PG8_WAIT_V(n) asm volatile("s_waitcnt vmcnt(" #n ")" ::: "memory")
; #define PG8_WAIT_L(n) asm volatile("s_waitcnt lgkmcnt(" #n ")" ::: "memory")
; #define PG8_BAR __builtin_amdgcn_s_barrier()
; #define PG8_SCHED __builtin_amdgcn_sched_barrier(0)
; template <class Epi, class Sched, bool ALIGN_EPI = false, bool SP2 = false>
; __device__ __forceinline__ void gemm_phase(PG8_LAS unsigned char* lds, const Gemm g, const Sched& S, const Epi& E) {
;     ...
;             PG8_WAIT_V(8); PG8_WAIT_L(0); PG8_BAR; PG8_MMA(0, 0, At, B0); PG8_MMA(0, 1, At, B1); PG8_BAR; PG8_SCHED;
;             PG8_LDA(At, 0, 1); PG8_STAGE(PG8_SB(0, 0), b2, voffB); PG8_STAGE(PG8_SB(0, 1), b2 + hstepB, voffB); PG8_STAGE(PG8_SA(0, 0), a2, voffA);
.Lengw1_e:
	s_waitcnt lgkmcnt(0)
	s_barrier
	s_setprio 3
	s_waitcnt lgkmcnt(0)
	v_mfma_f32_16x16x32_bf16 v[126:129], v[130:133], v[192:195], v[126:129]
	v_mfma_f32_16x16x32_bf16 v[118:121], v[156:159], v[192:195], v[118:121]
	v_mfma_f32_16x16x32_bf16 v[102:105], v[156:159], v[200:203], v[102:105]
	v_mfma_f32_16x16x32_bf16 v[110:113], v[130:133], v[200:203], v[110:113]
	v_mfma_f32_16x16x32_bf16 v[94:97], v[130:133], v[208:211], v[94:97]
	v_mfma_f32_16x16x32_bf16 v[86:89], v[156:159], v[208:211], v[86:89]
	v_mfma_f32_16x16x32_bf16 v[70:73], v[156:159], v[216:219], v[70:73]
	v_mfma_f32_16x16x32_bf16 v[78:81], v[130:133], v[216:219], v[78:81]
	v_mfma_f32_16x16x32_bf16 v[126:129], v[134:137], v[196:199], v[126:129]
	v_mfma_f32_16x16x32_bf16 v[118:121], v[172:175], v[196:199], v[118:121]
	v_mfma_f32_16x16x32_bf16 v[102:105], v[172:175], v[204:207], v[102:105]
	v_mfma_f32_16x16x32_bf16 v[110:113], v[134:137], v[204:207], v[110:113]
	v_mfma_f32_16x16x32_bf16 v[94:97], v[134:137], v[212:215], v[94:97]
	v_mfma_f32_16x16x32_bf16 v[86:89], v[172:175], v[212:215], v[86:89]
	v_mfma_f32_16x16x32_bf16 v[70:73], v[172:175], v[220:223], v[70:73]
	v_mfma_f32_16x16x32_bf16 v[78:81], v[134:137], v[220:223], v[78:81]
	s_setprio 0
	s_setprio 3
	v_mfma_f32_16x16x32_bf16 v[122:125], v[176:179], v[192:195], v[122:125]
	v_mfma_f32_16x16x32_bf16 v[114:117], v[184:187], v[192:195], v[114:117]
	v_mfma_f32_16x16x32_bf16 v[98:101], v[184:187], v[200:203], v[98:101]
	v_mfma_f32_16x16x32_bf16 v[106:109], v[176:179], v[200:203], v[106:109]
	v_mfma_f32_16x16x32_bf16 v[90:93], v[176:179], v[208:211], v[90:93]
	v_mfma_f32_16x16x32_bf16 v[82:85], v[184:187], v[208:211], v[82:85]
	v_mfma_f32_16x16x32_bf16 v[66:69], v[184:187], v[216:219], v[66:69]
	v_mfma_f32_16x16x32_bf16 v[74:77], v[176:179], v[216:219], v[74:77]
	v_mfma_f32_16x16x32_bf16 v[122:125], v[180:183], v[196:199], v[122:125]
	v_mfma_f32_16x16x32_bf16 v[114:117], v[188:191], v[196:199], v[114:117]
	v_mfma_f32_16x16x32_bf16 v[98:101], v[188:191], v[204:207], v[98:101]
	v_mfma_f32_16x16x32_bf16 v[106:109], v[180:183], v[204:207], v[106:109]
	v_mfma_f32_16x16x32_bf16 v[90:93], v[180:183], v[212:215], v[90:93]
	v_mfma_f32_16x16x32_bf16 v[82:85], v[188:191], v[212:215], v[82:85]
	v_mfma_f32_16x16x32_bf16 v[66:69], v[188:191], v[220:223], v[66:69]
	v_mfma_f32_16x16x32_bf16 v[74:77], v[180:183], v[220:223], v[74:77]
	s_setprio 0
	s_barrier
	s_add_i32 s56, s83, s66
	v_lshl_add_u64 v[160:161], s[8:9], 0, v[140:141]
	s_mov_b32 m0, s56
	ds_read_b128 v[192:195], v169 offset:16384
	ds_read_b128 v[196:199], v169 offset:17408
	ds_read_b128 v[200:203], v169 offset:18432
	ds_read_b128 v[204:207], v169 offset:19456
	ds_read_b128 v[208:211], v169 offset:20480
	ds_read_b128 v[212:215], v169 offset:21504
	ds_read_b128 v[216:219], v169 offset:22528
	ds_read_b128 v[220:223], v169 offset:23552
	global_load_lds_dwordx4 v[160:161], off
	s_add_i32 m0, s56, 0x2000
	s_add_u32 s56, s8, 0x100000
	v_lshl_add_u64 v[224:225], s[8:9], 0, v[144:145]
	s_addc_u32 s57, s9, 0
	s_add_i32 s58, s89, s66
	global_load_lds_dwordx4 v[224:225], off
	v_lshl_add_u64 v[226:227], s[56:57], 0, v[140:141]
	s_mov_b32 m0, s58
	v_lshl_add_u64 v[228:229], s[36:37], 0, v[142:143]
	global_load_lds_dwordx4 v[226:227], off
	v_lshl_add_u64 v[226:227], s[56:57], 0, v[144:145]
	s_add_i32 m0, s58, 0x2000
	s_nop 0
	global_load_lds_dwordx4 v[226:227], off
	v_lshl_add_u64 v[226:227], s[36:37], 0, v[138:139]
	s_mov_b32 m0, s55
	s_nop 0
	global_load_lds_dwordx4 v[226:227], off
	s_mov_b32 m0, s67
	s_nop 0
	global_load_lds_dwordx4 v[228:229], off
	s_cmp_eq_u32 s97, 0
	s_cbranch_scc1 .Lengw2_a
	s_cmp_eq_u32 s97, 2
	s_cbranch_scc1 .Lengw2_b
	s_cmp_eq_u32 s97, 4
	s_cbranch_scc1 .Lengw2_c
	s_waitcnt vmcnt(16)
	s_branch .Lengw2_e

; #define PG8_STAGE(bufoff, gbase, voff) do { _Pragma("unroll") for (int _i = 0; _i < 2; ++_i) \
;         __builtin_amdgcn_global_load_lds((const unsigned*)((const char*)(gbase) + (voff)[_i]), (PG8_LAS unsigned*)(lds + (bufoff) + ldsw + _i * 8192), 16, 0, 0); } while (0)
; #define PG8_LDA(dst, b, h) do { _Pragma("unroll") for (int m = 0; m < 4; ++m) _Pragma("unroll") for (int k = 0; k < 2; ++k) dst[m][k] = *(const PG8_LAS bf16x8*)(lds + PG8_SA(b, h) + aoff + m * 2048 + k * 1024); } while (0)
; #define PG8_LDB(dst, b, h) do { _Pragma("unroll") for (int n = 0; n < 2; ++n) _Pragma("unroll") for (int k = 0; k < 2; ++k) dst[n][k] = *(const PG8_LAS bf16x8*)(lds + PG8_SB(b, h) + boff + n * 2048 + k * 1024); } while (0)
; #define PG8_MMA(ai, bj, At, Bt) do { __builtin_amdgcn_s_setprio(3); _Pragma("unroll") for (int m = 0; m < 4; ++m) _Pragma("unroll") for (int n = 0; n < 2; ++n) _Pragma("unroll") for (int k = 0; k < 2; ++k) \
;         acc[ai][bj][m][n] = __builtin_amdgcn_mfma_f32_16x16x32_bf16(Bt[n][k], At[m][k], acc[ai][bj][m][n], 0, 0, 0); __builtin_amdgcn_s_setprio(0); } while (0)
; #define PG8_WAIT_V(n) asm volatile("s_waitcnt vmcnt(" #n ")" ::: "memory")
; #define PG8_WAIT_L(n) asm volatile("s_waitcnt lgkmcnt(" #n ")" ::: "memory")
; #define PG8_BAR __builtin_amdgcn_s_barrier()
; #define PG8_SCHED __builtin_amdgcn_sched_barrier(0)
; template <class Epi, class Sched, bool ALIGN_EPI = false, bool SP2 = false>
; __device__ __forceinline__ void gemm_phase(PG8_LAS unsigned char* lds, const Gemm g, const Sched& S, const Epi& E) {
;     ...
;             PG8_WAIT_V(8); PG8_WAIT_L(0); PG8_BAR; PG8_MMA(1, 0, At, B0); PG8_MMA(1, 1, At, B1); PG8_BAR; PG8_SCHED;
;             PG8_LDB(B0, 1, 0); PG8_LDB(B1, 1, 1); PG8_SCHED; PG8_LDA(At, 1, 0); PG8_STAGE(PG8_SA(0, 1), a2 + hstepA, voffA);
;             PG8_WAIT_V(8); PG8_WAIT_L(0); PG8_BAR; PG8_MMA(0, 0, At, B0); PG8_MMA(0, 1, At, B1); PG8_BAR; PG8_SCHED;
.Lengw2_e:
	s_waitcnt lgkmcnt(0)
	s_barrier
	s_setprio 3
	s_waitcnt lgkmcnt(0)
	v_mfma_f32_16x16x32_bf16 v[62:65], v[130:133], v[192:195], v[62:65]
	v_mfma_f32_16x16x32_bf16 v[54:57], v[156:159], v[192:195], v[54:57]
	v_mfma_f32_16x16x32_bf16 v[38:41], v[156:159], v[200:203], v[38:41]
	v_mfma_f32_16x16x32_bf16 v[46:49], v[130:133], v[200:203], v[46:49]
	v_mfma_f32_16x16x32_bf16 v[30:33], v[130:133], v[208:211], v[30:33]
	v_mfma_f32_16x16x32_bf16 v[22:25], v[156:159], v[208:211], v[22:25]
	v_mfma_f32_16x16x32_bf16 v[6:9], v[156:159], v[216:219], v[6:9]
	v_mfma_f32_16x16x32_bf16 v[14:17], v[130:133], v[216:219], v[14:17]
	v_mfma_f32_16x16x32_bf16 v[62:65], v[134:137], v[196:199], v[62:65]
	v_mfma_f32_16x16x32_bf16 v[54:57], v[172:175], v[196:199], v[54:57]
	v_mfma_f32_16x16x32_bf16 v[38:41], v[172:175], v[204:207], v[38:41]
	v_mfma_f32_16x16x32_bf16 v[46:49], v[134:137], v[204:207], v[46:49]
	v_mfma_f32_16x16x32_bf16 v[30:33], v[134:137], v[212:215], v[30:33]
	v_mfma_f32_16x16x32_bf16 v[22:25], v[172:175], v[212:215], v[22:25]
	v_mfma_f32_16x16x32_bf16 v[6:9], v[172:175], v[220:223], v[6:9]
	v_mfma_f32_16x16x32_bf16 v[14:17], v[134:137], v[220:223], v[14:17]
	s_setprio 0
	s_setprio 3
	v_mfma_f32_16x16x32_bf16 v[58:61], v[176:179], v[192:195], v[58:61]
	v_mfma_f32_16x16x32_bf16 v[50:53], v[184:187], v[192:195], v[50:53]
	v_mfma_f32_16x16x32_bf16 v[34:37], v[184:187], v[200:203], v[34:37]
	v_mfma_f32_16x16x32_bf16 v[42:45], v[176:179], v[200:203], v[42:45]
	v_mfma_f32_16x16x32_bf16 v[26:29], v[176:179], v[208:211], v[26:29]
	v_mfma_f32_16x16x32_bf16 v[18:21], v[184:187], v[208:211], v[18:21]
	v_mfma_f32_16x16x32_bf16 v[2:5], v[184:187], v[216:219], v[2:5]
	v_mfma_f32_16x16x32_bf16 v[10:13], v[176:179], v[216:219], v[10:13]
	v_mfma_f32_16x16x32_bf16 v[58:61], v[180:183], v[196:199], v[58:61]
	v_mfma_f32_16x16x32_bf16 v[50:53], v[188:191], v[196:199], v[50:53]
	v_mfma_f32_16x16x32_bf16 v[34:37], v[188:191], v[204:207], v[34:37]
	v_mfma_f32_16x16x32_bf16 v[42:45], v[180:183], v[204:207], v[42:45]
	v_mfma_f32_16x16x32_bf16 v[26:29], v[180:183], v[212:215], v[26:29]
	v_mfma_f32_16x16x32_bf16 v[18:21], v[188:191], v[212:215], v[18:21]
	v_mfma_f32_16x16x32_bf16 v[2:5], v[188:191], v[220:223], v[2:5]
	v_mfma_f32_16x16x32_bf16 v[10:13], v[180:183], v[220:223], v[10:13]
	s_setprio 0
	s_barrier
	s_add_i32 s56, 0, 0x18000
	v_add_u32_e32 v146, s56, v164
	s_add_i32 s57, 0, 0x1c000
	ds_read_b128 v[130:133], v146
	ds_read_b128 v[134:137], v146 offset:1024
	ds_read_b128 v[156:159], v146 offset:2048
	ds_read_b128 v[172:175], v146 offset:3072
	v_add_u32_e32 v146, s57, v164
	ds_read_b128 v[176:179], v146
	ds_read_b128 v[180:183], v146 offset:1024
	ds_read_b128 v[184:187], v146 offset:2048
	ds_read_b128 v[188:191], v146 offset:3072
	s_add_u32 s36, s36, 0x100000
	s_addc_u32 s37, s37, 0
	s_mov_b32 m0, s72
	v_lshl_add_u64 v[230:231], s[36:37], 0, v[138:139]
	ds_read_b128 v[192:195], v169 offset:32768
	ds_read_b128 v[196:199], v169 offset:33792
	ds_read_b128 v[200:203], v169 offset:34816
	ds_read_b128 v[204:207], v169 offset:35840
	ds_read_b128 v[208:211], v169 offset:36864
	ds_read_b128 v[212:215], v169 offset:37888
	ds_read_b128 v[216:219], v169 offset:38912
	ds_read_b128 v[220:223], v169 offset:39936
	global_load_lds_dwordx4 v[230:231], off
	v_lshl_add_u64 v[230:231], s[36:37], 0, v[142:143]
	s_mov_b32 m0, s73
	s_nop 0
	global_load_lds_dwordx4 v[230:231], off
	s_cmp_eq_u32 s97, 4
	s_cbranch_scc1 .Lengw3_c
	s_cmp_eq_u32 s97, 8
	s_cbranch_scc1 .Lengw3_d
	s_waitcnt vmcnt(8)
	s_branch .Lengw3_e

; #define PG8_STAGE(bufoff, gbase, voff) do { _Pragma("unroll") for (int _i = 0; _i < 2; ++_i) \
;         __builtin_amdgcn_global_load_lds((const unsigned*)((const char*)(gbase) + (voff)[_i]), (PG8_LAS unsigned*)(lds + (bufoff) + ldsw + _i * 8192), 16, 0, 0); } while (0)
; #define PG8_LDA(dst, b, h) do { _Pragma("unroll") for (int m = 0; m < 4; ++m) _Pragma("unroll") for (int k = 0; k < 2; ++k) dst[m][k] = *(const PG8_LAS bf16x8*)(lds + PG8_SA(b, h) + aoff + m * 2048 + k * 1024); } while (0)
; #define PG8_MMA(ai, bj, At, Bt) do { __builtin_amdgcn_s_setprio(3); _Pragma("unroll") for (int m = 0; m < 4; ++m) _Pragma("unroll") for (int n = 0; n < 2; ++n) _Pragma("unroll") for (int k = 0; k < 2; ++k) \
;         acc[ai][bj][m][n] = __builtin_amdgcn_mfma_f32_16x16x32_bf16(Bt[n][k], At[m][k], acc[ai][bj][m][n], 0, 0, 0); __builtin_amdgcn_s_setprio(0); } while (0)
; #define PG8_WAIT_V(n) asm volatile("s_waitcnt vmcnt(" #n ")" ::: "memory")
; #define PG8_WAIT_L(n) asm volatile("s_waitcnt lgkmcnt(" #n ")" ::: "memory")
; #define PG8_BAR __builtin_amdgcn_s_barrier()
; #define PG8_SCHED __builtin_amdgcn_sched_barrier(0)
; template <class Epi, class Sched, bool ALIGN_EPI = false, bool SP2 = false>
; __device__ __forceinline__ void gemm_phase(PG8_LAS unsigned char* lds, const Gemm g, const Sched& S, const Epi& E) {
;     ...
;             PG8_WAIT_V(8); PG8_WAIT_L(0); PG8_BAR; PG8_MMA(0, 0, At, B0); PG8_MMA(0, 1, At, B1); PG8_BAR; PG8_SCHED;
;             PG8_LDA(At, 1, 1); PG8_STAGE(PG8_SB(1, 0), b3, voffB); PG8_STAGE(PG8_SB(1, 1), b3 + hstepB, voffB); PG8_STAGE(PG8_SA(1, 0), a3, voffA);
;             PG8_WAIT_V(8); PG8_WAIT_L(0); PG8_BAR; PG8_MMA(1, 0, At, B0); PG8_MMA(1, 1, At, B1); PG8_BAR; PG8_SCHED;
.Lengw3_e:
	s_waitcnt lgkmcnt(0)
	s_barrier
	s_setprio 3
	s_waitcnt lgkmcnt(0)
	v_mfma_f32_16x16x32_bf16 v[126:129], v[130:133], v[192:195], v[126:129]
	v_mfma_f32_16x16x32_bf16 v[118:121], v[156:159], v[192:195], v[118:121]
	v_mfma_f32_16x16x32_bf16 v[102:105], v[156:159], v[200:203], v[102:105]
	v_mfma_f32_16x16x32_bf16 v[110:113], v[130:133], v[200:203], v[110:113]
	v_mfma_f32_16x16x32_bf16 v[94:97], v[130:133], v[208:211], v[94:97]
	v_mfma_f32_16x16x32_bf16 v[86:89], v[156:159], v[208:211], v[86:89]
	v_mfma_f32_16x16x32_bf16 v[70:73], v[156:159], v[216:219], v[70:73]
	v_mfma_f32_16x16x32_bf16 v[78:81], v[130:133], v[216:219], v[78:81]
	v_mfma_f32_16x16x32_bf16 v[126:129], v[134:137], v[196:199], v[126:129]
	v_mfma_f32_16x16x32_bf16 v[118:121], v[172:175], v[196:199], v[118:121]
	v_mfma_f32_16x16x32_bf16 v[102:105], v[172:175], v[204:207], v[102:105]
	v_mfma_f32_16x16x32_bf16 v[110:113], v[134:137], v[204:207], v[110:113]
	v_mfma_f32_16x16x32_bf16 v[94:97], v[134:137], v[212:215], v[94:97]
	v_mfma_f32_16x16x32_bf16 v[86:89], v[172:175], v[212:215], v[86:89]
	v_mfma_f32_16x16x32_bf16 v[70:73], v[172:175], v[220:223], v[70:73]
	v_mfma_f32_16x16x32_bf16 v[78:81], v[134:137], v[220:223], v[78:81]
	s_setprio 0
	s_setprio 3
	v_mfma_f32_16x16x32_bf16 v[122:125], v[176:179], v[192:195], v[122:125]
	v_mfma_f32_16x16x32_bf16 v[114:117], v[184:187], v[192:195], v[114:117]
	v_mfma_f32_16x16x32_bf16 v[98:101], v[184:187], v[200:203], v[98:101]
	v_mfma_f32_16x16x32_bf16 v[106:109], v[176:179], v[200:203], v[106:109]
	v_mfma_f32_16x16x32_bf16 v[90:93], v[176:179], v[208:211], v[90:93]
	v_mfma_f32_16x16x32_bf16 v[82:85], v[184:187], v[208:211], v[82:85]
	v_mfma_f32_16x16x32_bf16 v[66:69], v[184:187], v[216:219], v[66:69]
	v_mfma_f32_16x16x32_bf16 v[74:77], v[176:179], v[216:219], v[74:77]
	v_mfma_f32_16x16x32_bf16 v[122:125], v[180:183], v[196:199], v[122:125]
	v_mfma_f32_16x16x32_bf16 v[114:117], v[188:191], v[196:199], v[114:117]
	v_mfma_f32_16x16x32_bf16 v[98:101], v[188:191], v[204:207], v[98:101]
	v_mfma_f32_16x16x32_bf16 v[106:109], v[180:183], v[204:207], v[106:109]
	v_mfma_f32_16x16x32_bf16 v[90:93], v[180:183], v[212:215], v[90:93]
	v_mfma_f32_16x16x32_bf16 v[82:85], v[188:191], v[212:215], v[82:85]
	v_mfma_f32_16x16x32_bf16 v[66:69], v[188:191], v[220:223], v[66:69]
	v_mfma_f32_16x16x32_bf16 v[74:77], v[180:183], v[220:223], v[74:77]
	s_setprio 0
	s_barrier
	s_add_i32 s36, s56, s66
	v_lshl_add_u64 v[160:161], v[160:161], 0, s[18:19]
	s_mov_b32 m0, s36
	ds_read_b128 v[192:195], v169 offset:49152
	ds_read_b128 v[196:199], v169 offset:50176
	ds_read_b128 v[200:203], v169 offset:51200
	ds_read_b128 v[204:207], v169 offset:52224
	ds_read_b128 v[208:211], v169 offset:53248
	ds_read_b128 v[212:215], v169 offset:54272
	ds_read_b128 v[216:219], v169 offset:55296
	ds_read_b128 v[220:223], v169 offset:56320
	global_load_lds_dwordx4 v[160:161], off
	s_add_i32 m0, s36, 0x2000
	s_add_u32 s8, s8, 0x100080
	v_lshl_add_u64 v[160:161], v[224:225], 0, s[18:19]
	s_addc_u32 s9, s9, 0
	s_add_i32 s36, s57, s66
	global_load_lds_dwordx4 v[160:161], off
	v_lshl_add_u64 v[160:161], s[8:9], 0, v[140:141]
	s_mov_b32 m0, s36
	s_nop 0
	global_load_lds_dwordx4 v[160:161], off
	v_lshl_add_u64 v[160:161], s[8:9], 0, v[144:145]
	s_add_i32 m0, s36, 0x2000
	s_nop 0
	global_load_lds_dwordx4 v[160:161], off
	v_lshl_add_u64 v[160:161], v[226:227], 0, s[18:19]
	s_mov_b32 m0, s75
	s_nop 0
	global_load_lds_dwordx4 v[160:161], off
	v_lshl_add_u64 v[160:161], v[228:229], 0, s[18:19]
	s_mov_b32 m0, s76
	s_nop 0
	global_load_lds_dwordx4 v[160:161], off
	s_waitcnt vmcnt(8)
	s_waitcnt lgkmcnt(0)
	s_barrier
	s_setprio 3
	s_waitcnt lgkmcnt(0)
	v_mfma_f32_16x16x32_bf16 v[62:65], v[130:133], v[192:195], v[62:65]
	v_mfma_f32_16x16x32_bf16 v[54:57], v[156:159], v[192:195], v[54:57]
	v_mfma_f32_16x16x32_bf16 v[38:41], v[156:159], v[200:203], v[38:41]
	v_mfma_f32_16x16x32_bf16 v[46:49], v[130:133], v[200:203], v[46:49]
	v_mfma_f32_16x16x32_bf16 v[30:33], v[130:133], v[208:211], v[30:33]
	v_mfma_f32_16x16x32_bf16 v[22:25], v[156:159], v[208:211], v[22:25]
	v_mfma_f32_16x16x32_bf16 v[6:9], v[156:159], v[216:219], v[6:9]
	v_mfma_f32_16x16x32_bf16 v[14:17], v[130:133], v[216:219], v[14:17]
	v_mfma_f32_16x16x32_bf16 v[62:65], v[134:137], v[196:199], v[62:65]
	v_mfma_f32_16x16x32_bf16 v[54:57], v[172:175], v[196:199], v[54:57]
	v_mfma_f32_16x16x32_bf16 v[38:41], v[172:175], v[204:207], v[38:41]
	v_mfma_f32_16x16x32_bf16 v[46:49], v[134:137], v[204:207], v[46:49]
	v_mfma_f32_16x16x32_bf16 v[30:33], v[134:137], v[212:215], v[30:33]
	v_mfma_f32_16x16x32_bf16 v[22:25], v[172:175], v[212:215], v[22:25]
	v_mfma_f32_16x16x32_bf16 v[6:9], v[172:175], v[220:223], v[6:9]
	v_mfma_f32_16x16x32_bf16 v[14:17], v[134:137], v[220:223], v[14:17]
	s_setprio 0
	s_setprio 3
	v_mfma_f32_16x16x32_bf16 v[58:61], v[176:179], v[192:195], v[58:61]
	v_mfma_f32_16x16x32_bf16 v[50:53], v[184:187], v[192:195], v[50:53]
	v_mfma_f32_16x16x32_bf16 v[34:37], v[184:187], v[200:203], v[34:37]
	v_mfma_f32_16x16x32_bf16 v[42:45], v[176:179], v[200:203], v[42:45]
	v_mfma_f32_16x16x32_bf16 v[26:29], v[176:179], v[208:211], v[26:29]
	v_mfma_f32_16x16x32_bf16 v[18:21], v[184:187], v[208:211], v[18:21]
	v_mfma_f32_16x16x32_bf16 v[2:5], v[184:187], v[216:219], v[2:5]
	v_mfma_f32_16x16x32_bf16 v[10:13], v[176:179], v[216:219], v[10:13]
	v_mfma_f32_16x16x32_bf16 v[58:61], v[180:183], v[196:199], v[58:61]
	v_mfma_f32_16x16x32_bf16 v[50:53], v[188:191], v[196:199], v[50:53]
	v_mfma_f32_16x16x32_bf16 v[34:37], v[188:191], v[204:207], v[34:37]
	v_mfma_f32_16x16x32_bf16 v[42:45], v[180:183], v[204:207], v[42:45]
	v_mfma_f32_16x16x32_bf16 v[26:29], v[180:183], v[212:215], v[26:29]
	v_mfma_f32_16x16x32_bf16 v[18:21], v[188:191], v[212:215], v[18:21]
	v_mfma_f32_16x16x32_bf16 v[2:5], v[188:191], v[220:223], v[2:5]
	v_mfma_f32_16x16x32_bf16 v[10:13], v[180:183], v[220:223], v[10:13]
	s_setprio 0
	s_barrier
	s_add_i32 s45, s45, 2
	s_add_u32 s6, s6, 0x100
	s_addc_u32 s7, s7, 0
	s_add_u32 s33, s33, 0x100
	s_addc_u32 s44, s44, 0
	s_cmp_gt_u32 s45, 61
	s_cbranch_scc0 .LBB0_143
	s_and_b64 vcc, exec, s[20:21]
	s_cbranch_vccz .LBB0_148
	s_barrier
	v_lshl_add_u32 v156, s0, 8, v163
	s_cmp_lt_i32 s54, 40
	s_mov_b64 s[0:1], -1
	s_cbranch_scc1 .LBB0_149

; #define PG8_STAGE(bufoff, gbase, voff) do { _Pragma("unroll") for (int _i = 0; _i < 2; ++_i) \
;         __builtin_amdgcn_global_load_lds((const unsigned*)((const char*)(gbase) + (voff)[_i]), (PG8_LAS unsigned*)(lds + (bufoff) + ldsw + _i * 8192), 16, 0, 0); } while (0)
; #define PG8_LDA(dst, b, h) do { _Pragma("unroll") for (int m = 0; m < 4; ++m) _Pragma("unroll") for (int k = 0; k < 2; ++k) dst[m][k] = *(const PG8_LAS bf16x8*)(lds + PG8_SA(b, h) + aoff + m * 2048 + k * 1024); } while (0)
; #define PG8_LDB(dst, b, h) do { _Pragma("unroll") for (int n = 0; n < 2; ++n) _Pragma("unroll") for (int k = 0; k < 2; ++k) dst[n][k] = *(const PG8_LAS bf16x8*)(lds + PG8_SB(b, h) + boff + n * 2048 + k * 1024); } while (0)
; #define PG8_MMA(ai, bj, At, Bt) do { __builtin_amdgcn_s_setprio(3); _Pragma("unroll") for (int m = 0; m < 4; ++m) _Pragma("unroll") for (int n = 0; n < 2; ++n) _Pragma("unroll") for (int k = 0; k < 2; ++k) \
;         acc[ai][bj][m][n] = __builtin_amdgcn_mfma_f32_16x16x32_bf16(Bt[n][k], At[m][k], acc[ai][bj][m][n], 0, 0, 0); __builtin_amdgcn_s_setprio(0); } while (0)
; #define PG8_WAIT_V(n) asm volatile("s_waitcnt vmcnt(" #n ")" ::: "memory")
; #define PG8_WAIT_L(n) asm volatile("s_waitcnt lgkmcnt(" #n ")" ::: "memory")
; #define PG8_BAR __builtin_amdgcn_s_barrier()
; #define PG8_SCHED __builtin_amdgcn_sched_barrier(0)
; template <class Epi, class Sched, bool ALIGN_EPI = false, bool SP2 = false>
; __device__ __forceinline__ void gemm_phase(PG8_LAS unsigned char* lds, const Gemm g, const Sched& S, const Epi& E) {
;     ...
;             PG8_LDB(B0, 0, 0); PG8_LDB(B1, 0, 1); PG8_SCHED; PG8_LDA(At, 0, 0); PG8_STAGE(PG8_SA(1, 1), a1 + hstepA, voffA);
;             PG8_WAIT_V(8); PG8_WAIT_L(0); PG8_BAR; PG8_MMA(0, 0, At, B0); PG8_MMA(0, 1, At, B1); PG8_BAR; PG8_SCHED;
;             PG8_LDA(At, 0, 1); PG8_STAGE(PG8_SB(0, 0), b2, voffB); PG8_STAGE(PG8_SB(0, 1), b2 + hstepB, voffB); PG8_STAGE(PG8_SA(0, 0), a2, voffA);
;             PG8_WAIT_V(8); PG8_WAIT_L(0); PG8_BAR; PG8_MMA(1, 0, At, B0); PG8_MMA(1, 1, At, B1); PG8_BAR; PG8_SCHED;
.LBB0_478:
	ds_read_b128 v[130:133], v170
	ds_read_b128 v[134:137], v170 offset:1024
	ds_read_b128 v[138:141], v170 offset:2048
	ds_read_b128 v[142:145], v170 offset:3072
	ds_read_b128 v[164:167], v171
	ds_read_b128 v[174:177], v171 offset:1024
	ds_read_b128 v[178:181], v171 offset:2048
	ds_read_b128 v[182:185], v171 offset:3072
	s_add_u32 s36, s6, 0xfff80080
	s_addc_u32 s37, s7, -1
	s_cmp_eq_u32 s79, 4
	s_cselect_b32 s59, s27, s37
	s_cselect_b32 s58, s26, s36
	s_cselect_b32 s37, s23, s78
	s_cselect_b32 s36, s25, s77
	v_lshl_add_u64 v[218:219], s[6:7], 0, v[154:155]
	s_add_i32 m0, s31, 0xc000
	ds_read_b128 v[186:189], v172
	ds_read_b128 v[190:193], v172 offset:1024
	ds_read_b128 v[194:197], v172 offset:2048
	ds_read_b128 v[198:201], v172 offset:3072
	ds_read_b128 v[202:205], v172 offset:4096
	ds_read_b128 v[206:209], v172 offset:5120
	ds_read_b128 v[210:213], v172 offset:6144
	ds_read_b128 v[214:217], v172 offset:7168
	global_load_lds_dwordx4 v[218:219], off
	v_lshl_add_u64 v[218:219], s[6:7], 0, v[156:157]
	s_add_i32 m0, s31, 0xe000
	s_nop 0
	global_load_lds_dwordx4 v[218:219], off
	s_waitcnt vmcnt(8)
	s_waitcnt lgkmcnt(0)
	s_barrier
	s_setprio 3
	s_waitcnt lgkmcnt(0)
	v_mfma_f32_16x16x32_bf16 v[126:129], v[130:133], v[186:189], v[126:129]
	v_mfma_f32_16x16x32_bf16 v[122:125], v[138:141], v[186:189], v[122:125]
	v_mfma_f32_16x16x32_bf16 v[114:117], v[138:141], v[194:197], v[114:117]
	v_mfma_f32_16x16x32_bf16 v[118:121], v[130:133], v[194:197], v[118:121]
	v_mfma_f32_16x16x32_bf16 v[110:113], v[130:133], v[202:205], v[110:113]
	v_mfma_f32_16x16x32_bf16 v[102:105], v[138:141], v[202:205], v[102:105]
	v_mfma_f32_16x16x32_bf16 v[74:77], v[138:141], v[210:213], v[74:77]
	v_mfma_f32_16x16x32_bf16 v[78:81], v[130:133], v[210:213], v[78:81]
	v_mfma_f32_16x16x32_bf16 v[126:129], v[134:137], v[190:193], v[126:129]
	v_mfma_f32_16x16x32_bf16 v[122:125], v[142:145], v[190:193], v[122:125]
	v_mfma_f32_16x16x32_bf16 v[114:117], v[142:145], v[198:201], v[114:117]
	v_mfma_f32_16x16x32_bf16 v[118:121], v[134:137], v[198:201], v[118:121]
	v_mfma_f32_16x16x32_bf16 v[110:113], v[134:137], v[206:209], v[110:113]
	v_mfma_f32_16x16x32_bf16 v[102:105], v[142:145], v[206:209], v[102:105]
	v_mfma_f32_16x16x32_bf16 v[74:77], v[142:145], v[214:217], v[74:77]
	v_mfma_f32_16x16x32_bf16 v[78:81], v[134:137], v[214:217], v[78:81]
	s_setprio 0
	s_setprio 3
	v_mfma_f32_16x16x32_bf16 v[106:109], v[164:167], v[186:189], v[106:109]
	v_mfma_f32_16x16x32_bf16 v[98:101], v[178:181], v[186:189], v[98:101]
	v_mfma_f32_16x16x32_bf16 v[90:93], v[178:181], v[194:197], v[90:93]
	v_mfma_f32_16x16x32_bf16 v[94:97], v[164:167], v[194:197], v[94:97]
	v_mfma_f32_16x16x32_bf16 v[86:89], v[164:167], v[202:205], v[86:89]
	v_mfma_f32_16x16x32_bf16 v[82:85], v[178:181], v[202:205], v[82:85]
	v_mfma_f32_16x16x32_bf16 v[66:69], v[178:181], v[210:213], v[66:69]
	v_mfma_f32_16x16x32_bf16 v[70:73], v[164:167], v[210:213], v[70:73]
	v_mfma_f32_16x16x32_bf16 v[106:109], v[174:177], v[190:193], v[106:109]
	v_mfma_f32_16x16x32_bf16 v[98:101], v[182:185], v[190:193], v[98:101]
	v_mfma_f32_16x16x32_bf16 v[90:93], v[182:185], v[198:201], v[90:93]
	v_mfma_f32_16x16x32_bf16 v[94:97], v[174:177], v[198:201], v[94:97]
	v_mfma_f32_16x16x32_bf16 v[86:89], v[174:177], v[206:209], v[86:89]
	v_mfma_f32_16x16x32_bf16 v[82:85], v[182:185], v[206:209], v[82:85]
	v_mfma_f32_16x16x32_bf16 v[66:69], v[182:185], v[214:217], v[66:69]
	v_mfma_f32_16x16x32_bf16 v[70:73], v[174:177], v[214:217], v[70:73]
	s_setprio 0
	s_barrier
	s_add_i32 s83, s72, s44
	v_lshl_add_u64 v[218:219], s[36:37], 0, v[148:149]
	s_mov_b32 m0, s83
	ds_read_b128 v[186:189], v172 offset:16384
	ds_read_b128 v[190:193], v172 offset:17408
	ds_read_b128 v[194:197], v172 offset:18432
	ds_read_b128 v[198:201], v172 offset:19456
	ds_read_b128 v[202:205], v172 offset:20480
	ds_read_b128 v[206:209], v172 offset:21504
	ds_read_b128 v[210:213], v172 offset:22528
	ds_read_b128 v[214:217], v172 offset:23552
	global_load_lds_dwordx4 v[218:219], off
	s_add_i32 m0, s83, 0x2000
	s_add_u32 s84, s36, 0x20000
	v_lshl_add_u64 v[220:221], s[36:37], 0, v[152:153]
	s_addc_u32 s85, s37, 0
	s_add_i32 s83, s73, s44
	global_load_lds_dwordx4 v[220:221], off
	v_lshl_add_u64 v[222:223], s[84:85], 0, v[148:149]
	s_mov_b32 m0, s83
	v_lshl_add_u64 v[224:225], s[58:59], 0, v[150:151]
	global_load_lds_dwordx4 v[222:223], off
	v_lshl_add_u64 v[222:223], s[84:85], 0, v[152:153]
	s_add_i32 m0, s83, 0x2000
	s_nop 0
	global_load_lds_dwordx4 v[222:223], off
	v_lshl_add_u64 v[222:223], s[58:59], 0, v[146:147]
	s_mov_b32 m0, s31
	s_nop 0
	global_load_lds_dwordx4 v[222:223], off
	s_mov_b32 m0, s45
	s_nop 0
	global_load_lds_dwordx4 v[224:225], off
	s_waitcnt vmcnt(8)
	s_waitcnt lgkmcnt(0)
	s_barrier
; #define PG8_STAGE(bufoff, gbase, voff) do { _Pragma("unroll") for (int _i = 0; _i < 2; ++_i) \
;         __builtin_amdgcn_global_load_lds((const unsigned*)((const char*)(gbase) + (voff)[_i]), (PG8_LAS unsigned*)(lds + (bufoff) + ldsw + _i * 8192), 16, 0, 0); } while (0)
; #define PG8_LDA(dst, b, h) do { _Pragma("unroll") for (int m = 0; m < 4; ++m) _Pragma("unroll") for (int k = 0; k < 2; ++k) dst[m][k] = *(const PG8_LAS bf16x8*)(lds + PG8_SA(b, h) + aoff + m * 2048 + k * 1024); } while (0)
; #define PG8_LDB(dst, b, h) do { _Pragma("unroll") for (int n = 0; n < 2; ++n) _Pragma("unroll") for (int k = 0; k < 2; ++k) dst[n][k] = *(const PG8_LAS bf16x8*)(lds + PG8_SB(b, h) + boff + n * 2048 + k * 1024); } while (0)
; #define PG8_MMA(ai, bj, At, Bt) do { __builtin_amdgcn_s_setprio(3); _Pragma("unroll") for (int m = 0; m < 4; ++m) _Pragma("unroll") for (int n = 0; n < 2; ++n) _Pragma("unroll") for (int k = 0; k < 2; ++k) \
;         acc[ai][bj][m][n] = __builtin_amdgcn_mfma_f32_16x16x32_bf16(Bt[n][k], At[m][k], acc[ai][bj][m][n], 0, 0, 0); __builtin_amdgcn_s_setprio(0); } while (0)
; #define PG8_WAIT_V(n) asm volatile("s_waitcnt vmcnt(" #n ")" ::: "memory")
; #define PG8_WAIT_L(n) asm volatile("s_waitcnt lgkmcnt(" #n ")" ::: "memory")
; #define PG8_BAR __builtin_amdgcn_s_barrier()
; #define PG8_SCHED __builtin_amdgcn_sched_barrier(0)
; template <class Epi, class Sched, bool ALIGN_EPI = false, bool SP2 = false>
; __device__ __forceinline__ void gemm_phase(PG8_LAS unsigned char* lds, const Gemm g, const Sched& S, const Epi& E) {
;     ...
;             PG8_WAIT_V(8); PG8_WAIT_L(0); PG8_BAR; PG8_MMA(1, 0, At, B0); PG8_MMA(1, 1, At, B1); PG8_BAR; PG8_SCHED;
;             PG8_LDB(B0, 1, 0); PG8_LDB(B1, 1, 1); PG8_SCHED; PG8_LDA(At, 1, 0); PG8_STAGE(PG8_SA(0, 1), a2 + hstepA, voffA);
;             PG8_WAIT_V(8); PG8_WAIT_L(0); PG8_BAR; PG8_MMA(0, 0, At, B0); PG8_MMA(0, 1, At, B1); PG8_BAR; PG8_SCHED;
	s_setprio 3
	s_waitcnt lgkmcnt(0)
	v_mfma_f32_16x16x32_bf16 v[62:65], v[130:133], v[186:189], v[62:65]
	v_mfma_f32_16x16x32_bf16 v[58:61], v[138:141], v[186:189], v[58:61]
	v_mfma_f32_16x16x32_bf16 v[46:49], v[138:141], v[194:197], v[46:49]
	v_mfma_f32_16x16x32_bf16 v[54:57], v[130:133], v[194:197], v[54:57]
	v_mfma_f32_16x16x32_bf16 v[38:41], v[130:133], v[202:205], v[38:41]
	v_mfma_f32_16x16x32_bf16 v[30:33], v[138:141], v[202:205], v[30:33]
	v_mfma_f32_16x16x32_bf16 v[14:17], v[138:141], v[210:213], v[14:17]
	v_mfma_f32_16x16x32_bf16 v[22:25], v[130:133], v[210:213], v[22:25]
	v_mfma_f32_16x16x32_bf16 v[62:65], v[134:137], v[190:193], v[62:65]
	v_mfma_f32_16x16x32_bf16 v[58:61], v[142:145], v[190:193], v[58:61]
	v_mfma_f32_16x16x32_bf16 v[46:49], v[142:145], v[198:201], v[46:49]
	v_mfma_f32_16x16x32_bf16 v[54:57], v[134:137], v[198:201], v[54:57]
	v_mfma_f32_16x16x32_bf16 v[38:41], v[134:137], v[206:209], v[38:41]
	v_mfma_f32_16x16x32_bf16 v[30:33], v[142:145], v[206:209], v[30:33]
	v_mfma_f32_16x16x32_bf16 v[14:17], v[142:145], v[214:217], v[14:17]
	v_mfma_f32_16x16x32_bf16 v[22:25], v[134:137], v[214:217], v[22:25]
	s_setprio 0
	s_setprio 3
	v_mfma_f32_16x16x32_bf16 v[50:53], v[164:167], v[186:189], v[50:53]
	v_mfma_f32_16x16x32_bf16 v[42:45], v[178:181], v[186:189], v[42:45]
	v_mfma_f32_16x16x32_bf16 v[26:29], v[178:181], v[194:197], v[26:29]
	v_mfma_f32_16x16x32_bf16 v[34:37], v[164:167], v[194:197], v[34:37]
	v_mfma_f32_16x16x32_bf16 v[18:21], v[164:167], v[202:205], v[18:21]
	v_mfma_f32_16x16x32_bf16 v[10:13], v[178:181], v[202:205], v[10:13]
	v_mfma_f32_16x16x32_bf16 v[2:5], v[178:181], v[210:213], v[2:5]
	v_mfma_f32_16x16x32_bf16 v[6:9], v[164:167], v[210:213], v[6:9]
	v_mfma_f32_16x16x32_bf16 v[50:53], v[174:177], v[190:193], v[50:53]
	v_mfma_f32_16x16x32_bf16 v[42:45], v[182:185], v[190:193], v[42:45]
	v_mfma_f32_16x16x32_bf16 v[26:29], v[182:185], v[198:201], v[26:29]
	v_mfma_f32_16x16x32_bf16 v[34:37], v[174:177], v[198:201], v[34:37]
	v_mfma_f32_16x16x32_bf16 v[18:21], v[174:177], v[206:209], v[18:21]
	v_mfma_f32_16x16x32_bf16 v[10:13], v[182:185], v[206:209], v[10:13]
	v_mfma_f32_16x16x32_bf16 v[2:5], v[182:185], v[214:217], v[2:5]
	v_mfma_f32_16x16x32_bf16 v[6:9], v[174:177], v[214:217], v[6:9]
	s_setprio 0
	s_barrier
	s_add_i32 s83, 0, 0x18000
	s_add_i32 s84, 0, 0x1c000
	v_add_u32_e32 v142, s83, v168
	v_add_u32_e32 v173, s84, v168
	ds_read_b128 v[130:133], v142
	ds_read_b128 v[134:137], v142 offset:1024
	ds_read_b128 v[138:141], v142 offset:2048
	ds_read_b128 v[142:145], v142 offset:3072
	ds_read_b128 v[164:167], v173
	ds_read_b128 v[174:177], v173 offset:1024
	ds_read_b128 v[178:181], v173 offset:2048
	ds_read_b128 v[182:185], v173 offset:3072
	s_add_u32 s58, s58, 0x80000
	s_addc_u32 s59, s59, 0
	s_mov_b32 m0, s54
	v_lshl_add_u64 v[226:227], s[58:59], 0, v[146:147]
	ds_read_b128 v[186:189], v172 offset:32768
	ds_read_b128 v[190:193], v172 offset:33792
	ds_read_b128 v[194:197], v172 offset:34816
	ds_read_b128 v[198:201], v172 offset:35840
	ds_read_b128 v[202:205], v172 offset:36864
	ds_read_b128 v[206:209], v172 offset:37888
	ds_read_b128 v[210:213], v172 offset:38912
	ds_read_b128 v[214:217], v172 offset:39936
	global_load_lds_dwordx4 v[226:227], off
	v_lshl_add_u64 v[226:227], s[58:59], 0, v[150:151]
	s_mov_b32 m0, s55
	s_nop 0
	global_load_lds_dwordx4 v[226:227], off
	s_waitcnt vmcnt(8)
	s_waitcnt lgkmcnt(0)
	s_barrier
	s_setprio 3
	s_waitcnt lgkmcnt(0)
	v_mfma_f32_16x16x32_bf16 v[126:129], v[130:133], v[186:189], v[126:129]
	v_mfma_f32_16x16x32_bf16 v[122:125], v[138:141], v[186:189], v[122:125]
	v_mfma_f32_16x16x32_bf16 v[114:117], v[138:141], v[194:197], v[114:117]
	v_mfma_f32_16x16x32_bf16 v[118:121], v[130:133], v[194:197], v[118:121]
	v_mfma_f32_16x16x32_bf16 v[110:113], v[130:133], v[202:205], v[110:113]
	v_mfma_f32_16x16x32_bf16 v[102:105], v[138:141], v[202:205], v[102:105]
	v_mfma_f32_16x16x32_bf16 v[74:77], v[138:141], v[210:213], v[74:77]
	v_mfma_f32_16x16x32_bf16 v[78:81], v[130:133], v[210:213], v[78:81]
	v_mfma_f32_16x16x32_bf16 v[126:129], v[134:137], v[190:193], v[126:129]
	v_mfma_f32_16x16x32_bf16 v[122:125], v[142:145], v[190:193], v[122:125]
	v_mfma_f32_16x16x32_bf16 v[114:117], v[142:145], v[198:201], v[114:117]
	v_mfma_f32_16x16x32_bf16 v[118:121], v[134:137], v[198:201], v[118:121]
	v_mfma_f32_16x16x32_bf16 v[110:113], v[134:137], v[206:209], v[110:113]
	v_mfma_f32_16x16x32_bf16 v[102:105], v[142:145], v[206:209], v[102:105]
	v_mfma_f32_16x16x32_bf16 v[74:77], v[142:145], v[214:217], v[74:77]
	v_mfma_f32_16x16x32_bf16 v[78:81], v[134:137], v[214:217], v[78:81]
	s_setprio 0
	s_setprio 3
	v_mfma_f32_16x16x32_bf16 v[106:109], v[164:167], v[186:189], v[106:109]
	v_mfma_f32_16x16x32_bf16 v[98:101], v[178:181], v[186:189], v[98:101]
	v_mfma_f32_16x16x32_bf16 v[90:93], v[178:181], v[194:197], v[90:93]
	v_mfma_f32_16x16x32_bf16 v[94:97], v[164:167], v[194:197], v[94:97]
	v_mfma_f32_16x16x32_bf16 v[86:89], v[164:167], v[202:205], v[86:89]
	v_mfma_f32_16x16x32_bf16 v[82:85], v[178:181], v[202:205], v[82:85]
	v_mfma_f32_16x16x32_bf16 v[66:69], v[178:181], v[210:213], v[66:69]
	v_mfma_f32_16x16x32_bf16 v[70:73], v[164:167], v[210:213], v[70:73]
	v_mfma_f32_16x16x32_bf16 v[106:109], v[174:177], v[190:193], v[106:109]
	v_mfma_f32_16x16x32_bf16 v[98:101], v[182:185], v[190:193], v[98:101]
	v_mfma_f32_16x16x32_bf16 v[90:93], v[182:185], v[198:201], v[90:93]
	v_mfma_f32_16x16x32_bf16 v[94:97], v[174:177], v[198:201], v[94:97]
	v_mfma_f32_16x16x32_bf16 v[86:89], v[174:177], v[206:209], v[86:89]
	v_mfma_f32_16x16x32_bf16 v[82:85], v[182:185], v[206:209], v[82:85]
	v_mfma_f32_16x16x32_bf16 v[66:69], v[182:185], v[214:217], v[66:69]
	v_mfma_f32_16x16x32_bf16 v[70:73], v[174:177], v[214:217], v[70:73]
	s_setprio 0
	s_barrier
; #define PG8_STAGE(bufoff, gbase, voff) do { _Pragma("unroll") for (int _i = 0; _i < 2; ++_i) \
;         __builtin_amdgcn_global_load_lds((const unsigned*)((const char*)(gbase) + (voff)[_i]), (PG8_LAS unsigned*)(lds + (bufoff) + ldsw + _i * 8192), 16, 0, 0); } while (0)
; #define PG8_LDA(dst, b, h) do { _Pragma("unroll") for (int m = 0; m < 4; ++m) _Pragma("unroll") for (int k = 0; k < 2; ++k) dst[m][k] = *(const PG8_LAS bf16x8*)(lds + PG8_SA(b, h) + aoff + m * 2048 + k * 1024); } while (0)
; #define PG8_MMA(ai, bj, At, Bt) do { __builtin_amdgcn_s_setprio(3); _Pragma("unroll") for (int m = 0; m < 4; ++m) _Pragma("unroll") for (int n = 0; n < 2; ++n) _Pragma("unroll") for (int k = 0; k < 2; ++k) \
;         acc[ai][bj][m][n] = __builtin_amdgcn_mfma_f32_16x16x32_bf16(Bt[n][k], At[m][k], acc[ai][bj][m][n], 0, 0, 0); __builtin_amdgcn_s_setprio(0); } while (0)
; #define PG8_WAIT_V(n) asm volatile("s_waitcnt vmcnt(" #n ")" ::: "memory")
; #define PG8_WAIT_L(n) asm volatile("s_waitcnt lgkmcnt(" #n ")" ::: "memory")
; #define PG8_BAR __builtin_amdgcn_s_barrier()
; #define PG8_SCHED __builtin_amdgcn_sched_barrier(0)
; template <class Epi, class Sched, bool ALIGN_EPI = false, bool SP2 = false>
; __device__ __forceinline__ void gemm_phase(PG8_LAS unsigned char* lds, const Gemm g, const Sched& S, const Epi& E) {
;     ...
;             PG8_LDA(At, 1, 1); PG8_STAGE(PG8_SB(1, 0), b3, voffB); PG8_STAGE(PG8_SB(1, 1), b3 + hstepB, voffB); PG8_STAGE(PG8_SA(1, 0), a3, voffA);
;             PG8_WAIT_V(8); PG8_WAIT_L(0); PG8_BAR; PG8_MMA(1, 0, At, B0); PG8_MMA(1, 1, At, B1); PG8_BAR; PG8_SCHED;
	s_add_i32 s58, s83, s44
	v_lshl_add_u64 v[218:219], v[218:219], 0, s[18:19]
	s_mov_b32 m0, s58
	ds_read_b128 v[186:189], v172 offset:49152
	ds_read_b128 v[190:193], v172 offset:50176
	ds_read_b128 v[194:197], v172 offset:51200
	ds_read_b128 v[198:201], v172 offset:52224
	ds_read_b128 v[202:205], v172 offset:53248
	ds_read_b128 v[206:209], v172 offset:54272
	ds_read_b128 v[210:213], v172 offset:55296
	ds_read_b128 v[214:217], v172 offset:56320
	global_load_lds_dwordx4 v[218:219], off
	s_add_i32 m0, s58, 0x2000
	s_add_u32 s36, s36, 0x20080
	v_lshl_add_u64 v[218:219], v[220:221], 0, s[18:19]
	s_addc_u32 s37, s37, 0
	s_add_i32 s58, s84, s44
	global_load_lds_dwordx4 v[218:219], off
	v_lshl_add_u64 v[218:219], s[36:37], 0, v[148:149]
	s_mov_b32 m0, s58
	s_nop 0
	global_load_lds_dwordx4 v[218:219], off
	v_lshl_add_u64 v[218:219], s[36:37], 0, v[152:153]
	s_add_i32 m0, s58, 0x2000
	s_nop 0
	global_load_lds_dwordx4 v[218:219], off
	v_lshl_add_u64 v[218:219], v[222:223], 0, s[18:19]
	s_mov_b32 m0, s63
	s_nop 0
	global_load_lds_dwordx4 v[218:219], off
	v_lshl_add_u64 v[218:219], v[224:225], 0, s[18:19]
	s_mov_b32 m0, s66
	s_nop 0
	global_load_lds_dwordx4 v[218:219], off
	s_waitcnt vmcnt(8)
	s_waitcnt lgkmcnt(0)
	s_barrier
	s_setprio 3
	s_waitcnt lgkmcnt(0)
	v_mfma_f32_16x16x32_bf16 v[62:65], v[130:133], v[186:189], v[62:65]
	v_mfma_f32_16x16x32_bf16 v[58:61], v[138:141], v[186:189], v[58:61]
	v_mfma_f32_16x16x32_bf16 v[46:49], v[138:141], v[194:197], v[46:49]
	v_mfma_f32_16x16x32_bf16 v[54:57], v[130:133], v[194:197], v[54:57]
	v_mfma_f32_16x16x32_bf16 v[38:41], v[130:133], v[202:205], v[38:41]
	v_mfma_f32_16x16x32_bf16 v[30:33], v[138:141], v[202:205], v[30:33]
	v_mfma_f32_16x16x32_bf16 v[14:17], v[138:141], v[210:213], v[14:17]
	v_mfma_f32_16x16x32_bf16 v[22:25], v[130:133], v[210:213], v[22:25]
	v_mfma_f32_16x16x32_bf16 v[62:65], v[134:137], v[190:193], v[62:65]
	v_mfma_f32_16x16x32_bf16 v[58:61], v[142:145], v[190:193], v[58:61]
	v_mfma_f32_16x16x32_bf16 v[46:49], v[142:145], v[198:201], v[46:49]
	v_mfma_f32_16x16x32_bf16 v[54:57], v[134:137], v[198:201], v[54:57]
	v_mfma_f32_16x16x32_bf16 v[38:41], v[134:137], v[206:209], v[38:41]
	v_mfma_f32_16x16x32_bf16 v[30:33], v[142:145], v[206:209], v[30:33]
	v_mfma_f32_16x16x32_bf16 v[14:17], v[142:145], v[214:217], v[14:17]
	v_mfma_f32_16x16x32_bf16 v[22:25], v[134:137], v[214:217], v[22:25]
	s_setprio 0
	s_setprio 3
	v_mfma_f32_16x16x32_bf16 v[50:53], v[164:167], v[186:189], v[50:53]
	v_mfma_f32_16x16x32_bf16 v[42:45], v[178:181], v[186:189], v[42:45]
	v_mfma_f32_16x16x32_bf16 v[26:29], v[178:181], v[194:197], v[26:29]
	v_mfma_f32_16x16x32_bf16 v[34:37], v[164:167], v[194:197], v[34:37]
	v_mfma_f32_16x16x32_bf16 v[18:21], v[164:167], v[202:205], v[18:21]
	v_mfma_f32_16x16x32_bf16 v[10:13], v[178:181], v[202:205], v[10:13]
	v_mfma_f32_16x16x32_bf16 v[2:5], v[178:181], v[210:213], v[2:5]
	v_mfma_f32_16x16x32_bf16 v[6:9], v[164:167], v[210:213], v[6:9]
	v_mfma_f32_16x16x32_bf16 v[50:53], v[174:177], v[190:193], v[50:53]
	v_mfma_f32_16x16x32_bf16 v[42:45], v[182:185], v[190:193], v[42:45]
	v_mfma_f32_16x16x32_bf16 v[26:29], v[182:185], v[198:201], v[26:29]
	v_mfma_f32_16x16x32_bf16 v[34:37], v[174:177], v[198:201], v[34:37]
	v_mfma_f32_16x16x32_bf16 v[18:21], v[174:177], v[206:209], v[18:21]
	v_mfma_f32_16x16x32_bf16 v[10:13], v[182:185], v[206:209], v[10:13]
	v_mfma_f32_16x16x32_bf16 v[2:5], v[182:185], v[214:217], v[2:5]
	v_mfma_f32_16x16x32_bf16 v[6:9], v[174:177], v[214:217], v[6:9]
	s_setprio 0
	s_barrier
	s_add_i32 s79, s79, 2
	s_add_u32 s6, s6, 0x100
	s_addc_u32 s7, s7, 0
	s_add_u32 s77, s77, 0x100
	s_addc_u32 s78, s78, 0
	s_cmp_gt_u32 s79, 5
	s_cbranch_scc0 .LBB0_478
	s_and_b64 vcc, exec, s[20:21]
	s_cbranch_vccz .LBB0_481
	s_barrier

; #define PG8_STAGE(bufoff, gbase, voff) do { _Pragma("unroll") for (int _i = 0; _i < 2; ++_i) \
;         __builtin_amdgcn_global_load_lds((const unsigned*)((const char*)(gbase) + (voff)[_i]), (PG8_LAS unsigned*)(lds + (bufoff) + ldsw + _i * 8192), 16, 0, 0); } while (0)
; #define PG8_LDA(dst, b, h) do { _Pragma("unroll") for (int m = 0; m < 4; ++m) _Pragma("unroll") for (int k = 0; k < 2; ++k) dst[m][k] = *(const PG8_LAS bf16x8*)(lds + PG8_SA(b, h) + aoff + m * 2048 + k * 1024); } while (0)
; #define PG8_LDB(dst, b, h) do { _Pragma("unroll") for (int n = 0; n < 2; ++n) _Pragma("unroll") for (int k = 0; k < 2; ++k) dst[n][k] = *(const PG8_LAS bf16x8*)(lds + PG8_SB(b, h) + boff + n * 2048 + k * 1024); } while (0)
; #define PG8_MMA(ai, bj, At, Bt) do { __builtin_amdgcn_s_setprio(3); _Pragma("unroll") for (int m = 0; m < 4; ++m) _Pragma("unroll") for (int n = 0; n < 2; ++n) _Pragma("unroll") for (int k = 0; k < 2; ++k) \
;         acc[ai][bj][m][n] = __builtin_amdgcn_mfma_f32_16x16x32_bf16(Bt[n][k], At[m][k], acc[ai][bj][m][n], 0, 0, 0); __builtin_amdgcn_s_setprio(0); } while (0)
; #define PG8_WAIT_V(n) asm volatile("s_waitcnt vmcnt(" #n ")" ::: "memory")
; #define PG8_WAIT_L(n) asm volatile("s_waitcnt lgkmcnt(" #n ")" ::: "memory")
; #define PG8_BAR __builtin_amdgcn_s_barrier()
; #define PG8_SCHED __builtin_amdgcn_sched_barrier(0)
; template <class Epi, class Sched, bool ALIGN_EPI = false, bool SP2 = false>
; __device__ __forceinline__ void gemm_phase(PG8_LAS unsigned char* lds, const Gemm g, const Sched& S, const Epi& E) {
;     ...
;             PG8_LDB(B0, 0, 0); PG8_LDB(B1, 0, 1); PG8_SCHED; PG8_LDA(At, 0, 0); PG8_STAGE(PG8_SA(1, 1), a1 + hstepA, voffA);
;             PG8_WAIT_V(8); PG8_WAIT_L(0); PG8_BAR; PG8_MMA(0, 0, At, B0); PG8_MMA(0, 1, At, B1); PG8_BAR; PG8_SCHED;
;             PG8_LDA(At, 0, 1); PG8_STAGE(PG8_SB(0, 0), b2, voffB); PG8_STAGE(PG8_SB(0, 1), b2 + hstepB, voffB); PG8_STAGE(PG8_SA(0, 0), a2, voffA);
;             PG8_WAIT_V(8); PG8_WAIT_L(0); PG8_BAR; PG8_MMA(1, 0, At, B0); PG8_MMA(1, 1, At, B1); PG8_BAR; PG8_SCHED;
.LBB0_727:
	v_add_u32_e32 v160, s66, v157
	ds_read_b128 v[130:133], v160
	ds_read_b128 v[164:167], v160 offset:1024
	ds_read_b128 v[168:171], v160 offset:2048
	ds_read_b128 v[172:175], v160 offset:3072
	v_add_u32_e32 v160, s67, v157
	s_add_u32 s0, s28, s30
	ds_read_b128 v[176:179], v160
	ds_read_b128 v[180:183], v160 offset:1024
	ds_read_b128 v[184:187], v160 offset:2048
	ds_read_b128 v[188:191], v160 offset:3072
	s_addc_u32 s1, s29, s31
	s_add_u32 s0, s0, 0x100
	s_addc_u32 s1, s1, 0
	s_add_u32 s84, s79, s30
	s_addc_u32 s85, s81, s31
	s_cmpk_eq_i32 s30, 0x1f00
	s_cselect_b32 s37, s23, s1
	s_cselect_b32 s36, s72, s0
	s_cselect_b32 s1, s75, s85
	s_cselect_b32 s0, s76, s84
	v_lshl_add_u64 v[160:161], v[150:151], 0, s[30:31]
	s_add_i32 m0, s44, 0xc000
	ds_read_b128 v[192:195], v159
	ds_read_b128 v[196:199], v159 offset:1024
	ds_read_b128 v[200:203], v159 offset:2048
	ds_read_b128 v[204:207], v159 offset:3072
	ds_read_b128 v[208:211], v159 offset:4096
	ds_read_b128 v[212:215], v159 offset:5120
	ds_read_b128 v[216:219], v159 offset:6144
	ds_read_b128 v[220:223], v159 offset:7168
	global_load_lds_dwordx4 v[160:161], off
	v_lshl_add_u64 v[160:161], v[152:153], 0, s[30:31]
	s_add_i32 m0, s44, 0xe000
	s_nop 0
	global_load_lds_dwordx4 v[160:161], off
	s_waitcnt vmcnt(8)
	s_waitcnt lgkmcnt(0)
	s_barrier
	s_setprio 3
	s_waitcnt lgkmcnt(0)
	v_mfma_f32_16x16x32_bf16 v[126:129], v[130:133], v[192:195], v[126:129]
	v_mfma_f32_16x16x32_bf16 v[122:125], v[168:171], v[192:195], v[122:125]
	v_mfma_f32_16x16x32_bf16 v[106:109], v[168:171], v[200:203], v[106:109]
	v_mfma_f32_16x16x32_bf16 v[110:113], v[130:133], v[200:203], v[110:113]
	v_mfma_f32_16x16x32_bf16 v[94:97], v[130:133], v[208:211], v[94:97]
	v_mfma_f32_16x16x32_bf16 v[90:93], v[168:171], v[208:211], v[90:93]
	v_mfma_f32_16x16x32_bf16 v[74:77], v[168:171], v[216:219], v[74:77]
	v_mfma_f32_16x16x32_bf16 v[78:81], v[130:133], v[216:219], v[78:81]
	v_mfma_f32_16x16x32_bf16 v[126:129], v[164:167], v[196:199], v[126:129]
	v_mfma_f32_16x16x32_bf16 v[122:125], v[172:175], v[196:199], v[122:125]
	v_mfma_f32_16x16x32_bf16 v[106:109], v[172:175], v[204:207], v[106:109]
	v_mfma_f32_16x16x32_bf16 v[110:113], v[164:167], v[204:207], v[110:113]
	v_mfma_f32_16x16x32_bf16 v[94:97], v[164:167], v[212:215], v[94:97]
	v_mfma_f32_16x16x32_bf16 v[90:93], v[172:175], v[212:215], v[90:93]
	v_mfma_f32_16x16x32_bf16 v[74:77], v[172:175], v[220:223], v[74:77]
	v_mfma_f32_16x16x32_bf16 v[78:81], v[164:167], v[220:223], v[78:81]
	s_setprio 0
	s_setprio 3
	v_mfma_f32_16x16x32_bf16 v[118:121], v[176:179], v[192:195], v[118:121]
	v_mfma_f32_16x16x32_bf16 v[114:117], v[184:187], v[192:195], v[114:117]
	v_mfma_f32_16x16x32_bf16 v[98:101], v[184:187], v[200:203], v[98:101]
	v_mfma_f32_16x16x32_bf16 v[102:105], v[176:179], v[200:203], v[102:105]
	v_mfma_f32_16x16x32_bf16 v[86:89], v[176:179], v[208:211], v[86:89]
	v_mfma_f32_16x16x32_bf16 v[82:85], v[184:187], v[208:211], v[82:85]
	v_mfma_f32_16x16x32_bf16 v[66:69], v[184:187], v[216:219], v[66:69]
	v_mfma_f32_16x16x32_bf16 v[70:73], v[176:179], v[216:219], v[70:73]
	v_mfma_f32_16x16x32_bf16 v[118:121], v[180:183], v[196:199], v[118:121]
	v_mfma_f32_16x16x32_bf16 v[114:117], v[188:191], v[196:199], v[114:117]
	v_mfma_f32_16x16x32_bf16 v[98:101], v[188:191], v[204:207], v[98:101]
	v_mfma_f32_16x16x32_bf16 v[102:105], v[180:183], v[204:207], v[102:105]
	v_mfma_f32_16x16x32_bf16 v[86:89], v[180:183], v[212:215], v[86:89]
	v_mfma_f32_16x16x32_bf16 v[82:85], v[188:191], v[212:215], v[82:85]
	v_mfma_f32_16x16x32_bf16 v[66:69], v[188:191], v[220:223], v[66:69]
	v_mfma_f32_16x16x32_bf16 v[70:73], v[180:183], v[220:223], v[70:73]
	s_setprio 0
	s_barrier
	s_add_i32 s84, s66, s33
	v_lshl_add_u64 v[160:161], s[0:1], 0, v[136:137]
	s_mov_b32 m0, s84
	ds_read_b128 v[192:195], v159 offset:16384
	ds_read_b128 v[196:199], v159 offset:17408
	ds_read_b128 v[200:203], v159 offset:18432
	ds_read_b128 v[204:207], v159 offset:19456
	ds_read_b128 v[208:211], v159 offset:20480
	ds_read_b128 v[212:215], v159 offset:21504
	ds_read_b128 v[216:219], v159 offset:22528
	ds_read_b128 v[220:223], v159 offset:23552
	global_load_lds_dwordx4 v[160:161], off
	s_add_i32 m0, s84, 0x2000
	s_add_u32 s84, s0, 0x100000
	v_lshl_add_u64 v[224:225], s[0:1], 0, v[140:141]
	s_addc_u32 s85, s1, 0
	s_add_i32 s86, s67, s33
	global_load_lds_dwordx4 v[224:225], off
	v_lshl_add_u64 v[226:227], s[84:85], 0, v[136:137]
	s_mov_b32 m0, s86
	v_lshl_add_u64 v[228:229], s[36:37], 0, v[138:139]
	global_load_lds_dwordx4 v[226:227], off
	v_lshl_add_u64 v[226:227], s[84:85], 0, v[140:141]
	s_add_i32 m0, s86, 0x2000
	s_nop 0
	global_load_lds_dwordx4 v[226:227], off
	v_lshl_add_u64 v[226:227], s[36:37], 0, v[134:135]
	s_mov_b32 m0, s44
	s_nop 0
	global_load_lds_dwordx4 v[226:227], off
	s_mov_b32 m0, s45
	s_nop 0
	global_load_lds_dwordx4 v[228:229], off
	s_waitcnt vmcnt(8)
	s_waitcnt lgkmcnt(0)
	s_barrier
; #define PG8_STAGE(bufoff, gbase, voff) do { _Pragma("unroll") for (int _i = 0; _i < 2; ++_i) \
;         __builtin_amdgcn_global_load_lds((const unsigned*)((const char*)(gbase) + (voff)[_i]), (PG8_LAS unsigned*)(lds + (bufoff) + ldsw + _i * 8192), 16, 0, 0); } while (0)
; #define PG8_LDA(dst, b, h) do { _Pragma("unroll") for (int m = 0; m < 4; ++m) _Pragma("unroll") for (int k = 0; k < 2; ++k) dst[m][k] = *(const PG8_LAS bf16x8*)(lds + PG8_SA(b, h) + aoff + m * 2048 + k * 1024); } while (0)
; #define PG8_LDB(dst, b, h) do { _Pragma("unroll") for (int n = 0; n < 2; ++n) _Pragma("unroll") for (int k = 0; k < 2; ++k) dst[n][k] = *(const PG8_LAS bf16x8*)(lds + PG8_SB(b, h) + boff + n * 2048 + k * 1024); } while (0)
; #define PG8_MMA(ai, bj, At, Bt) do { __builtin_amdgcn_s_setprio(3); _Pragma("unroll") for (int m = 0; m < 4; ++m) _Pragma("unroll") for (int n = 0; n < 2; ++n) _Pragma("unroll") for (int k = 0; k < 2; ++k) \
;         acc[ai][bj][m][n] = __builtin_amdgcn_mfma_f32_16x16x32_bf16(Bt[n][k], At[m][k], acc[ai][bj][m][n], 0, 0, 0); __builtin_amdgcn_s_setprio(0); } while (0)
; #define PG8_WAIT_V(n) asm volatile("s_waitcnt vmcnt(" #n ")" ::: "memory")
; #define PG8_WAIT_L(n) asm volatile("s_waitcnt lgkmcnt(" #n ")" ::: "memory")
; #define PG8_BAR __builtin_amdgcn_s_barrier()
; #define PG8_SCHED __builtin_amdgcn_sched_barrier(0)
; template <class Epi, class Sched, bool ALIGN_EPI = false, bool SP2 = false>
; __device__ __forceinline__ void gemm_phase(PG8_LAS unsigned char* lds, const Gemm g, const Sched& S, const Epi& E) {
;     ...
;             PG8_WAIT_V(8); PG8_WAIT_L(0); PG8_BAR; PG8_MMA(1, 0, At, B0); PG8_MMA(1, 1, At, B1); PG8_BAR; PG8_SCHED;
;             PG8_LDB(B0, 1, 0); PG8_LDB(B1, 1, 1); PG8_SCHED; PG8_LDA(At, 1, 0); PG8_STAGE(PG8_SA(0, 1), a2 + hstepA, voffA);
;             PG8_WAIT_V(8); PG8_WAIT_L(0); PG8_BAR; PG8_MMA(0, 0, At, B0); PG8_MMA(0, 1, At, B1); PG8_BAR; PG8_SCHED;
	s_setprio 3
	s_waitcnt lgkmcnt(0)
	v_mfma_f32_16x16x32_bf16 v[62:65], v[130:133], v[192:195], v[62:65]
	v_mfma_f32_16x16x32_bf16 v[58:61], v[168:171], v[192:195], v[58:61]
	v_mfma_f32_16x16x32_bf16 v[42:45], v[168:171], v[200:203], v[42:45]
	v_mfma_f32_16x16x32_bf16 v[46:49], v[130:133], v[200:203], v[46:49]
	v_mfma_f32_16x16x32_bf16 v[30:33], v[130:133], v[208:211], v[30:33]
	v_mfma_f32_16x16x32_bf16 v[26:29], v[168:171], v[208:211], v[26:29]
	v_mfma_f32_16x16x32_bf16 v[10:13], v[168:171], v[216:219], v[10:13]
	v_mfma_f32_16x16x32_bf16 v[14:17], v[130:133], v[216:219], v[14:17]
	v_mfma_f32_16x16x32_bf16 v[62:65], v[164:167], v[196:199], v[62:65]
	v_mfma_f32_16x16x32_bf16 v[58:61], v[172:175], v[196:199], v[58:61]
	v_mfma_f32_16x16x32_bf16 v[42:45], v[172:175], v[204:207], v[42:45]
	v_mfma_f32_16x16x32_bf16 v[46:49], v[164:167], v[204:207], v[46:49]
	v_mfma_f32_16x16x32_bf16 v[30:33], v[164:167], v[212:215], v[30:33]
	v_mfma_f32_16x16x32_bf16 v[26:29], v[172:175], v[212:215], v[26:29]
	v_mfma_f32_16x16x32_bf16 v[10:13], v[172:175], v[220:223], v[10:13]
	v_mfma_f32_16x16x32_bf16 v[14:17], v[164:167], v[220:223], v[14:17]
	s_setprio 0
	s_setprio 3
	v_mfma_f32_16x16x32_bf16 v[54:57], v[176:179], v[192:195], v[54:57]
	v_mfma_f32_16x16x32_bf16 v[50:53], v[184:187], v[192:195], v[50:53]
	v_mfma_f32_16x16x32_bf16 v[34:37], v[184:187], v[200:203], v[34:37]
	v_mfma_f32_16x16x32_bf16 v[38:41], v[176:179], v[200:203], v[38:41]
	v_mfma_f32_16x16x32_bf16 v[22:25], v[176:179], v[208:211], v[22:25]
	v_mfma_f32_16x16x32_bf16 v[18:21], v[184:187], v[208:211], v[18:21]
	v_mfma_f32_16x16x32_bf16 v[2:5], v[184:187], v[216:219], v[2:5]
	v_mfma_f32_16x16x32_bf16 v[6:9], v[176:179], v[216:219], v[6:9]
	v_mfma_f32_16x16x32_bf16 v[54:57], v[180:183], v[196:199], v[54:57]
	v_mfma_f32_16x16x32_bf16 v[50:53], v[188:191], v[196:199], v[50:53]
	v_mfma_f32_16x16x32_bf16 v[34:37], v[188:191], v[204:207], v[34:37]
	v_mfma_f32_16x16x32_bf16 v[38:41], v[180:183], v[204:207], v[38:41]
	v_mfma_f32_16x16x32_bf16 v[22:25], v[180:183], v[212:215], v[22:25]
	v_mfma_f32_16x16x32_bf16 v[18:21], v[188:191], v[212:215], v[18:21]
	v_mfma_f32_16x16x32_bf16 v[2:5], v[188:191], v[220:223], v[2:5]
	v_mfma_f32_16x16x32_bf16 v[6:9], v[180:183], v[220:223], v[6:9]
	s_setprio 0
	s_barrier
	s_add_i32 s84, 0, 0x18000
	v_add_u32_e32 v163, s84, v157
	s_add_i32 s85, 0, 0x1c000
	ds_read_b128 v[130:133], v163
	ds_read_b128 v[164:167], v163 offset:1024
	ds_read_b128 v[168:171], v163 offset:2048
	ds_read_b128 v[172:175], v163 offset:3072
	v_add_u32_e32 v163, s85, v157
	ds_read_b128 v[176:179], v163
	ds_read_b128 v[180:183], v163 offset:1024
	ds_read_b128 v[184:187], v163 offset:2048
	ds_read_b128 v[188:191], v163 offset:3072
	s_add_u32 s36, s36, 0x100000
	s_addc_u32 s37, s37, 0
	s_mov_b32 m0, s54
	v_lshl_add_u64 v[230:231], s[36:37], 0, v[134:135]
	ds_read_b128 v[192:195], v159 offset:32768
	ds_read_b128 v[196:199], v159 offset:33792
	ds_read_b128 v[200:203], v159 offset:34816
	ds_read_b128 v[204:207], v159 offset:35840
	ds_read_b128 v[208:211], v159 offset:36864
	ds_read_b128 v[212:215], v159 offset:37888
	ds_read_b128 v[216:219], v159 offset:38912
	ds_read_b128 v[220:223], v159 offset:39936
	global_load_lds_dwordx4 v[230:231], off
	v_lshl_add_u64 v[230:231], s[36:37], 0, v[138:139]
	s_mov_b32 m0, s55
	s_nop 0
	global_load_lds_dwordx4 v[230:231], off
	s_waitcnt vmcnt(8)
	s_waitcnt lgkmcnt(0)
	s_barrier
	s_setprio 3
	s_waitcnt lgkmcnt(0)
	v_mfma_f32_16x16x32_bf16 v[126:129], v[130:133], v[192:195], v[126:129]
	v_mfma_f32_16x16x32_bf16 v[122:125], v[168:171], v[192:195], v[122:125]
	v_mfma_f32_16x16x32_bf16 v[106:109], v[168:171], v[200:203], v[106:109]
	v_mfma_f32_16x16x32_bf16 v[110:113], v[130:133], v[200:203], v[110:113]
	v_mfma_f32_16x16x32_bf16 v[94:97], v[130:133], v[208:211], v[94:97]
	v_mfma_f32_16x16x32_bf16 v[90:93], v[168:171], v[208:211], v[90:93]
	v_mfma_f32_16x16x32_bf16 v[74:77], v[168:171], v[216:219], v[74:77]
	v_mfma_f32_16x16x32_bf16 v[78:81], v[130:133], v[216:219], v[78:81]
	v_mfma_f32_16x16x32_bf16 v[126:129], v[164:167], v[196:199], v[126:129]
	v_mfma_f32_16x16x32_bf16 v[122:125], v[172:175], v[196:199], v[122:125]
	v_mfma_f32_16x16x32_bf16 v[106:109], v[172:175], v[204:207], v[106:109]
	v_mfma_f32_16x16x32_bf16 v[110:113], v[164:167], v[204:207], v[110:113]
	v_mfma_f32_16x16x32_bf16 v[94:97], v[164:167], v[212:215], v[94:97]
	v_mfma_f32_16x16x32_bf16 v[90:93], v[172:175], v[212:215], v[90:93]
	v_mfma_f32_16x16x32_bf16 v[74:77], v[172:175], v[220:223], v[74:77]
	v_mfma_f32_16x16x32_bf16 v[78:81], v[164:167], v[220:223], v[78:81]
	s_setprio 0
	s_setprio 3
	v_mfma_f32_16x16x32_bf16 v[118:121], v[176:179], v[192:195], v[118:121]
	v_mfma_f32_16x16x32_bf16 v[114:117], v[184:187], v[192:195], v[114:117]
	v_mfma_f32_16x16x32_bf16 v[98:101], v[184:187], v[200:203], v[98:101]
	v_mfma_f32_16x16x32_bf16 v[102:105], v[176:179], v[200:203], v[102:105]
	v_mfma_f32_16x16x32_bf16 v[86:89], v[176:179], v[208:211], v[86:89]
	v_mfma_f32_16x16x32_bf16 v[82:85], v[184:187], v[208:211], v[82:85]
	v_mfma_f32_16x16x32_bf16 v[66:69], v[184:187], v[216:219], v[66:69]
	v_mfma_f32_16x16x32_bf16 v[70:73], v[176:179], v[216:219], v[70:73]
	v_mfma_f32_16x16x32_bf16 v[118:121], v[180:183], v[196:199], v[118:121]
	v_mfma_f32_16x16x32_bf16 v[114:117], v[188:191], v[196:199], v[114:117]
	v_mfma_f32_16x16x32_bf16 v[98:101], v[188:191], v[204:207], v[98:101]
	v_mfma_f32_16x16x32_bf16 v[102:105], v[180:183], v[204:207], v[102:105]
	v_mfma_f32_16x16x32_bf16 v[86:89], v[180:183], v[212:215], v[86:89]
	v_mfma_f32_16x16x32_bf16 v[82:85], v[188:191], v[212:215], v[82:85]
	v_mfma_f32_16x16x32_bf16 v[66:69], v[188:191], v[220:223], v[66:69]
	v_mfma_f32_16x16x32_bf16 v[70:73], v[180:183], v[220:223], v[70:73]
	s_setprio 0
	s_barrier
; #define PG8_STAGE(bufoff, gbase, voff) do { _Pragma("unroll") for (int _i = 0; _i < 2; ++_i) \
;         __builtin_amdgcn_global_load_lds((const unsigned*)((const char*)(gbase) + (voff)[_i]), (PG8_LAS unsigned*)(lds + (bufoff) + ldsw + _i * 8192), 16, 0, 0); } while (0)
; #define PG8_LDA(dst, b, h) do { _Pragma("unroll") for (int m = 0; m < 4; ++m) _Pragma("unroll") for (int k = 0; k < 2; ++k) dst[m][k] = *(const PG8_LAS bf16x8*)(lds + PG8_SA(b, h) + aoff + m * 2048 + k * 1024); } while (0)
; #define PG8_MMA(ai, bj, At, Bt) do { __builtin_amdgcn_s_setprio(3); _Pragma("unroll") for (int m = 0; m < 4; ++m) _Pragma("unroll") for (int n = 0; n < 2; ++n) _Pragma("unroll") for (int k = 0; k < 2; ++k) \
;         acc[ai][bj][m][n] = __builtin_amdgcn_mfma_f32_16x16x32_bf16(Bt[n][k], At[m][k], acc[ai][bj][m][n], 0, 0, 0); __builtin_amdgcn_s_setprio(0); } while (0)
; #define PG8_WAIT_V(n) asm volatile("s_waitcnt vmcnt(" #n ")" ::: "memory")
; #define PG8_WAIT_L(n) asm volatile("s_waitcnt lgkmcnt(" #n ")" ::: "memory")
; #define PG8_BAR __builtin_amdgcn_s_barrier()
; #define PG8_SCHED __builtin_amdgcn_sched_barrier(0)
; template <class Epi, class Sched, bool ALIGN_EPI = false, bool SP2 = false>
; __device__ __forceinline__ void gemm_phase(PG8_LAS unsigned char* lds, const Gemm g, const Sched& S, const Epi& E) {
;     ...
;             PG8_LDA(At, 1, 1); PG8_STAGE(PG8_SB(1, 0), b3, voffB); PG8_STAGE(PG8_SB(1, 1), b3 + hstepB, voffB); PG8_STAGE(PG8_SA(1, 0), a3, voffA);
;             PG8_WAIT_V(8); PG8_WAIT_L(0); PG8_BAR; PG8_MMA(1, 0, At, B0); PG8_MMA(1, 1, At, B1); PG8_BAR; PG8_SCHED;
	s_add_i32 s36, s84, s33
	v_lshl_add_u64 v[160:161], v[160:161], 0, s[10:11]
	s_mov_b32 m0, s36
	ds_read_b128 v[192:195], v159 offset:49152
	ds_read_b128 v[196:199], v159 offset:50176
	ds_read_b128 v[200:203], v159 offset:51200
	ds_read_b128 v[204:207], v159 offset:52224
	ds_read_b128 v[208:211], v159 offset:53248
	ds_read_b128 v[212:215], v159 offset:54272
	ds_read_b128 v[216:219], v159 offset:55296
	ds_read_b128 v[220:223], v159 offset:56320
	global_load_lds_dwordx4 v[160:161], off
	s_add_i32 m0, s36, 0x2000
	s_add_u32 s0, s0, 0x100080
	v_lshl_add_u64 v[160:161], v[224:225], 0, s[10:11]
	s_addc_u32 s1, s1, 0
	s_add_i32 s36, s85, s33
	global_load_lds_dwordx4 v[160:161], off
	v_lshl_add_u64 v[160:161], s[0:1], 0, v[136:137]
	s_mov_b32 m0, s36
	s_nop 0
	global_load_lds_dwordx4 v[160:161], off
	v_lshl_add_u64 v[160:161], s[0:1], 0, v[140:141]
	s_add_i32 m0, s36, 0x2000
	s_nop 0
	global_load_lds_dwordx4 v[160:161], off
	v_lshl_add_u64 v[160:161], v[226:227], 0, s[10:11]
	s_mov_b32 m0, s61
	s_nop 0
	global_load_lds_dwordx4 v[160:161], off
	v_lshl_add_u64 v[160:161], v[228:229], 0, s[10:11]
	s_mov_b32 m0, s62
	s_nop 0
	global_load_lds_dwordx4 v[160:161], off
	s_waitcnt vmcnt(8)
	s_waitcnt lgkmcnt(0)
	s_barrier
	s_setprio 3
	s_waitcnt lgkmcnt(0)
	v_mfma_f32_16x16x32_bf16 v[62:65], v[130:133], v[192:195], v[62:65]
	v_mfma_f32_16x16x32_bf16 v[58:61], v[168:171], v[192:195], v[58:61]
	v_mfma_f32_16x16x32_bf16 v[42:45], v[168:171], v[200:203], v[42:45]
	v_mfma_f32_16x16x32_bf16 v[46:49], v[130:133], v[200:203], v[46:49]
	v_mfma_f32_16x16x32_bf16 v[30:33], v[130:133], v[208:211], v[30:33]
	v_mfma_f32_16x16x32_bf16 v[26:29], v[168:171], v[208:211], v[26:29]
	v_mfma_f32_16x16x32_bf16 v[10:13], v[168:171], v[216:219], v[10:13]
	v_mfma_f32_16x16x32_bf16 v[14:17], v[130:133], v[216:219], v[14:17]
	v_mfma_f32_16x16x32_bf16 v[62:65], v[164:167], v[196:199], v[62:65]
	v_mfma_f32_16x16x32_bf16 v[58:61], v[172:175], v[196:199], v[58:61]
	v_mfma_f32_16x16x32_bf16 v[42:45], v[172:175], v[204:207], v[42:45]
	v_mfma_f32_16x16x32_bf16 v[46:49], v[164:167], v[204:207], v[46:49]
	v_mfma_f32_16x16x32_bf16 v[30:33], v[164:167], v[212:215], v[30:33]
	v_mfma_f32_16x16x32_bf16 v[26:29], v[172:175], v[212:215], v[26:29]
	v_mfma_f32_16x16x32_bf16 v[10:13], v[172:175], v[220:223], v[10:13]
	v_mfma_f32_16x16x32_bf16 v[14:17], v[164:167], v[220:223], v[14:17]
	s_setprio 0
	s_setprio 3
	v_mfma_f32_16x16x32_bf16 v[54:57], v[176:179], v[192:195], v[54:57]
	v_mfma_f32_16x16x32_bf16 v[50:53], v[184:187], v[192:195], v[50:53]
	v_mfma_f32_16x16x32_bf16 v[34:37], v[184:187], v[200:203], v[34:37]
	v_mfma_f32_16x16x32_bf16 v[38:41], v[176:179], v[200:203], v[38:41]
	v_mfma_f32_16x16x32_bf16 v[22:25], v[176:179], v[208:211], v[22:25]
	v_mfma_f32_16x16x32_bf16 v[18:21], v[184:187], v[208:211], v[18:21]
	v_mfma_f32_16x16x32_bf16 v[2:5], v[184:187], v[216:219], v[2:5]
	v_mfma_f32_16x16x32_bf16 v[6:9], v[176:179], v[216:219], v[6:9]
	v_mfma_f32_16x16x32_bf16 v[54:57], v[180:183], v[196:199], v[54:57]
	v_mfma_f32_16x16x32_bf16 v[50:53], v[188:191], v[196:199], v[50:53]
	v_mfma_f32_16x16x32_bf16 v[34:37], v[188:191], v[204:207], v[34:37]
	v_mfma_f32_16x16x32_bf16 v[38:41], v[180:183], v[204:207], v[38:41]
	v_mfma_f32_16x16x32_bf16 v[22:25], v[180:183], v[212:215], v[22:25]
	v_mfma_f32_16x16x32_bf16 v[18:21], v[188:191], v[212:215], v[18:21]
	v_mfma_f32_16x16x32_bf16 v[2:5], v[188:191], v[220:223], v[2:5]
	v_mfma_f32_16x16x32_bf16 v[6:9], v[180:183], v[220:223], v[6:9]
	s_setprio 0
	s_barrier
	s_add_i32 s83, s83, 2
	s_add_u32 s30, s30, 0x100
	s_addc_u32 s31, s31, 0
	s_cmp_gt_u32 s83, 61
	s_cbranch_scc1 .LBB0_730

; #define PG8_STAGE(bufoff, gbase, voff) do { _Pragma("unroll") for (int _i = 0; _i < 2; ++_i) \
;         __builtin_amdgcn_global_load_lds((const unsigned*)((const char*)(gbase) + (voff)[_i]), (PG8_LAS unsigned*)(lds + (bufoff) + ldsw + _i * 8192), 16, 0, 0); } while (0)
; #define PG8_LDA(dst, b, h) do { _Pragma("unroll") for (int m = 0; m < 4; ++m) _Pragma("unroll") for (int k = 0; k < 2; ++k) dst[m][k] = *(const PG8_LAS bf16x8*)(lds + PG8_SA(b, h) + aoff + m * 2048 + k * 1024); } while (0)
; #define PG8_LDB(dst, b, h) do { _Pragma("unroll") for (int n = 0; n < 2; ++n) _Pragma("unroll") for (int k = 0; k < 2; ++k) dst[n][k] = *(const PG8_LAS bf16x8*)(lds + PG8_SB(b, h) + boff + n * 2048 + k * 1024); } while (0)
; #define PG8_MMA(ai, bj, At, Bt) do { __builtin_amdgcn_s_setprio(3); _Pragma("unroll") for (int m = 0; m < 4; ++m) _Pragma("unroll") for (int n = 0; n < 2; ++n) _Pragma("unroll") for (int k = 0; k < 2; ++k) \
;         acc[ai][bj][m][n] = __builtin_amdgcn_mfma_f32_16x16x32_bf16(Bt[n][k], At[m][k], acc[ai][bj][m][n], 0, 0, 0); __builtin_amdgcn_s_setprio(0); } while (0)
; #define PG8_WAIT_V(n) asm volatile("s_waitcnt vmcnt(" #n ")" ::: "memory")
; #define PG8_WAIT_L(n) asm volatile("s_waitcnt lgkmcnt(" #n ")" ::: "memory")
; template <class Epi, class Sched, bool ALIGN_EPI = false, bool SP2 = false>
; __device__ __forceinline__ void gemm_phase(PG8_LAS unsigned char* lds, const Gemm g, const Sched& S, const Epi& E) {
;     ...
;         for (int t = 0; t < nt; t += 2) {
;             const bool last = (t == nt - 2);
;             const char* a1 = cA + (size_t)(t + 1) * kstep;
;             const char* a2 = last ? nA : cA + (size_t)(t + 2) * kstep; const char* b2 = last ? nB : cB + (size_t)(t + 2) * kstep;
;             const char* a3 = a2 + kstep; const char* b3 = b2 + kstep;
;             if (last && has_next) S.a_ready(nxt);
;             if constexpr (Epi::MIDK) { if (t == E.midk_step(nt)) E.midk(acc, cur, wr, wc, fr, fq); }
;             if constexpr (SP2) {
;             PG8_LDB(B0, 0, 0); PG8_LDB(B1, 0, 1); PG8_SCHED; PG8_LDA(At, 0, 0); PG8_STAGE(PG8_SA(1, 1), a1 + hstepA, voffA);
;             PG8_WAIT_V(8); PG8_WAIT_L(0); PG8_BAR; PG8_MMA(0, 0, At, B0); PG8_MMA(0, 1, At, B1); PG8_BAR; PG8_SCHED;
;             PG8_LDA(At, 0, 1); PG8_STAGE(PG8_SB(0, 0), b2, voffB); PG8_STAGE(PG8_SB(0, 1), b2 + hstepB, voffB); PG8_STAGE(PG8_SA(0, 0), a2, voffA);
.LBB0_808:
	v_add_u32_e32 v3, s65, v186
	ds_read_b128 v[134:137], v3
	ds_read_b128 v[138:141], v3 offset:1024
	ds_read_b128 v[142:145], v3 offset:2048
	ds_read_b128 v[146:149], v3 offset:3072
	v_add_u32_e32 v3, s66, v186
	s_add_u32 s36, s28, s30
	ds_read_b128 v[150:153], v3
	ds_read_b128 v[154:157], v3 offset:1024
	ds_read_b128 v[158:161], v3 offset:2048
	ds_read_b128 v[190:193], v3 offset:3072
	s_addc_u32 s37, s29, s31
	s_add_u32 s36, s36, 0x100
	s_addc_u32 s37, s37, 0
	s_add_u32 s86, s83, s30
	s_addc_u32 s87, s84, s31
	s_cmpk_eq_i32 s30, 0x1f00
	s_cselect_b32 s41, s23, s37
	s_cselect_b32 s40, s75, s36
	s_cselect_b32 s37, s77, s87
	s_cselect_b32 s36, s78, s86
	v_lshl_add_u64 v[4:5], v[180:181], 0, s[30:31]
	s_add_i32 m0, s42, 0xc000
	ds_read_b128 v[194:197], v188
	ds_read_b128 v[198:201], v188 offset:1024
	ds_read_b128 v[202:205], v188 offset:2048
	ds_read_b128 v[206:209], v188 offset:3072
	ds_read_b128 v[210:213], v188 offset:4096
	ds_read_b128 v[214:217], v188 offset:5120
	ds_read_b128 v[218:221], v188 offset:6144
	ds_read_b128 v[222:225], v188 offset:7168
	global_load_lds_dwordx4 v[4:5], off
	v_lshl_add_u64 v[4:5], v[182:183], 0, s[30:31]
	s_add_i32 m0, s42, 0xe000
	s_nop 0
	global_load_lds_dwordx4 v[4:5], off
	s_waitcnt vmcnt(8)
	s_waitcnt lgkmcnt(0)
	s_barrier
	s_setprio 3
	s_waitcnt lgkmcnt(0)
	v_mfma_f32_16x16x32_bf16 v[130:133], v[134:137], v[194:197], v[130:133]
	v_mfma_f32_16x16x32_bf16 v[126:129], v[142:145], v[194:197], v[126:129]
	v_mfma_f32_16x16x32_bf16 v[110:113], v[142:145], v[202:205], v[110:113]
	v_mfma_f32_16x16x32_bf16 v[114:117], v[134:137], v[202:205], v[114:117]
	v_mfma_f32_16x16x32_bf16 v[98:101], v[134:137], v[210:213], v[98:101]
	v_mfma_f32_16x16x32_bf16 v[94:97], v[142:145], v[210:213], v[94:97]
	v_mfma_f32_16x16x32_bf16 v[78:81], v[142:145], v[218:221], v[78:81]
	v_mfma_f32_16x16x32_bf16 v[82:85], v[134:137], v[218:221], v[82:85]
	v_mfma_f32_16x16x32_bf16 v[130:133], v[138:141], v[198:201], v[130:133]
	v_mfma_f32_16x16x32_bf16 v[126:129], v[146:149], v[198:201], v[126:129]
	v_mfma_f32_16x16x32_bf16 v[110:113], v[146:149], v[206:209], v[110:113]
	v_mfma_f32_16x16x32_bf16 v[114:117], v[138:141], v[206:209], v[114:117]
	v_mfma_f32_16x16x32_bf16 v[98:101], v[138:141], v[214:217], v[98:101]
	v_mfma_f32_16x16x32_bf16 v[94:97], v[146:149], v[214:217], v[94:97]
	v_mfma_f32_16x16x32_bf16 v[78:81], v[146:149], v[222:225], v[78:81]
	v_mfma_f32_16x16x32_bf16 v[82:85], v[138:141], v[222:225], v[82:85]
	s_setprio 0
	s_setprio 3
	v_mfma_f32_16x16x32_bf16 v[122:125], v[150:153], v[194:197], v[122:125]
	v_mfma_f32_16x16x32_bf16 v[118:121], v[158:161], v[194:197], v[118:121]
	v_mfma_f32_16x16x32_bf16 v[102:105], v[158:161], v[202:205], v[102:105]
	v_mfma_f32_16x16x32_bf16 v[106:109], v[150:153], v[202:205], v[106:109]
	v_mfma_f32_16x16x32_bf16 v[90:93], v[150:153], v[210:213], v[90:93]
	v_mfma_f32_16x16x32_bf16 v[86:89], v[158:161], v[210:213], v[86:89]
	v_mfma_f32_16x16x32_bf16 v[70:73], v[158:161], v[218:221], v[70:73]
	v_mfma_f32_16x16x32_bf16 v[74:77], v[150:153], v[218:221], v[74:77]
	v_mfma_f32_16x16x32_bf16 v[122:125], v[154:157], v[198:201], v[122:125]
	v_mfma_f32_16x16x32_bf16 v[118:121], v[190:193], v[198:201], v[118:121]
	v_mfma_f32_16x16x32_bf16 v[102:105], v[190:193], v[206:209], v[102:105]
	v_mfma_f32_16x16x32_bf16 v[106:109], v[154:157], v[206:209], v[106:109]
	v_mfma_f32_16x16x32_bf16 v[90:93], v[154:157], v[214:217], v[90:93]
	v_mfma_f32_16x16x32_bf16 v[86:89], v[190:193], v[214:217], v[86:89]
	v_mfma_f32_16x16x32_bf16 v[70:73], v[190:193], v[222:225], v[70:73]
	v_mfma_f32_16x16x32_bf16 v[74:77], v[154:157], v[222:225], v[74:77]
	s_setprio 0
	s_barrier
	s_add_i32 s86, s65, s33
	v_lshl_add_u64 v[226:227], s[36:37], 0, v[166:167]
	s_mov_b32 m0, s86
	ds_read_b128 v[194:197], v188 offset:16384
	ds_read_b128 v[198:201], v188 offset:17408
	ds_read_b128 v[202:205], v188 offset:18432
	ds_read_b128 v[206:209], v188 offset:19456
	ds_read_b128 v[210:213], v188 offset:20480
	ds_read_b128 v[214:217], v188 offset:21504
	ds_read_b128 v[218:221], v188 offset:22528
	ds_read_b128 v[222:225], v188 offset:23552
	global_load_lds_dwordx4 v[226:227], off
	s_add_i32 m0, s86, 0x2000
	s_add_u32 s86, s36, 0x100000
	v_lshl_add_u64 v[228:229], s[36:37], 0, v[170:171]
	s_addc_u32 s87, s37, 0
	s_add_i32 s88, s66, s33
	global_load_lds_dwordx4 v[228:229], off
	v_lshl_add_u64 v[4:5], s[86:87], 0, v[166:167]
	s_mov_b32 m0, s88
	v_lshl_add_u64 v[230:231], s[40:41], 0, v[164:165]
	global_load_lds_dwordx4 v[4:5], off
	v_lshl_add_u64 v[4:5], s[86:87], 0, v[170:171]
	s_add_i32 m0, s88, 0x2000
	v_lshl_add_u64 v[232:233], s[40:41], 0, v[168:169]
	global_load_lds_dwordx4 v[4:5], off
	s_mov_b32 m0, s42
	s_nop 0
	global_load_lds_dwordx4 v[230:231], off
	s_mov_b32 m0, s43
	s_nop 0
	global_load_lds_dwordx4 v[232:233], off
	s_waitcnt vmcnt(8)
	s_waitcnt lgkmcnt(0)
	s_barrier
; #define PG8_STAGE(bufoff, gbase, voff) do { _Pragma("unroll") for (int _i = 0; _i < 2; ++_i) \
;         __builtin_amdgcn_global_load_lds((const unsigned*)((const char*)(gbase) + (voff)[_i]), (PG8_LAS unsigned*)(lds + (bufoff) + ldsw + _i * 8192), 16, 0, 0); } while (0)
; #define PG8_LDA(dst, b, h) do { _Pragma("unroll") for (int m = 0; m < 4; ++m) _Pragma("unroll") for (int k = 0; k < 2; ++k) dst[m][k] = *(const PG8_LAS bf16x8*)(lds + PG8_SA(b, h) + aoff + m * 2048 + k * 1024); } while (0)
; #define PG8_LDB(dst, b, h) do { _Pragma("unroll") for (int n = 0; n < 2; ++n) _Pragma("unroll") for (int k = 0; k < 2; ++k) dst[n][k] = *(const PG8_LAS bf16x8*)(lds + PG8_SB(b, h) + boff + n * 2048 + k * 1024); } while (0)
; #define PG8_MMA(ai, bj, At, Bt) do { __builtin_amdgcn_s_setprio(3); _Pragma("unroll") for (int m = 0; m < 4; ++m) _Pragma("unroll") for (int n = 0; n < 2; ++n) _Pragma("unroll") for (int k = 0; k < 2; ++k) \
;         acc[ai][bj][m][n] = __builtin_amdgcn_mfma_f32_16x16x32_bf16(Bt[n][k], At[m][k], acc[ai][bj][m][n], 0, 0, 0); __builtin_amdgcn_s_setprio(0); } while (0)
; #define PG8_WAIT_V(n) asm volatile("s_waitcnt vmcnt(" #n ")" ::: "memory")
; #define PG8_WAIT_L(n) asm volatile("s_waitcnt lgkmcnt(" #n ")" ::: "memory")
; #define PG8_BAR __builtin_amdgcn_s_barrier()
; #define PG8_SCHED __builtin_amdgcn_sched_barrier(0)
; template <class Epi, class Sched, bool ALIGN_EPI = false, bool SP2 = false>
; __device__ __forceinline__ void gemm_phase(PG8_LAS unsigned char* lds, const Gemm g, const Sched& S, const Epi& E) {
;     ...
;             PG8_WAIT_V(8); PG8_WAIT_L(0); PG8_BAR; PG8_MMA(1, 0, At, B0); PG8_MMA(1, 1, At, B1); PG8_BAR; PG8_SCHED;
;             PG8_LDB(B0, 1, 0); PG8_LDB(B1, 1, 1); PG8_SCHED; PG8_LDA(At, 1, 0); PG8_STAGE(PG8_SA(0, 1), a2 + hstepA, voffA);
;             PG8_WAIT_V(8); PG8_WAIT_L(0); PG8_BAR; PG8_MMA(0, 0, At, B0); PG8_MMA(0, 1, At, B1); PG8_BAR; PG8_SCHED;
	s_setprio 3
	s_waitcnt lgkmcnt(0)
	v_mfma_f32_16x16x32_bf16 v[66:69], v[134:137], v[194:197], v[66:69]
	v_mfma_f32_16x16x32_bf16 v[62:65], v[142:145], v[194:197], v[62:65]
	v_mfma_f32_16x16x32_bf16 v[46:49], v[142:145], v[202:205], v[46:49]
	v_mfma_f32_16x16x32_bf16 v[50:53], v[134:137], v[202:205], v[50:53]
	v_mfma_f32_16x16x32_bf16 v[34:37], v[134:137], v[210:213], v[34:37]
	v_mfma_f32_16x16x32_bf16 v[30:33], v[142:145], v[210:213], v[30:33]
	v_mfma_f32_16x16x32_bf16 v[14:17], v[142:145], v[218:221], v[14:17]
	v_mfma_f32_16x16x32_bf16 v[18:21], v[134:137], v[218:221], v[18:21]
	v_mfma_f32_16x16x32_bf16 v[66:69], v[138:141], v[198:201], v[66:69]
	v_mfma_f32_16x16x32_bf16 v[62:65], v[146:149], v[198:201], v[62:65]
	v_mfma_f32_16x16x32_bf16 v[46:49], v[146:149], v[206:209], v[46:49]
	v_mfma_f32_16x16x32_bf16 v[50:53], v[138:141], v[206:209], v[50:53]
	v_mfma_f32_16x16x32_bf16 v[34:37], v[138:141], v[214:217], v[34:37]
	v_mfma_f32_16x16x32_bf16 v[30:33], v[146:149], v[214:217], v[30:33]
	v_mfma_f32_16x16x32_bf16 v[14:17], v[146:149], v[222:225], v[14:17]
	v_mfma_f32_16x16x32_bf16 v[18:21], v[138:141], v[222:225], v[18:21]
	s_setprio 0
	s_setprio 3
	v_mfma_f32_16x16x32_bf16 v[58:61], v[150:153], v[194:197], v[58:61]
	v_mfma_f32_16x16x32_bf16 v[54:57], v[158:161], v[194:197], v[54:57]
	v_mfma_f32_16x16x32_bf16 v[38:41], v[158:161], v[202:205], v[38:41]
	v_mfma_f32_16x16x32_bf16 v[42:45], v[150:153], v[202:205], v[42:45]
	v_mfma_f32_16x16x32_bf16 v[26:29], v[150:153], v[210:213], v[26:29]
	v_mfma_f32_16x16x32_bf16 v[22:25], v[158:161], v[210:213], v[22:25]
	v_mfma_f32_16x16x32_bf16 v[4:7], v[158:161], v[218:221], v[6:9]
	v_mfma_f32_16x16x32_bf16 v[10:13], v[150:153], v[218:221], v[10:13]
	v_mfma_f32_16x16x32_bf16 v[58:61], v[154:157], v[198:201], v[58:61]
	v_mfma_f32_16x16x32_bf16 v[54:57], v[190:193], v[198:201], v[54:57]
	v_mfma_f32_16x16x32_bf16 v[38:41], v[190:193], v[206:209], v[38:41]
	v_mfma_f32_16x16x32_bf16 v[42:45], v[154:157], v[206:209], v[42:45]
	v_mfma_f32_16x16x32_bf16 v[26:29], v[154:157], v[214:217], v[26:29]
	v_mfma_f32_16x16x32_bf16 v[22:25], v[190:193], v[214:217], v[22:25]
	v_mfma_f32_16x16x32_bf16 v[4:7], v[190:193], v[222:225], v[4:7]
	v_mfma_f32_16x16x32_bf16 v[10:13], v[154:157], v[222:225], v[10:13]
	s_setprio 0
	s_barrier
	s_add_i32 s86, 0, 0x18000
	v_add_u32_e32 v3, s86, v186
	s_add_i32 s87, 0, 0x1c000
	ds_read_b128 v[134:137], v3
	ds_read_b128 v[138:141], v3 offset:1024
	ds_read_b128 v[142:145], v3 offset:2048
	ds_read_b128 v[146:149], v3 offset:3072
	v_add_u32_e32 v3, s87, v186
	ds_read_b128 v[150:153], v3
	ds_read_b128 v[154:157], v3 offset:1024
	ds_read_b128 v[158:161], v3 offset:2048
	ds_read_b128 v[190:193], v3 offset:3072
	s_add_u32 s40, s40, 0x100000
	s_addc_u32 s41, s41, 0
	s_mov_b32 m0, s44
	v_lshl_add_u64 v[8:9], s[40:41], 0, v[164:165]
	ds_read_b128 v[194:197], v188 offset:32768
	ds_read_b128 v[198:201], v188 offset:33792
	ds_read_b128 v[202:205], v188 offset:34816
	ds_read_b128 v[206:209], v188 offset:35840
	ds_read_b128 v[210:213], v188 offset:36864
	ds_read_b128 v[214:217], v188 offset:37888
	ds_read_b128 v[218:221], v188 offset:38912
	ds_read_b128 v[222:225], v188 offset:39936
	global_load_lds_dwordx4 v[8:9], off
	v_lshl_add_u64 v[8:9], s[40:41], 0, v[168:169]
	s_mov_b32 m0, s45
	s_nop 0
	global_load_lds_dwordx4 v[8:9], off
	s_waitcnt vmcnt(8)
	s_waitcnt lgkmcnt(0)
	s_barrier
	s_setprio 3
	s_waitcnt lgkmcnt(0)
	v_mfma_f32_16x16x32_bf16 v[130:133], v[134:137], v[194:197], v[130:133]
	v_mfma_f32_16x16x32_bf16 v[126:129], v[142:145], v[194:197], v[126:129]
	v_mfma_f32_16x16x32_bf16 v[110:113], v[142:145], v[202:205], v[110:113]
	v_mfma_f32_16x16x32_bf16 v[114:117], v[134:137], v[202:205], v[114:117]
	v_mfma_f32_16x16x32_bf16 v[98:101], v[134:137], v[210:213], v[98:101]
	v_mfma_f32_16x16x32_bf16 v[94:97], v[142:145], v[210:213], v[94:97]
	v_mfma_f32_16x16x32_bf16 v[78:81], v[142:145], v[218:221], v[78:81]
	v_mfma_f32_16x16x32_bf16 v[82:85], v[134:137], v[218:221], v[82:85]
	v_mfma_f32_16x16x32_bf16 v[130:133], v[138:141], v[198:201], v[130:133]
	v_mfma_f32_16x16x32_bf16 v[126:129], v[146:149], v[198:201], v[126:129]
	v_mfma_f32_16x16x32_bf16 v[110:113], v[146:149], v[206:209], v[110:113]
	v_mfma_f32_16x16x32_bf16 v[114:117], v[138:141], v[206:209], v[114:117]
	v_mfma_f32_16x16x32_bf16 v[98:101], v[138:141], v[214:217], v[98:101]
	v_mfma_f32_16x16x32_bf16 v[94:97], v[146:149], v[214:217], v[94:97]
	v_mfma_f32_16x16x32_bf16 v[78:81], v[146:149], v[222:225], v[78:81]
	v_mfma_f32_16x16x32_bf16 v[82:85], v[138:141], v[222:225], v[82:85]
	s_setprio 0
	s_setprio 3
	v_mfma_f32_16x16x32_bf16 v[122:125], v[150:153], v[194:197], v[122:125]
	v_mfma_f32_16x16x32_bf16 v[118:121], v[158:161], v[194:197], v[118:121]
	v_mfma_f32_16x16x32_bf16 v[102:105], v[158:161], v[202:205], v[102:105]
	v_mfma_f32_16x16x32_bf16 v[106:109], v[150:153], v[202:205], v[106:109]
	v_mfma_f32_16x16x32_bf16 v[90:93], v[150:153], v[210:213], v[90:93]
	v_mfma_f32_16x16x32_bf16 v[86:89], v[158:161], v[210:213], v[86:89]
	v_mfma_f32_16x16x32_bf16 v[70:73], v[158:161], v[218:221], v[70:73]
	v_mfma_f32_16x16x32_bf16 v[74:77], v[150:153], v[218:221], v[74:77]
	v_mfma_f32_16x16x32_bf16 v[122:125], v[154:157], v[198:201], v[122:125]
	v_mfma_f32_16x16x32_bf16 v[118:121], v[190:193], v[198:201], v[118:121]
	v_mfma_f32_16x16x32_bf16 v[102:105], v[190:193], v[206:209], v[102:105]
	v_mfma_f32_16x16x32_bf16 v[106:109], v[154:157], v[206:209], v[106:109]
	v_mfma_f32_16x16x32_bf16 v[90:93], v[154:157], v[214:217], v[90:93]
	v_mfma_f32_16x16x32_bf16 v[86:89], v[190:193], v[214:217], v[86:89]
	v_mfma_f32_16x16x32_bf16 v[70:73], v[190:193], v[222:225], v[70:73]
	v_mfma_f32_16x16x32_bf16 v[74:77], v[154:157], v[222:225], v[74:77]
	s_setprio 0
	s_barrier
; #define PG8_STAGE(bufoff, gbase, voff) do { _Pragma("unroll") for (int _i = 0; _i < 2; ++_i) \
;         __builtin_amdgcn_global_load_lds((const unsigned*)((const char*)(gbase) + (voff)[_i]), (PG8_LAS unsigned*)(lds + (bufoff) + ldsw + _i * 8192), 16, 0, 0); } while (0)
; #define PG8_LDA(dst, b, h) do { _Pragma("unroll") for (int m = 0; m < 4; ++m) _Pragma("unroll") for (int k = 0; k < 2; ++k) dst[m][k] = *(const PG8_LAS bf16x8*)(lds + PG8_SA(b, h) + aoff + m * 2048 + k * 1024); } while (0)
; #define PG8_MMA(ai, bj, At, Bt) do { __builtin_amdgcn_s_setprio(3); _Pragma("unroll") for (int m = 0; m < 4; ++m) _Pragma("unroll") for (int n = 0; n < 2; ++n) _Pragma("unroll") for (int k = 0; k < 2; ++k) \
;         acc[ai][bj][m][n] = __builtin_amdgcn_mfma_f32_16x16x32_bf16(Bt[n][k], At[m][k], acc[ai][bj][m][n], 0, 0, 0); __builtin_amdgcn_s_setprio(0); } while (0)
; #define PG8_WAIT_V(n) asm volatile("s_waitcnt vmcnt(" #n ")" ::: "memory")
; #define PG8_WAIT_L(n) asm volatile("s_waitcnt lgkmcnt(" #n ")" ::: "memory")
; #define PG8_BAR __builtin_amdgcn_s_barrier()
; #define PG8_SCHED __builtin_amdgcn_sched_barrier(0)
; template <class Epi, class Sched, bool ALIGN_EPI = false, bool SP2 = false>
; __device__ __forceinline__ void gemm_phase(PG8_LAS unsigned char* lds, const Gemm g, const Sched& S, const Epi& E) {
;     ...
;             PG8_LDA(At, 1, 1); PG8_STAGE(PG8_SB(1, 0), b3, voffB); PG8_STAGE(PG8_SB(1, 1), b3 + hstepB, voffB); PG8_STAGE(PG8_SA(1, 0), a3, voffA);
;             PG8_WAIT_V(8); PG8_WAIT_L(0); PG8_BAR; PG8_MMA(1, 0, At, B0); PG8_MMA(1, 1, At, B1); PG8_BAR; PG8_SCHED;
	s_add_i32 s40, s86, s33
	v_lshl_add_u64 v[8:9], v[226:227], 0, s[10:11]
	s_mov_b32 m0, s40
	ds_read_b128 v[194:197], v188 offset:49152
	ds_read_b128 v[198:201], v188 offset:50176
	ds_read_b128 v[202:205], v188 offset:51200
	ds_read_b128 v[206:209], v188 offset:52224
	ds_read_b128 v[210:213], v188 offset:53248
	ds_read_b128 v[214:217], v188 offset:54272
	ds_read_b128 v[218:221], v188 offset:55296
	ds_read_b128 v[222:225], v188 offset:56320
	global_load_lds_dwordx4 v[8:9], off
	s_add_i32 m0, s40, 0x2000
	s_add_u32 s36, s36, 0x100080
	v_lshl_add_u64 v[8:9], v[228:229], 0, s[10:11]
	s_addc_u32 s37, s37, 0
	s_add_i32 s40, s87, s33
	global_load_lds_dwordx4 v[8:9], off
	v_lshl_add_u64 v[8:9], s[36:37], 0, v[166:167]
	s_mov_b32 m0, s40
	s_nop 0
	global_load_lds_dwordx4 v[8:9], off
	v_lshl_add_u64 v[8:9], s[36:37], 0, v[170:171]
	s_add_i32 m0, s40, 0x2000
	s_nop 0
	global_load_lds_dwordx4 v[8:9], off
	v_lshl_add_u64 v[8:9], v[230:231], 0, s[10:11]
	s_mov_b32 m0, s60
	s_nop 0
	global_load_lds_dwordx4 v[8:9], off
	v_lshl_add_u64 v[8:9], v[232:233], 0, s[10:11]
	s_mov_b32 m0, s61
	s_nop 0
	global_load_lds_dwordx4 v[8:9], off
	s_waitcnt vmcnt(8)
	s_waitcnt lgkmcnt(0)
	s_barrier
	s_setprio 3
	s_waitcnt lgkmcnt(0)
	v_mfma_f32_16x16x32_bf16 v[66:69], v[134:137], v[194:197], v[66:69]
	v_mfma_f32_16x16x32_bf16 v[62:65], v[142:145], v[194:197], v[62:65]
	v_mfma_f32_16x16x32_bf16 v[46:49], v[142:145], v[202:205], v[46:49]
	v_mfma_f32_16x16x32_bf16 v[50:53], v[134:137], v[202:205], v[50:53]
	v_mfma_f32_16x16x32_bf16 v[34:37], v[134:137], v[210:213], v[34:37]
	v_mfma_f32_16x16x32_bf16 v[30:33], v[142:145], v[210:213], v[30:33]
	v_mfma_f32_16x16x32_bf16 v[14:17], v[142:145], v[218:221], v[14:17]
	v_mfma_f32_16x16x32_bf16 v[18:21], v[134:137], v[218:221], v[18:21]
	v_mfma_f32_16x16x32_bf16 v[66:69], v[138:141], v[198:201], v[66:69]
	v_mfma_f32_16x16x32_bf16 v[62:65], v[146:149], v[198:201], v[62:65]
	v_mfma_f32_16x16x32_bf16 v[46:49], v[146:149], v[206:209], v[46:49]
	v_mfma_f32_16x16x32_bf16 v[50:53], v[138:141], v[206:209], v[50:53]
	v_mfma_f32_16x16x32_bf16 v[34:37], v[138:141], v[214:217], v[34:37]
	v_mfma_f32_16x16x32_bf16 v[30:33], v[146:149], v[214:217], v[30:33]
	v_mfma_f32_16x16x32_bf16 v[14:17], v[146:149], v[222:225], v[14:17]
	v_mfma_f32_16x16x32_bf16 v[18:21], v[138:141], v[222:225], v[18:21]
	s_setprio 0
	s_setprio 3
	v_mfma_f32_16x16x32_bf16 v[58:61], v[150:153], v[194:197], v[58:61]
	v_mfma_f32_16x16x32_bf16 v[54:57], v[158:161], v[194:197], v[54:57]
	v_mfma_f32_16x16x32_bf16 v[42:45], v[150:153], v[202:205], v[42:45]
	v_mfma_f32_16x16x32_bf16 v[38:41], v[158:161], v[202:205], v[38:41]
	v_mfma_f32_16x16x32_bf16 v[26:29], v[150:153], v[210:213], v[26:29]
	v_mfma_f32_16x16x32_bf16 v[22:25], v[158:161], v[210:213], v[22:25]
	v_mfma_f32_16x16x32_bf16 v[8:11], v[150:153], v[218:221], v[10:13]
	v_mfma_f32_16x16x32_bf16 v[4:7], v[158:161], v[218:221], v[4:7]
	v_mfma_f32_16x16x32_bf16 v[58:61], v[154:157], v[198:201], v[58:61]
	v_mfma_f32_16x16x32_bf16 v[54:57], v[190:193], v[198:201], v[54:57]
	v_mfma_f32_16x16x32_bf16 v[42:45], v[154:157], v[206:209], v[42:45]
	v_mfma_f32_16x16x32_bf16 v[38:41], v[190:193], v[206:209], v[38:41]
	v_mfma_f32_16x16x32_bf16 v[26:29], v[154:157], v[214:217], v[26:29]
	v_mfma_f32_16x16x32_bf16 v[22:25], v[190:193], v[214:217], v[22:25]
	v_mfma_f32_16x16x32_bf16 v[10:13], v[154:157], v[222:225], v[8:11]
	v_mfma_f32_16x16x32_bf16 v[6:9], v[190:193], v[222:225], v[4:7]
	s_setprio 0
	s_barrier
	s_add_i32 s85, s85, 2
	s_add_u32 s30, s30, 0x100
	s_addc_u32 s31, s31, 0
	s_cmp_gt_u32 s85, 61
	s_cbranch_scc1 .LBB0_811

; #define PG8_STAGE(bufoff, gbase, voff) do { _Pragma("unroll") for (int _i = 0; _i < 2; ++_i) \
;         __builtin_amdgcn_global_load_lds((const unsigned*)((const char*)(gbase) + (voff)[_i]), (PG8_LAS unsigned*)(lds + (bufoff) + ldsw + _i * 8192), 16, 0, 0); } while (0)
; #define PG8_LDA(dst, b, h) do { _Pragma("unroll") for (int m = 0; m < 4; ++m) _Pragma("unroll") for (int k = 0; k < 2; ++k) dst[m][k] = *(const PG8_LAS bf16x8*)(lds + PG8_SA(b, h) + aoff + m * 2048 + k * 1024); } while (0)
; #define PG8_LDB(dst, b, h) do { _Pragma("unroll") for (int n = 0; n < 2; ++n) _Pragma("unroll") for (int k = 0; k < 2; ++k) dst[n][k] = *(const PG8_LAS bf16x8*)(lds + PG8_SB(b, h) + boff + n * 2048 + k * 1024); } while (0)
; #define PG8_MMA(ai, bj, At, Bt) do { __builtin_amdgcn_s_setprio(3); _Pragma("unroll") for (int m = 0; m < 4; ++m) _Pragma("unroll") for (int n = 0; n < 2; ++n) _Pragma("unroll") for (int k = 0; k < 2; ++k) \
;         acc[ai][bj][m][n] = __builtin_amdgcn_mfma_f32_16x16x32_bf16(Bt[n][k], At[m][k], acc[ai][bj][m][n], 0, 0, 0); __builtin_amdgcn_s_setprio(0); } while (0)
; #define PG8_WAIT_V(n) asm volatile("s_waitcnt vmcnt(" #n ")" ::: "memory")
; #define PG8_WAIT_L(n) asm volatile("s_waitcnt lgkmcnt(" #n ")" ::: "memory")
; template <class Epi, class Sched, bool ALIGN_EPI = false, bool SP2 = false>
; __device__ __forceinline__ void gemm_phase(PG8_LAS unsigned char* lds, const Gemm g, const Sched& S, const Epi& E) {
;     ...
;         for (int t = 0; t < nt; t += 2) {
;             const bool last = (t == nt - 2);
;             const char* a1 = cA + (size_t)(t + 1) * kstep;
;             const char* a2 = last ? nA : cA + (size_t)(t + 2) * kstep; const char* b2 = last ? nB : cB + (size_t)(t + 2) * kstep;
;             const char* a3 = a2 + kstep; const char* b3 = b2 + kstep;
;             if (last && has_next) S.a_ready(nxt);
;             if constexpr (Epi::MIDK) { if (t == E.midk_step(nt)) E.midk(acc, cur, wr, wc, fr, fq); }
;             if constexpr (SP2) {
;             PG8_LDB(B0, 0, 0); PG8_LDB(B1, 0, 1); PG8_SCHED; PG8_LDA(At, 0, 0); PG8_STAGE(PG8_SA(1, 1), a1 + hstepA, voffA);
;             PG8_WAIT_V(8); PG8_WAIT_L(0); PG8_BAR; PG8_MMA(0, 0, At, B0); PG8_MMA(0, 1, At, B1); PG8_BAR; PG8_SCHED;
;             PG8_LDA(At, 0, 1); PG8_STAGE(PG8_SB(0, 0), b2, voffB); PG8_STAGE(PG8_SB(0, 1), b2 + hstepB, voffB); PG8_STAGE(PG8_SA(0, 0), a2, voffA);
.LBB0_908:
	ds_read_b128 v[158:161], v155
	ds_read_b128 v[164:167], v155 offset:1024
	ds_read_b128 v[168:171], v155 offset:2048
	ds_read_b128 v[172:175], v155 offset:3072
	ds_read_b128 v[176:179], v156
	ds_read_b128 v[180:183], v156 offset:1024
	ds_read_b128 v[184:187], v156 offset:2048
	ds_read_b128 v[188:191], v156 offset:3072
	s_add_u32 s26, s24, 0xfff00080
	s_addc_u32 s27, s25, -1
	s_cmp_eq_u32 s55, 60
	s_cselect_b32 s29, s17, s27
	s_cselect_b32 s28, s47, s26
	s_cselect_b32 s27, s15, s54
	s_cselect_b32 s26, s52, s53
	v_lshl_add_u64 v[146:147], s[24:25], 0, v[138:139]
	s_add_i32 m0, s23, 0xc000
	ds_read_b128 v[192:195], v157
	ds_read_b128 v[196:199], v157 offset:1024
	ds_read_b128 v[200:203], v157 offset:2048
	ds_read_b128 v[204:207], v157 offset:3072
	ds_read_b128 v[208:211], v157 offset:4096
	ds_read_b128 v[212:215], v157 offset:5120
	ds_read_b128 v[216:219], v157 offset:6144
	ds_read_b128 v[220:223], v157 offset:7168
	global_load_lds_dwordx4 v[146:147], off
	v_lshl_add_u64 v[146:147], s[24:25], 0, v[140:141]
	s_add_i32 m0, s23, 0xe000
	s_nop 0
	global_load_lds_dwordx4 v[146:147], off
	s_waitcnt vmcnt(8)
	s_waitcnt lgkmcnt(0)
	s_barrier
	s_setprio 3
	s_waitcnt lgkmcnt(0)
	v_mfma_f32_16x16x32_bf16 v[126:129], v[158:161], v[192:195], v[126:129]
	v_mfma_f32_16x16x32_bf16 v[122:125], v[168:171], v[192:195], v[122:125]
	v_mfma_f32_16x16x32_bf16 v[106:109], v[168:171], v[200:203], v[106:109]
	v_mfma_f32_16x16x32_bf16 v[114:117], v[158:161], v[200:203], v[114:117]
	v_mfma_f32_16x16x32_bf16 v[98:101], v[158:161], v[208:211], v[98:101]
	v_mfma_f32_16x16x32_bf16 v[90:93], v[168:171], v[208:211], v[90:93]
	v_mfma_f32_16x16x32_bf16 v[74:77], v[168:171], v[216:219], v[74:77]
	v_mfma_f32_16x16x32_bf16 v[82:85], v[158:161], v[216:219], v[82:85]
	v_mfma_f32_16x16x32_bf16 v[126:129], v[164:167], v[196:199], v[126:129]
	v_mfma_f32_16x16x32_bf16 v[122:125], v[172:175], v[196:199], v[122:125]
	v_mfma_f32_16x16x32_bf16 v[106:109], v[172:175], v[204:207], v[106:109]
	v_mfma_f32_16x16x32_bf16 v[114:117], v[164:167], v[204:207], v[114:117]
	v_mfma_f32_16x16x32_bf16 v[98:101], v[164:167], v[212:215], v[98:101]
	v_mfma_f32_16x16x32_bf16 v[90:93], v[172:175], v[212:215], v[90:93]
	v_mfma_f32_16x16x32_bf16 v[74:77], v[172:175], v[220:223], v[74:77]
	v_mfma_f32_16x16x32_bf16 v[82:85], v[164:167], v[220:223], v[82:85]
	s_setprio 0
	s_setprio 3
	v_mfma_f32_16x16x32_bf16 v[118:121], v[176:179], v[192:195], v[118:121]
	v_mfma_f32_16x16x32_bf16 v[110:113], v[184:187], v[192:195], v[110:113]
	v_mfma_f32_16x16x32_bf16 v[94:97], v[184:187], v[200:203], v[94:97]
	v_mfma_f32_16x16x32_bf16 v[102:105], v[176:179], v[200:203], v[102:105]
	v_mfma_f32_16x16x32_bf16 v[86:89], v[176:179], v[208:211], v[86:89]
	v_mfma_f32_16x16x32_bf16 v[78:81], v[184:187], v[208:211], v[78:81]
	v_mfma_f32_16x16x32_bf16 v[66:69], v[184:187], v[216:219], v[66:69]
	v_mfma_f32_16x16x32_bf16 v[70:73], v[176:179], v[216:219], v[70:73]
	v_mfma_f32_16x16x32_bf16 v[118:121], v[180:183], v[196:199], v[118:121]
	v_mfma_f32_16x16x32_bf16 v[110:113], v[188:191], v[196:199], v[110:113]
	v_mfma_f32_16x16x32_bf16 v[94:97], v[188:191], v[204:207], v[94:97]
	v_mfma_f32_16x16x32_bf16 v[102:105], v[180:183], v[204:207], v[102:105]
	v_mfma_f32_16x16x32_bf16 v[86:89], v[180:183], v[212:215], v[86:89]
	v_mfma_f32_16x16x32_bf16 v[78:81], v[188:191], v[212:215], v[78:81]
	v_mfma_f32_16x16x32_bf16 v[66:69], v[188:191], v[220:223], v[66:69]
	v_mfma_f32_16x16x32_bf16 v[70:73], v[180:183], v[220:223], v[70:73]
	s_setprio 0
	s_barrier
	s_add_i32 s56, s42, s30
	v_lshl_add_u64 v[146:147], s[26:27], 0, v[134:135]
	s_mov_b32 m0, s56
	ds_read_b128 v[192:195], v157 offset:16384
	ds_read_b128 v[196:199], v157 offset:17408
	ds_read_b128 v[200:203], v157 offset:18432
	ds_read_b128 v[204:207], v157 offset:19456
	ds_read_b128 v[208:211], v157 offset:20480
	ds_read_b128 v[212:215], v157 offset:21504
	ds_read_b128 v[216:219], v157 offset:22528
	ds_read_b128 v[220:223], v157 offset:23552
	global_load_lds_dwordx4 v[146:147], off
	s_add_i32 m0, s56, 0x2000
	s_add_u32 s56, s26, 0x100000
	v_lshl_add_u64 v[224:225], s[26:27], 0, v[130:131]
	s_addc_u32 s57, s27, 0
	s_add_i32 s58, s43, s30
	global_load_lds_dwordx4 v[224:225], off
	v_lshl_add_u64 v[226:227], s[56:57], 0, v[134:135]
	s_mov_b32 m0, s58
	v_lshl_add_u64 v[228:229], s[28:29], 0, v[132:133]
	global_load_lds_dwordx4 v[226:227], off
	v_lshl_add_u64 v[226:227], s[56:57], 0, v[130:131]
	s_add_i32 m0, s58, 0x2000
	s_nop 0
	global_load_lds_dwordx4 v[226:227], off
	v_lshl_add_u64 v[226:227], s[28:29], 0, v[136:137]
	s_mov_b32 m0, s23
	s_nop 0
	global_load_lds_dwordx4 v[226:227], off
	s_mov_b32 m0, s33
	s_nop 0
	global_load_lds_dwordx4 v[228:229], off
	s_waitcnt vmcnt(8)
	s_waitcnt lgkmcnt(0)
	s_barrier
; #define PG8_STAGE(bufoff, gbase, voff) do { _Pragma("unroll") for (int _i = 0; _i < 2; ++_i) \
;         __builtin_amdgcn_global_load_lds((const unsigned*)((const char*)(gbase) + (voff)[_i]), (PG8_LAS unsigned*)(lds + (bufoff) + ldsw + _i * 8192), 16, 0, 0); } while (0)
; #define PG8_LDA(dst, b, h) do { _Pragma("unroll") for (int m = 0; m < 4; ++m) _Pragma("unroll") for (int k = 0; k < 2; ++k) dst[m][k] = *(const PG8_LAS bf16x8*)(lds + PG8_SA(b, h) + aoff + m * 2048 + k * 1024); } while (0)
; #define PG8_LDB(dst, b, h) do { _Pragma("unroll") for (int n = 0; n < 2; ++n) _Pragma("unroll") for (int k = 0; k < 2; ++k) dst[n][k] = *(const PG8_LAS bf16x8*)(lds + PG8_SB(b, h) + boff + n * 2048 + k * 1024); } while (0)
; #define PG8_MMA(ai, bj, At, Bt) do { __builtin_amdgcn_s_setprio(3); _Pragma("unroll") for (int m = 0; m < 4; ++m) _Pragma("unroll") for (int n = 0; n < 2; ++n) _Pragma("unroll") for (int k = 0; k < 2; ++k) \
;         acc[ai][bj][m][n] = __builtin_amdgcn_mfma_f32_16x16x32_bf16(Bt[n][k], At[m][k], acc[ai][bj][m][n], 0, 0, 0); __builtin_amdgcn_s_setprio(0); } while (0)
; #define PG8_WAIT_V(n) asm volatile("s_waitcnt vmcnt(" #n ")" ::: "memory")
; #define PG8_WAIT_L(n) asm volatile("s_waitcnt lgkmcnt(" #n ")" ::: "memory")
; #define PG8_BAR __builtin_amdgcn_s_barrier()
; #define PG8_SCHED __builtin_amdgcn_sched_barrier(0)
; template <class Epi, class Sched, bool ALIGN_EPI = false, bool SP2 = false>
; __device__ __forceinline__ void gemm_phase(PG8_LAS unsigned char* lds, const Gemm g, const Sched& S, const Epi& E) {
;     ...
;             PG8_WAIT_V(8); PG8_WAIT_L(0); PG8_BAR; PG8_MMA(1, 0, At, B0); PG8_MMA(1, 1, At, B1); PG8_BAR; PG8_SCHED;
;             PG8_LDB(B0, 1, 0); PG8_LDB(B1, 1, 1); PG8_SCHED; PG8_LDA(At, 1, 0); PG8_STAGE(PG8_SA(0, 1), a2 + hstepA, voffA);
;             PG8_WAIT_V(8); PG8_WAIT_L(0); PG8_BAR; PG8_MMA(0, 0, At, B0); PG8_MMA(0, 1, At, B1); PG8_BAR; PG8_SCHED;
	s_setprio 3
	s_waitcnt lgkmcnt(0)
	v_mfma_f32_16x16x32_bf16 v[62:65], v[158:161], v[192:195], v[62:65]
	v_mfma_f32_16x16x32_bf16 v[58:61], v[168:171], v[192:195], v[58:61]
	v_mfma_f32_16x16x32_bf16 v[42:45], v[168:171], v[200:203], v[42:45]
	v_mfma_f32_16x16x32_bf16 v[50:53], v[158:161], v[200:203], v[50:53]
	v_mfma_f32_16x16x32_bf16 v[34:37], v[158:161], v[208:211], v[34:37]
	v_mfma_f32_16x16x32_bf16 v[26:29], v[168:171], v[208:211], v[26:29]
	v_mfma_f32_16x16x32_bf16 v[10:13], v[168:171], v[216:219], v[10:13]
	v_mfma_f32_16x16x32_bf16 v[14:17], v[158:161], v[216:219], v[14:17]
	v_mfma_f32_16x16x32_bf16 v[62:65], v[164:167], v[196:199], v[62:65]
	v_mfma_f32_16x16x32_bf16 v[58:61], v[172:175], v[196:199], v[58:61]
	v_mfma_f32_16x16x32_bf16 v[42:45], v[172:175], v[204:207], v[42:45]
	v_mfma_f32_16x16x32_bf16 v[50:53], v[164:167], v[204:207], v[50:53]
	v_mfma_f32_16x16x32_bf16 v[34:37], v[164:167], v[212:215], v[34:37]
	v_mfma_f32_16x16x32_bf16 v[26:29], v[172:175], v[212:215], v[26:29]
	v_mfma_f32_16x16x32_bf16 v[10:13], v[172:175], v[220:223], v[10:13]
	v_mfma_f32_16x16x32_bf16 v[14:17], v[164:167], v[220:223], v[14:17]
	s_setprio 0
	s_setprio 3
	v_mfma_f32_16x16x32_bf16 v[54:57], v[176:179], v[192:195], v[54:57]
	v_mfma_f32_16x16x32_bf16 v[46:49], v[184:187], v[192:195], v[46:49]
	v_mfma_f32_16x16x32_bf16 v[30:33], v[184:187], v[200:203], v[30:33]
	v_mfma_f32_16x16x32_bf16 v[38:41], v[176:179], v[200:203], v[38:41]
	v_mfma_f32_16x16x32_bf16 v[22:25], v[176:179], v[208:211], v[22:25]
	v_mfma_f32_16x16x32_bf16 v[18:21], v[184:187], v[208:211], v[18:21]
	v_mfma_f32_16x16x32_bf16 v[2:5], v[184:187], v[216:219], v[2:5]
	v_mfma_f32_16x16x32_bf16 v[6:9], v[176:179], v[216:219], v[6:9]
	v_mfma_f32_16x16x32_bf16 v[54:57], v[180:183], v[196:199], v[54:57]
	v_mfma_f32_16x16x32_bf16 v[46:49], v[188:191], v[196:199], v[46:49]
	v_mfma_f32_16x16x32_bf16 v[30:33], v[188:191], v[204:207], v[30:33]
	v_mfma_f32_16x16x32_bf16 v[38:41], v[180:183], v[204:207], v[38:41]
	v_mfma_f32_16x16x32_bf16 v[22:25], v[180:183], v[212:215], v[22:25]
	v_mfma_f32_16x16x32_bf16 v[18:21], v[188:191], v[212:215], v[18:21]
	v_mfma_f32_16x16x32_bf16 v[2:5], v[188:191], v[220:223], v[2:5]
	v_mfma_f32_16x16x32_bf16 v[6:9], v[180:183], v[220:223], v[6:9]
	s_setprio 0
	s_barrier
	s_add_i32 s56, 0, 0x18000
	v_add_u32_e32 v148, s56, v151
	s_add_i32 s57, 0, 0x1c000
	ds_read_b128 v[158:161], v148
	ds_read_b128 v[164:167], v148 offset:1024
	ds_read_b128 v[168:171], v148 offset:2048
	ds_read_b128 v[172:175], v148 offset:3072
	v_add_u32_e32 v148, s57, v151
	ds_read_b128 v[176:179], v148
	ds_read_b128 v[180:183], v148 offset:1024
	ds_read_b128 v[184:187], v148 offset:2048
	ds_read_b128 v[188:191], v148 offset:3072
	s_add_u32 s28, s28, 0x100000
	s_addc_u32 s29, s29, 0
	s_mov_b32 m0, s36
	v_lshl_add_u64 v[230:231], s[28:29], 0, v[136:137]
	ds_read_b128 v[192:195], v157 offset:32768
	ds_read_b128 v[196:199], v157 offset:33792
	ds_read_b128 v[200:203], v157 offset:34816
	ds_read_b128 v[204:207], v157 offset:35840
	ds_read_b128 v[208:211], v157 offset:36864
	ds_read_b128 v[212:215], v157 offset:37888
	ds_read_b128 v[216:219], v157 offset:38912
	ds_read_b128 v[220:223], v157 offset:39936
	global_load_lds_dwordx4 v[230:231], off
	v_lshl_add_u64 v[230:231], s[28:29], 0, v[132:133]
	s_mov_b32 m0, s37
	s_nop 0
	global_load_lds_dwordx4 v[230:231], off
	s_waitcnt vmcnt(8)
	s_waitcnt lgkmcnt(0)
	s_barrier
	s_setprio 3
	s_waitcnt lgkmcnt(0)
	v_mfma_f32_16x16x32_bf16 v[126:129], v[158:161], v[192:195], v[126:129]
	v_mfma_f32_16x16x32_bf16 v[122:125], v[168:171], v[192:195], v[122:125]
	v_mfma_f32_16x16x32_bf16 v[106:109], v[168:171], v[200:203], v[106:109]
	v_mfma_f32_16x16x32_bf16 v[114:117], v[158:161], v[200:203], v[114:117]
	v_mfma_f32_16x16x32_bf16 v[98:101], v[158:161], v[208:211], v[98:101]
	v_mfma_f32_16x16x32_bf16 v[90:93], v[168:171], v[208:211], v[90:93]
	v_mfma_f32_16x16x32_bf16 v[74:77], v[168:171], v[216:219], v[74:77]
	v_mfma_f32_16x16x32_bf16 v[82:85], v[158:161], v[216:219], v[82:85]
	v_mfma_f32_16x16x32_bf16 v[126:129], v[164:167], v[196:199], v[126:129]
	v_mfma_f32_16x16x32_bf16 v[122:125], v[172:175], v[196:199], v[122:125]
	v_mfma_f32_16x16x32_bf16 v[106:109], v[172:175], v[204:207], v[106:109]
	v_mfma_f32_16x16x32_bf16 v[114:117], v[164:167], v[204:207], v[114:117]
	v_mfma_f32_16x16x32_bf16 v[98:101], v[164:167], v[212:215], v[98:101]
	v_mfma_f32_16x16x32_bf16 v[90:93], v[172:175], v[212:215], v[90:93]
	v_mfma_f32_16x16x32_bf16 v[74:77], v[172:175], v[220:223], v[74:77]
	v_mfma_f32_16x16x32_bf16 v[82:85], v[164:167], v[220:223], v[82:85]
	s_setprio 0
	s_setprio 3
	v_mfma_f32_16x16x32_bf16 v[118:121], v[176:179], v[192:195], v[118:121]
	v_mfma_f32_16x16x32_bf16 v[110:113], v[184:187], v[192:195], v[110:113]
	v_mfma_f32_16x16x32_bf16 v[94:97], v[184:187], v[200:203], v[94:97]
	v_mfma_f32_16x16x32_bf16 v[102:105], v[176:179], v[200:203], v[102:105]
	v_mfma_f32_16x16x32_bf16 v[86:89], v[176:179], v[208:211], v[86:89]
	v_mfma_f32_16x16x32_bf16 v[78:81], v[184:187], v[208:211], v[78:81]
	v_mfma_f32_16x16x32_bf16 v[66:69], v[184:187], v[216:219], v[66:69]
	v_mfma_f32_16x16x32_bf16 v[70:73], v[176:179], v[216:219], v[70:73]
	v_mfma_f32_16x16x32_bf16 v[118:121], v[180:183], v[196:199], v[118:121]
	v_mfma_f32_16x16x32_bf16 v[110:113], v[188:191], v[196:199], v[110:113]
	v_mfma_f32_16x16x32_bf16 v[94:97], v[188:191], v[204:207], v[94:97]
	v_mfma_f32_16x16x32_bf16 v[102:105], v[180:183], v[204:207], v[102:105]
	v_mfma_f32_16x16x32_bf16 v[86:89], v[180:183], v[212:215], v[86:89]
	v_mfma_f32_16x16x32_bf16 v[78:81], v[188:191], v[212:215], v[78:81]
	v_mfma_f32_16x16x32_bf16 v[66:69], v[188:191], v[220:223], v[66:69]
	v_mfma_f32_16x16x32_bf16 v[70:73], v[180:183], v[220:223], v[70:73]
	s_setprio 0
	s_barrier
; #define PG8_STAGE(bufoff, gbase, voff) do { _Pragma("unroll") for (int _i = 0; _i < 2; ++_i) \
;         __builtin_amdgcn_global_load_lds((const unsigned*)((const char*)(gbase) + (voff)[_i]), (PG8_LAS unsigned*)(lds + (bufoff) + ldsw + _i * 8192), 16, 0, 0); } while (0)
; #define PG8_LDA(dst, b, h) do { _Pragma("unroll") for (int m = 0; m < 4; ++m) _Pragma("unroll") for (int k = 0; k < 2; ++k) dst[m][k] = *(const PG8_LAS bf16x8*)(lds + PG8_SA(b, h) + aoff + m * 2048 + k * 1024); } while (0)
; #define PG8_MMA(ai, bj, At, Bt) do { __builtin_amdgcn_s_setprio(3); _Pragma("unroll") for (int m = 0; m < 4; ++m) _Pragma("unroll") for (int n = 0; n < 2; ++n) _Pragma("unroll") for (int k = 0; k < 2; ++k) \
;         acc[ai][bj][m][n] = __builtin_amdgcn_mfma_f32_16x16x32_bf16(Bt[n][k], At[m][k], acc[ai][bj][m][n], 0, 0, 0); __builtin_amdgcn_s_setprio(0); } while (0)
; #define PG8_WAIT_V(n) asm volatile("s_waitcnt vmcnt(" #n ")" ::: "memory")
; #define PG8_WAIT_L(n) asm volatile("s_waitcnt lgkmcnt(" #n ")" ::: "memory")
; #define PG8_BAR __builtin_amdgcn_s_barrier()
; #define PG8_SCHED __builtin_amdgcn_sched_barrier(0)
; template <class Epi, class Sched, bool ALIGN_EPI = false, bool SP2 = false>
; __device__ __forceinline__ void gemm_phase(PG8_LAS unsigned char* lds, const Gemm g, const Sched& S, const Epi& E) {
;     ...
;             PG8_LDA(At, 1, 1); PG8_STAGE(PG8_SB(1, 0), b3, voffB); PG8_STAGE(PG8_SB(1, 1), b3 + hstepB, voffB); PG8_STAGE(PG8_SA(1, 0), a3, voffA);
;             PG8_WAIT_V(8); PG8_WAIT_L(0); PG8_BAR; PG8_MMA(1, 0, At, B0); PG8_MMA(1, 1, At, B1); PG8_BAR; PG8_SCHED;
;     ...
;         if constexpr (ALIGN_EPI) { if (wr == 0) PG8_BAR; }
	s_add_i32 s28, s56, s30
	v_lshl_add_u64 v[146:147], v[146:147], 0, s[12:13]
	s_mov_b32 m0, s28
	ds_read_b128 v[192:195], v157 offset:49152
	ds_read_b128 v[196:199], v157 offset:50176
	ds_read_b128 v[200:203], v157 offset:51200
	ds_read_b128 v[204:207], v157 offset:52224
	ds_read_b128 v[208:211], v157 offset:53248
	ds_read_b128 v[212:215], v157 offset:54272
	ds_read_b128 v[216:219], v157 offset:55296
	ds_read_b128 v[220:223], v157 offset:56320
	global_load_lds_dwordx4 v[146:147], off
	s_add_i32 m0, s28, 0x2000
	s_add_u32 s26, s26, 0x100080
	v_lshl_add_u64 v[146:147], v[224:225], 0, s[12:13]
	s_addc_u32 s27, s27, 0
	s_add_i32 s28, s57, s30
	global_load_lds_dwordx4 v[146:147], off
	v_lshl_add_u64 v[146:147], s[26:27], 0, v[134:135]
	s_mov_b32 m0, s28
	s_nop 0
	global_load_lds_dwordx4 v[146:147], off
	v_lshl_add_u64 v[146:147], s[26:27], 0, v[130:131]
	s_add_i32 m0, s28, 0x2000
	s_nop 0
	global_load_lds_dwordx4 v[146:147], off
	v_lshl_add_u64 v[146:147], v[226:227], 0, s[12:13]
	s_mov_b32 m0, s39
	s_nop 0
	global_load_lds_dwordx4 v[146:147], off
	v_lshl_add_u64 v[146:147], v[228:229], 0, s[12:13]
	s_mov_b32 m0, s40
	s_nop 0
	global_load_lds_dwordx4 v[146:147], off
	s_waitcnt vmcnt(8)
	s_waitcnt lgkmcnt(0)
	s_barrier
	s_setprio 3
	s_waitcnt lgkmcnt(0)
	v_mfma_f32_16x16x32_bf16 v[62:65], v[158:161], v[192:195], v[62:65]
	v_mfma_f32_16x16x32_bf16 v[58:61], v[168:171], v[192:195], v[58:61]
	v_mfma_f32_16x16x32_bf16 v[42:45], v[168:171], v[200:203], v[42:45]
	v_mfma_f32_16x16x32_bf16 v[50:53], v[158:161], v[200:203], v[50:53]
	v_mfma_f32_16x16x32_bf16 v[34:37], v[158:161], v[208:211], v[34:37]
	v_mfma_f32_16x16x32_bf16 v[26:29], v[168:171], v[208:211], v[26:29]
	v_mfma_f32_16x16x32_bf16 v[10:13], v[168:171], v[216:219], v[10:13]
	v_mfma_f32_16x16x32_bf16 v[14:17], v[158:161], v[216:219], v[14:17]
	v_mfma_f32_16x16x32_bf16 v[62:65], v[164:167], v[196:199], v[62:65]
	v_mfma_f32_16x16x32_bf16 v[58:61], v[172:175], v[196:199], v[58:61]
	v_mfma_f32_16x16x32_bf16 v[42:45], v[172:175], v[204:207], v[42:45]
	v_mfma_f32_16x16x32_bf16 v[50:53], v[164:167], v[204:207], v[50:53]
	v_mfma_f32_16x16x32_bf16 v[34:37], v[164:167], v[212:215], v[34:37]
	v_mfma_f32_16x16x32_bf16 v[26:29], v[172:175], v[212:215], v[26:29]
	v_mfma_f32_16x16x32_bf16 v[10:13], v[172:175], v[220:223], v[10:13]
	v_mfma_f32_16x16x32_bf16 v[14:17], v[164:167], v[220:223], v[14:17]
	s_setprio 0
	s_setprio 3
	v_mfma_f32_16x16x32_bf16 v[54:57], v[176:179], v[192:195], v[54:57]
	v_mfma_f32_16x16x32_bf16 v[46:49], v[184:187], v[192:195], v[46:49]
	v_mfma_f32_16x16x32_bf16 v[30:33], v[184:187], v[200:203], v[30:33]
	v_mfma_f32_16x16x32_bf16 v[38:41], v[176:179], v[200:203], v[38:41]
	v_mfma_f32_16x16x32_bf16 v[22:25], v[176:179], v[208:211], v[22:25]
	v_mfma_f32_16x16x32_bf16 v[18:21], v[184:187], v[208:211], v[18:21]
	v_mfma_f32_16x16x32_bf16 v[2:5], v[184:187], v[216:219], v[2:5]
	v_mfma_f32_16x16x32_bf16 v[6:9], v[176:179], v[216:219], v[6:9]
	v_mfma_f32_16x16x32_bf16 v[54:57], v[180:183], v[196:199], v[54:57]
	v_mfma_f32_16x16x32_bf16 v[46:49], v[188:191], v[196:199], v[46:49]
	v_mfma_f32_16x16x32_bf16 v[30:33], v[188:191], v[204:207], v[30:33]
	v_mfma_f32_16x16x32_bf16 v[38:41], v[180:183], v[204:207], v[38:41]
	v_mfma_f32_16x16x32_bf16 v[22:25], v[180:183], v[212:215], v[22:25]
	v_mfma_f32_16x16x32_bf16 v[18:21], v[188:191], v[212:215], v[18:21]
	v_mfma_f32_16x16x32_bf16 v[2:5], v[188:191], v[220:223], v[2:5]
	v_mfma_f32_16x16x32_bf16 v[6:9], v[180:183], v[220:223], v[6:9]
	s_setprio 0
	s_barrier
	s_add_i32 s55, s55, 2
	s_add_u32 s24, s24, 0x100
	s_addc_u32 s25, s25, 0
	s_add_u32 s53, s53, 0x100
	s_addc_u32 s54, s54, 0
	s_cmp_gt_u32 s55, 61
	s_cbranch_scc0 .LBB0_908
	s_and_b64 vcc, exec, s[0:1]
	s_cbranch_vccz .LBB0_911
	s_barrier

; #define PG8_STAGE(bufoff, gbase, voff) do { _Pragma("unroll") for (int _i = 0; _i < 2; ++_i) \
;         __builtin_amdgcn_global_load_lds((const unsigned*)((const char*)(gbase) + (voff)[_i]), (PG8_LAS unsigned*)(lds + (bufoff) + ldsw + _i * 8192), 16, 0, 0); } while (0)
; #define PG8_LDA(dst, b, h) do { _Pragma("unroll") for (int m = 0; m < 4; ++m) _Pragma("unroll") for (int k = 0; k < 2; ++k) dst[m][k] = *(const PG8_LAS bf16x8*)(lds + PG8_SA(b, h) + aoff + m * 2048 + k * 1024); } while (0)
; #define PG8_LDB(dst, b, h) do { _Pragma("unroll") for (int n = 0; n < 2; ++n) _Pragma("unroll") for (int k = 0; k < 2; ++k) dst[n][k] = *(const PG8_LAS bf16x8*)(lds + PG8_SB(b, h) + boff + n * 2048 + k * 1024); } while (0)
; #define PG8_MMA(ai, bj, At, Bt) do { __builtin_amdgcn_s_setprio(3); _Pragma("unroll") for (int m = 0; m < 4; ++m) _Pragma("unroll") for (int n = 0; n < 2; ++n) _Pragma("unroll") for (int k = 0; k < 2; ++k) \
;         acc[ai][bj][m][n] = __builtin_amdgcn_mfma_f32_16x16x32_bf16(Bt[n][k], At[m][k], acc[ai][bj][m][n], 0, 0, 0); __builtin_amdgcn_s_setprio(0); } while (0)
; #define PG8_WAIT_V(n) asm volatile("s_waitcnt vmcnt(" #n ")" ::: "memory")
; #define PG8_WAIT_L(n) asm volatile("s_waitcnt lgkmcnt(" #n ")" ::: "memory")
; template <class Epi, class Sched, bool ALIGN_EPI = false, bool SP2 = false>
; __device__ __forceinline__ void gemm_phase(PG8_LAS unsigned char* lds, const Gemm g, const Sched& S, const Epi& E) {
;     ...
;         for (int t = 0; t < nt; t += 2) {
;             const bool last = (t == nt - 2);
;             const char* a1 = cA + (size_t)(t + 1) * kstep;
;             const char* a2 = last ? nA : cA + (size_t)(t + 2) * kstep; const char* b2 = last ? nB : cB + (size_t)(t + 2) * kstep;
;             const char* a3 = a2 + kstep; const char* b3 = b2 + kstep;
;             if (last && has_next) S.a_ready(nxt);
;             if constexpr (Epi::MIDK) { if (t == E.midk_step(nt)) E.midk(acc, cur, wr, wc, fr, fq); }
;             if constexpr (SP2) {
;             PG8_LDB(B0, 0, 0); PG8_LDB(B1, 0, 1); PG8_SCHED; PG8_LDA(At, 0, 0); PG8_STAGE(PG8_SA(1, 1), a1 + hstepA, voffA);
;             PG8_WAIT_V(8); PG8_WAIT_L(0); PG8_BAR; PG8_MMA(0, 0, At, B0); PG8_MMA(0, 1, At, B1); PG8_BAR; PG8_SCHED;
;             PG8_LDA(At, 0, 1); PG8_STAGE(PG8_SB(0, 0), b2, voffB); PG8_STAGE(PG8_SB(0, 1), b2 + hstepB, voffB); PG8_STAGE(PG8_SA(0, 0), a2, voffA);
.LBB0_975:
	v_add_u32_e32 v144, s46, v206
	v_add_u32_e32 v160, s47, v206
	s_add_u32 s28, s2, s12
	ds_read_b128 v[132:135], v144
	ds_read_b128 v[136:139], v144 offset:1024
	ds_read_b128 v[140:143], v144 offset:2048
	ds_read_b128 v[144:147], v144 offset:3072
	ds_read_b128 v[148:151], v160
	ds_read_b128 v[152:155], v160 offset:1024
	ds_read_b128 v[156:159], v160 offset:2048
	ds_read_b128 v[160:163], v160 offset:3072
	s_addc_u32 s29, s3, s13
	s_add_u32 s28, s28, 0x21500100
	s_addc_u32 s29, s29, 0
	s_add_u32 s81, s44, s12
	s_addc_u32 s82, s45, s13
	s_cmpk_eq_i32 s12, 0x5500
	s_cselect_b32 s31, s1, s29
	s_cselect_b32 s30, s0, s28
	s_cselect_b32 s29, s11, s82
	s_cselect_b32 s28, s10, s81
	s_mov_b32 m0, s71
	v_lshl_add_u64 v[234:235], v[2:3], 0, s[12:13]
	ds_read_b128 v[164:167], v207
	ds_read_b128 v[168:171], v207 offset:1024
	ds_read_b128 v[210:213], v207 offset:2048
	ds_read_b128 v[214:217], v207 offset:3072
	ds_read_b128 v[218:221], v207 offset:4096
	ds_read_b128 v[222:225], v207 offset:5120
	ds_read_b128 v[226:229], v207 offset:6144
	ds_read_b128 v[230:233], v207 offset:7168
	global_load_lds_dwordx4 v[234:235], off
	v_lshl_add_u64 v[234:235], v[200:201], 0, s[12:13]
	s_mov_b32 m0, s72
	s_nop 0
	global_load_lds_dwordx4 v[234:235], off
	s_waitcnt vmcnt(8)
	s_waitcnt lgkmcnt(0)
	s_barrier
	s_setprio 3
	s_waitcnt lgkmcnt(0)
	v_mfma_f32_16x16x32_bf16 v[128:131], v[132:135], v[164:167], v[128:131]
	v_mfma_f32_16x16x32_bf16 v[124:127], v[140:143], v[164:167], v[124:127]
	v_mfma_f32_16x16x32_bf16 v[96:99], v[140:143], v[210:213], v[96:99]
	v_mfma_f32_16x16x32_bf16 v[100:103], v[132:135], v[210:213], v[100:103]
	v_mfma_f32_16x16x32_bf16 v[112:115], v[132:135], v[218:221], v[112:115]
	v_mfma_f32_16x16x32_bf16 v[108:111], v[140:143], v[218:221], v[108:111]
	v_mfma_f32_16x16x32_bf16 v[76:79], v[140:143], v[226:229], v[76:79]
	v_mfma_f32_16x16x32_bf16 v[80:83], v[132:135], v[226:229], v[80:83]
	v_mfma_f32_16x16x32_bf16 v[128:131], v[136:139], v[168:171], v[128:131]
	v_mfma_f32_16x16x32_bf16 v[124:127], v[144:147], v[168:171], v[124:127]
	v_mfma_f32_16x16x32_bf16 v[96:99], v[144:147], v[214:217], v[96:99]
	v_mfma_f32_16x16x32_bf16 v[100:103], v[136:139], v[214:217], v[100:103]
	v_mfma_f32_16x16x32_bf16 v[112:115], v[136:139], v[222:225], v[112:115]
	v_mfma_f32_16x16x32_bf16 v[108:111], v[144:147], v[222:225], v[108:111]
	v_mfma_f32_16x16x32_bf16 v[76:79], v[144:147], v[230:233], v[76:79]
	v_mfma_f32_16x16x32_bf16 v[80:83], v[136:139], v[230:233], v[80:83]
	s_setprio 0
	s_setprio 3
	v_mfma_f32_16x16x32_bf16 v[120:123], v[148:151], v[164:167], v[120:123]
	v_mfma_f32_16x16x32_bf16 v[116:119], v[156:159], v[164:167], v[116:119]
	v_mfma_f32_16x16x32_bf16 v[88:91], v[156:159], v[210:213], v[88:91]
	v_mfma_f32_16x16x32_bf16 v[92:95], v[148:151], v[210:213], v[92:95]
	v_mfma_f32_16x16x32_bf16 v[104:107], v[148:151], v[218:221], v[104:107]
	v_mfma_f32_16x16x32_bf16 v[84:87], v[156:159], v[218:221], v[84:87]
	v_mfma_f32_16x16x32_bf16 v[68:71], v[156:159], v[226:229], v[68:71]
	v_mfma_f32_16x16x32_bf16 v[72:75], v[148:151], v[226:229], v[72:75]
	v_mfma_f32_16x16x32_bf16 v[120:123], v[152:155], v[168:171], v[120:123]
	v_mfma_f32_16x16x32_bf16 v[116:119], v[160:163], v[168:171], v[116:119]
	v_mfma_f32_16x16x32_bf16 v[88:91], v[160:163], v[214:217], v[88:91]
	v_mfma_f32_16x16x32_bf16 v[92:95], v[152:155], v[214:217], v[92:95]
	v_mfma_f32_16x16x32_bf16 v[104:107], v[152:155], v[222:225], v[104:107]
	v_mfma_f32_16x16x32_bf16 v[84:87], v[160:163], v[222:225], v[84:87]
	v_mfma_f32_16x16x32_bf16 v[68:71], v[160:163], v[230:233], v[68:71]
	v_mfma_f32_16x16x32_bf16 v[72:75], v[152:155], v[230:233], v[72:75]
	s_setprio 0
	s_barrier
	s_mov_b32 m0, s73
	v_lshl_add_u64 v[234:235], s[28:29], 0, v[174:175]
	s_add_u32 s82, s28, 0x2b0000
	ds_read_b128 v[164:167], v207 offset:16384
	ds_read_b128 v[168:171], v207 offset:17408
	ds_read_b128 v[210:213], v207 offset:18432
	ds_read_b128 v[214:217], v207 offset:19456
	ds_read_b128 v[218:221], v207 offset:20480
	ds_read_b128 v[222:225], v207 offset:21504
	ds_read_b128 v[226:229], v207 offset:22528
	ds_read_b128 v[230:233], v207 offset:23552
	global_load_lds_dwordx4 v[234:235], off
	v_lshl_add_u64 v[236:237], s[28:29], 0, v[178:179]
	s_mov_b32 m0, s74
	s_addc_u32 s83, s29, 0
	global_load_lds_dwordx4 v[236:237], off
	v_lshl_add_u64 v[238:239], s[82:83], 0, v[174:175]
	s_mov_b32 m0, s75
	v_lshl_add_u64 v[240:241], s[30:31], 0, v[176:177]
	global_load_lds_dwordx4 v[238:239], off
	v_lshl_add_u64 v[238:239], s[82:83], 0, v[178:179]
	s_mov_b32 m0, s76
	s_nop 0
	global_load_lds_dwordx4 v[238:239], off
	v_lshl_add_u64 v[238:239], s[30:31], 0, v[172:173]
	s_mov_b32 m0, s42
	s_nop 0
	global_load_lds_dwordx4 v[238:239], off
	s_mov_b32 m0, s54
	s_nop 0
	global_load_lds_dwordx4 v[240:241], off
	s_waitcnt vmcnt(8)
	s_waitcnt lgkmcnt(0)
	s_barrier
; #define PG8_STAGE(bufoff, gbase, voff) do { _Pragma("unroll") for (int _i = 0; _i < 2; ++_i) \
;         __builtin_amdgcn_global_load_lds((const unsigned*)((const char*)(gbase) + (voff)[_i]), (PG8_LAS unsigned*)(lds + (bufoff) + ldsw + _i * 8192), 16, 0, 0); } while (0)
; #define PG8_LDA(dst, b, h) do { _Pragma("unroll") for (int m = 0; m < 4; ++m) _Pragma("unroll") for (int k = 0; k < 2; ++k) dst[m][k] = *(const PG8_LAS bf16x8*)(lds + PG8_SA(b, h) + aoff + m * 2048 + k * 1024); } while (0)
; #define PG8_LDB(dst, b, h) do { _Pragma("unroll") for (int n = 0; n < 2; ++n) _Pragma("unroll") for (int k = 0; k < 2; ++k) dst[n][k] = *(const PG8_LAS bf16x8*)(lds + PG8_SB(b, h) + boff + n * 2048 + k * 1024); } while (0)
; #define PG8_MMA(ai, bj, At, Bt) do { __builtin_amdgcn_s_setprio(3); _Pragma("unroll") for (int m = 0; m < 4; ++m) _Pragma("unroll") for (int n = 0; n < 2; ++n) _Pragma("unroll") for (int k = 0; k < 2; ++k) \
;         acc[ai][bj][m][n] = __builtin_amdgcn_mfma_f32_16x16x32_bf16(Bt[n][k], At[m][k], acc[ai][bj][m][n], 0, 0, 0); __builtin_amdgcn_s_setprio(0); } while (0)
; #define PG8_WAIT_V(n) asm volatile("s_waitcnt vmcnt(" #n ")" ::: "memory")
; #define PG8_WAIT_L(n) asm volatile("s_waitcnt lgkmcnt(" #n ")" ::: "memory")
; #define PG8_BAR __builtin_amdgcn_s_barrier()
; #define PG8_SCHED __builtin_amdgcn_sched_barrier(0)
; template <class Epi, class Sched, bool ALIGN_EPI = false, bool SP2 = false>
; __device__ __forceinline__ void gemm_phase(PG8_LAS unsigned char* lds, const Gemm g, const Sched& S, const Epi& E) {
;     ...
;             PG8_WAIT_V(8); PG8_WAIT_L(0); PG8_BAR; PG8_MMA(1, 0, At, B0); PG8_MMA(1, 1, At, B1); PG8_BAR; PG8_SCHED;
;             PG8_LDB(B0, 1, 0); PG8_LDB(B1, 1, 1); PG8_SCHED; PG8_LDA(At, 1, 0); PG8_STAGE(PG8_SA(0, 1), a2 + hstepA, voffA);
;             PG8_WAIT_V(8); PG8_WAIT_L(0); PG8_BAR; PG8_MMA(0, 0, At, B0); PG8_MMA(0, 1, At, B1); PG8_BAR; PG8_SCHED;
	s_setprio 3
	s_waitcnt lgkmcnt(0)
	v_mfma_f32_16x16x32_bf16 v[64:67], v[132:135], v[164:167], v[64:67]
	v_mfma_f32_16x16x32_bf16 v[60:63], v[140:143], v[164:167], v[60:63]
	v_mfma_f32_16x16x32_bf16 v[44:47], v[140:143], v[210:213], v[44:47]
	v_mfma_f32_16x16x32_bf16 v[48:51], v[132:135], v[210:213], v[48:51]
	v_mfma_f32_16x16x32_bf16 v[32:35], v[132:135], v[218:221], v[32:35]
	v_mfma_f32_16x16x32_bf16 v[28:31], v[140:143], v[218:221], v[28:31]
	v_mfma_f32_16x16x32_bf16 v[12:15], v[140:143], v[226:229], v[12:15]
	v_mfma_f32_16x16x32_bf16 v[16:19], v[132:135], v[226:229], v[16:19]
	v_mfma_f32_16x16x32_bf16 v[64:67], v[136:139], v[168:171], v[64:67]
	v_mfma_f32_16x16x32_bf16 v[60:63], v[144:147], v[168:171], v[60:63]
	v_mfma_f32_16x16x32_bf16 v[44:47], v[144:147], v[214:217], v[44:47]
	v_mfma_f32_16x16x32_bf16 v[48:51], v[136:139], v[214:217], v[48:51]
	v_mfma_f32_16x16x32_bf16 v[32:35], v[136:139], v[222:225], v[32:35]
	v_mfma_f32_16x16x32_bf16 v[28:31], v[144:147], v[222:225], v[28:31]
	v_mfma_f32_16x16x32_bf16 v[12:15], v[144:147], v[230:233], v[12:15]
	v_mfma_f32_16x16x32_bf16 v[16:19], v[136:139], v[230:233], v[16:19]
	s_setprio 0
	s_setprio 3
	v_mfma_f32_16x16x32_bf16 v[56:59], v[148:151], v[164:167], v[56:59]
	v_mfma_f32_16x16x32_bf16 v[52:55], v[156:159], v[164:167], v[52:55]
	v_mfma_f32_16x16x32_bf16 v[36:39], v[156:159], v[210:213], v[36:39]
	v_mfma_f32_16x16x32_bf16 v[40:43], v[148:151], v[210:213], v[40:43]
	v_mfma_f32_16x16x32_bf16 v[24:27], v[148:151], v[218:221], v[24:27]
	v_mfma_f32_16x16x32_bf16 v[20:23], v[156:159], v[218:221], v[20:23]
	v_mfma_f32_16x16x32_bf16 v[4:7], v[156:159], v[226:229], v[4:7]
	v_mfma_f32_16x16x32_bf16 v[8:11], v[148:151], v[226:229], v[8:11]
	v_mfma_f32_16x16x32_bf16 v[56:59], v[152:155], v[168:171], v[56:59]
	v_mfma_f32_16x16x32_bf16 v[52:55], v[160:163], v[168:171], v[52:55]
	v_mfma_f32_16x16x32_bf16 v[36:39], v[160:163], v[214:217], v[36:39]
	v_mfma_f32_16x16x32_bf16 v[40:43], v[152:155], v[214:217], v[40:43]
	v_mfma_f32_16x16x32_bf16 v[24:27], v[152:155], v[222:225], v[24:27]
	v_mfma_f32_16x16x32_bf16 v[20:23], v[160:163], v[222:225], v[20:23]
	v_mfma_f32_16x16x32_bf16 v[4:7], v[160:163], v[230:233], v[4:7]
	v_mfma_f32_16x16x32_bf16 v[8:11], v[152:155], v[230:233], v[8:11]
	s_setprio 0
	s_barrier
	v_add_u32_e32 v144, s52, v206
	v_add_u32_e32 v160, s53, v206
	ds_read_b128 v[132:135], v144
	ds_read_b128 v[136:139], v144 offset:1024
	ds_read_b128 v[140:143], v144 offset:2048
	ds_read_b128 v[144:147], v144 offset:3072
	ds_read_b128 v[148:151], v160
	ds_read_b128 v[152:155], v160 offset:1024
	ds_read_b128 v[156:159], v160 offset:2048
	ds_read_b128 v[160:163], v160 offset:3072
	s_add_u32 s30, s30, 0x2b0000
	s_addc_u32 s31, s31, 0
	s_mov_b32 m0, s55
	v_lshl_add_u64 v[242:243], s[30:31], 0, v[172:173]
	ds_read_b128 v[164:167], v207 offset:32768
	ds_read_b128 v[168:171], v207 offset:33792
	ds_read_b128 v[210:213], v207 offset:34816
	ds_read_b128 v[214:217], v207 offset:35840
	ds_read_b128 v[218:221], v207 offset:36864
	ds_read_b128 v[222:225], v207 offset:37888
	ds_read_b128 v[226:229], v207 offset:38912
	ds_read_b128 v[230:233], v207 offset:39936
	global_load_lds_dwordx4 v[242:243], off
	v_lshl_add_u64 v[242:243], s[30:31], 0, v[176:177]
	s_mov_b32 m0, s56
	s_nop 0
	global_load_lds_dwordx4 v[242:243], off
	s_waitcnt vmcnt(8)
	s_waitcnt lgkmcnt(0)
	s_barrier
	s_setprio 3
	s_waitcnt lgkmcnt(0)
	v_mfma_f32_16x16x32_bf16 v[128:131], v[132:135], v[164:167], v[128:131]
	v_mfma_f32_16x16x32_bf16 v[124:127], v[140:143], v[164:167], v[124:127]
	v_mfma_f32_16x16x32_bf16 v[96:99], v[140:143], v[210:213], v[96:99]
	v_mfma_f32_16x16x32_bf16 v[100:103], v[132:135], v[210:213], v[100:103]
	v_mfma_f32_16x16x32_bf16 v[112:115], v[132:135], v[218:221], v[112:115]
	v_mfma_f32_16x16x32_bf16 v[108:111], v[140:143], v[218:221], v[108:111]
	v_mfma_f32_16x16x32_bf16 v[76:79], v[140:143], v[226:229], v[76:79]
	v_mfma_f32_16x16x32_bf16 v[80:83], v[132:135], v[226:229], v[80:83]
	v_mfma_f32_16x16x32_bf16 v[128:131], v[136:139], v[168:171], v[128:131]
	v_mfma_f32_16x16x32_bf16 v[124:127], v[144:147], v[168:171], v[124:127]
	v_mfma_f32_16x16x32_bf16 v[96:99], v[144:147], v[214:217], v[96:99]
	v_mfma_f32_16x16x32_bf16 v[100:103], v[136:139], v[214:217], v[100:103]
	v_mfma_f32_16x16x32_bf16 v[112:115], v[136:139], v[222:225], v[112:115]
	v_mfma_f32_16x16x32_bf16 v[108:111], v[144:147], v[222:225], v[108:111]
	v_mfma_f32_16x16x32_bf16 v[76:79], v[144:147], v[230:233], v[76:79]
	v_mfma_f32_16x16x32_bf16 v[80:83], v[136:139], v[230:233], v[80:83]
	s_setprio 0
	s_setprio 3
	v_mfma_f32_16x16x32_bf16 v[120:123], v[148:151], v[164:167], v[120:123]
	v_mfma_f32_16x16x32_bf16 v[116:119], v[156:159], v[164:167], v[116:119]
	v_mfma_f32_16x16x32_bf16 v[88:91], v[156:159], v[210:213], v[88:91]
	v_mfma_f32_16x16x32_bf16 v[92:95], v[148:151], v[210:213], v[92:95]
	v_mfma_f32_16x16x32_bf16 v[104:107], v[148:151], v[218:221], v[104:107]
	v_mfma_f32_16x16x32_bf16 v[84:87], v[156:159], v[218:221], v[84:87]
	v_mfma_f32_16x16x32_bf16 v[68:71], v[156:159], v[226:229], v[68:71]
	v_mfma_f32_16x16x32_bf16 v[72:75], v[148:151], v[226:229], v[72:75]
	v_mfma_f32_16x16x32_bf16 v[120:123], v[152:155], v[168:171], v[120:123]
	v_mfma_f32_16x16x32_bf16 v[116:119], v[160:163], v[168:171], v[116:119]
	v_mfma_f32_16x16x32_bf16 v[88:91], v[160:163], v[214:217], v[88:91]
	v_mfma_f32_16x16x32_bf16 v[92:95], v[152:155], v[214:217], v[92:95]
	v_mfma_f32_16x16x32_bf16 v[104:107], v[152:155], v[222:225], v[104:107]
	v_mfma_f32_16x16x32_bf16 v[84:87], v[160:163], v[222:225], v[84:87]
	v_mfma_f32_16x16x32_bf16 v[68:71], v[160:163], v[230:233], v[68:71]
	v_mfma_f32_16x16x32_bf16 v[72:75], v[152:155], v[230:233], v[72:75]
	s_setprio 0
	s_barrier
; #define PG8_STAGE(bufoff, gbase, voff) do { _Pragma("unroll") for (int _i = 0; _i < 2; ++_i) \
;         __builtin_amdgcn_global_load_lds((const unsigned*)((const char*)(gbase) + (voff)[_i]), (PG8_LAS unsigned*)(lds + (bufoff) + ldsw + _i * 8192), 16, 0, 0); } while (0)
; #define PG8_LDA(dst, b, h) do { _Pragma("unroll") for (int m = 0; m < 4; ++m) _Pragma("unroll") for (int k = 0; k < 2; ++k) dst[m][k] = *(const PG8_LAS bf16x8*)(lds + PG8_SA(b, h) + aoff + m * 2048 + k * 1024); } while (0)
; #define PG8_MMA(ai, bj, At, Bt) do { __builtin_amdgcn_s_setprio(3); _Pragma("unroll") for (int m = 0; m < 4; ++m) _Pragma("unroll") for (int n = 0; n < 2; ++n) _Pragma("unroll") for (int k = 0; k < 2; ++k) \
;         acc[ai][bj][m][n] = __builtin_amdgcn_mfma_f32_16x16x32_bf16(Bt[n][k], At[m][k], acc[ai][bj][m][n], 0, 0, 0); __builtin_amdgcn_s_setprio(0); } while (0)
; #define PG8_WAIT_V(n) asm volatile("s_waitcnt vmcnt(" #n ")" ::: "memory")
; #define PG8_WAIT_L(n) asm volatile("s_waitcnt lgkmcnt(" #n ")" ::: "memory")
; #define PG8_BAR __builtin_amdgcn_s_barrier()
; #define PG8_SCHED __builtin_amdgcn_sched_barrier(0)
; template <class Epi, class Sched, bool ALIGN_EPI = false, bool SP2 = false>
; __device__ __forceinline__ void gemm_phase(PG8_LAS unsigned char* lds, const Gemm g, const Sched& S, const Epi& E) {
;     ...
;             PG8_LDA(At, 1, 1); PG8_STAGE(PG8_SB(1, 0), b3, voffB); PG8_STAGE(PG8_SB(1, 1), b3 + hstepB, voffB); PG8_STAGE(PG8_SA(1, 0), a3, voffA);
;             PG8_WAIT_V(8); PG8_WAIT_L(0); PG8_BAR; PG8_MMA(1, 0, At, B0); PG8_MMA(1, 1, At, B1); PG8_BAR; PG8_SCHED;
	s_mov_b32 m0, s77
	v_lshl_add_u64 v[234:235], v[234:235], 0, s[4:5]
	s_add_u32 s28, s28, 0x2b0080
	ds_read_b128 v[164:167], v207 offset:49152
	ds_read_b128 v[168:171], v207 offset:50176
	ds_read_b128 v[210:213], v207 offset:51200
	ds_read_b128 v[214:217], v207 offset:52224
	ds_read_b128 v[218:221], v207 offset:53248
	ds_read_b128 v[222:225], v207 offset:54272
	ds_read_b128 v[226:229], v207 offset:55296
	ds_read_b128 v[230:233], v207 offset:56320
	global_load_lds_dwordx4 v[234:235], off
	v_lshl_add_u64 v[234:235], v[236:237], 0, s[4:5]
	s_mov_b32 m0, s78
	s_addc_u32 s29, s29, 0
	global_load_lds_dwordx4 v[234:235], off
	v_lshl_add_u64 v[234:235], s[28:29], 0, v[174:175]
	s_mov_b32 m0, s79
	s_nop 0
	global_load_lds_dwordx4 v[234:235], off
	v_lshl_add_u64 v[234:235], s[28:29], 0, v[178:179]
	s_mov_b32 m0, s80
	s_nop 0
	global_load_lds_dwordx4 v[234:235], off
	v_lshl_add_u64 v[234:235], v[238:239], 0, s[4:5]
	s_mov_b32 m0, s57
	s_nop 0
	global_load_lds_dwordx4 v[234:235], off
	v_lshl_add_u64 v[234:235], v[240:241], 0, s[4:5]
	s_mov_b32 m0, s58
	s_nop 0
	global_load_lds_dwordx4 v[234:235], off
	s_waitcnt vmcnt(8)
	s_waitcnt lgkmcnt(0)
	s_barrier
	s_setprio 3
	s_waitcnt lgkmcnt(0)
	v_mfma_f32_16x16x32_bf16 v[64:67], v[132:135], v[164:167], v[64:67]
	v_mfma_f32_16x16x32_bf16 v[60:63], v[140:143], v[164:167], v[60:63]
	v_mfma_f32_16x16x32_bf16 v[44:47], v[140:143], v[210:213], v[44:47]
	v_mfma_f32_16x16x32_bf16 v[48:51], v[132:135], v[210:213], v[48:51]
	v_mfma_f32_16x16x32_bf16 v[32:35], v[132:135], v[218:221], v[32:35]
	v_mfma_f32_16x16x32_bf16 v[28:31], v[140:143], v[218:221], v[28:31]
	v_mfma_f32_16x16x32_bf16 v[12:15], v[140:143], v[226:229], v[12:15]
	v_mfma_f32_16x16x32_bf16 v[16:19], v[132:135], v[226:229], v[16:19]
	v_mfma_f32_16x16x32_bf16 v[64:67], v[136:139], v[168:171], v[64:67]
	v_mfma_f32_16x16x32_bf16 v[60:63], v[144:147], v[168:171], v[60:63]
	v_mfma_f32_16x16x32_bf16 v[44:47], v[144:147], v[214:217], v[44:47]
	v_mfma_f32_16x16x32_bf16 v[48:51], v[136:139], v[214:217], v[48:51]
	v_mfma_f32_16x16x32_bf16 v[32:35], v[136:139], v[222:225], v[32:35]
	v_mfma_f32_16x16x32_bf16 v[28:31], v[144:147], v[222:225], v[28:31]
	v_mfma_f32_16x16x32_bf16 v[12:15], v[144:147], v[230:233], v[12:15]
	v_mfma_f32_16x16x32_bf16 v[16:19], v[136:139], v[230:233], v[16:19]
	s_setprio 0
	s_setprio 3
	v_mfma_f32_16x16x32_bf16 v[56:59], v[148:151], v[164:167], v[56:59]
	v_mfma_f32_16x16x32_bf16 v[52:55], v[156:159], v[164:167], v[52:55]
	v_mfma_f32_16x16x32_bf16 v[36:39], v[156:159], v[210:213], v[36:39]
	v_mfma_f32_16x16x32_bf16 v[40:43], v[148:151], v[210:213], v[40:43]
	v_mfma_f32_16x16x32_bf16 v[24:27], v[148:151], v[218:221], v[24:27]
	v_mfma_f32_16x16x32_bf16 v[20:23], v[156:159], v[218:221], v[20:23]
	v_mfma_f32_16x16x32_bf16 v[4:7], v[156:159], v[226:229], v[4:7]
	v_mfma_f32_16x16x32_bf16 v[8:11], v[148:151], v[226:229], v[8:11]
	v_mfma_f32_16x16x32_bf16 v[56:59], v[152:155], v[168:171], v[56:59]
	v_mfma_f32_16x16x32_bf16 v[52:55], v[160:163], v[168:171], v[52:55]
	v_mfma_f32_16x16x32_bf16 v[36:39], v[160:163], v[214:217], v[36:39]
	v_mfma_f32_16x16x32_bf16 v[40:43], v[152:155], v[214:217], v[40:43]
	v_mfma_f32_16x16x32_bf16 v[24:27], v[152:155], v[222:225], v[24:27]
	v_mfma_f32_16x16x32_bf16 v[20:23], v[160:163], v[222:225], v[20:23]
	v_mfma_f32_16x16x32_bf16 v[4:7], v[160:163], v[230:233], v[4:7]
	v_mfma_f32_16x16x32_bf16 v[8:11], v[152:155], v[230:233], v[8:11]
	s_setprio 0
	s_barrier
	s_add_i32 s61, s61, 2
	s_add_u32 s12, s12, 0x100
	s_addc_u32 s13, s13, 0
	s_cmpk_gt_u32 s61, 0xa9
	s_cbranch_scc1 .LBB0_978

; #define PG8_STAGE(bufoff, gbase, voff) do { _Pragma("unroll") for (int _i = 0; _i < 2; ++_i) \
;         __builtin_amdgcn_global_load_lds((const unsigned*)((const char*)(gbase) + (voff)[_i]), (PG8_LAS unsigned*)(lds + (bufoff) + ldsw + _i * 8192), 16, 0, 0); } while (0)
; #define PG8_LDA(dst, b, h) do { _Pragma("unroll") for (int m = 0; m < 4; ++m) _Pragma("unroll") for (int k = 0; k < 2; ++k) dst[m][k] = *(const PG8_LAS bf16x8*)(lds + PG8_SA(b, h) + aoff + m * 2048 + k * 1024); } while (0)
; #define PG8_LDB(dst, b, h) do { _Pragma("unroll") for (int n = 0; n < 2; ++n) _Pragma("unroll") for (int k = 0; k < 2; ++k) dst[n][k] = *(const PG8_LAS bf16x8*)(lds + PG8_SB(b, h) + boff + n * 2048 + k * 1024); } while (0)
; #define PG8_MMA(ai, bj, At, Bt) do { __builtin_amdgcn_s_setprio(3); _Pragma("unroll") for (int m = 0; m < 4; ++m) _Pragma("unroll") for (int n = 0; n < 2; ++n) _Pragma("unroll") for (int k = 0; k < 2; ++k) \
;         acc[ai][bj][m][n] = __builtin_amdgcn_mfma_f32_16x16x32_bf16(Bt[n][k], At[m][k], acc[ai][bj][m][n], 0, 0, 0); __builtin_amdgcn_s_setprio(0); } while (0)
; #define PG8_WAIT_V(n) asm volatile("s_waitcnt vmcnt(" #n ")" ::: "memory")
; #define PG8_WAIT_L(n) asm volatile("s_waitcnt lgkmcnt(" #n ")" ::: "memory")
; template <class Epi, class Sched, bool ALIGN_EPI = false, bool SP2 = false>
; __device__ __forceinline__ void gemm_phase(PG8_LAS unsigned char* lds, const Gemm g, const Sched& S, const Epi& E) {
;     ...
;         for (int t = 0; t < nt; t += 2) {
;             const bool last = (t == nt - 2);
;             const char* a1 = cA + (size_t)(t + 1) * kstep;
;             const char* a2 = last ? nA : cA + (size_t)(t + 2) * kstep; const char* b2 = last ? nB : cB + (size_t)(t + 2) * kstep;
;             const char* a3 = a2 + kstep; const char* b3 = b2 + kstep;
;             if (last && has_next) S.a_ready(nxt);
;             if constexpr (Epi::MIDK) { if (t == E.midk_step(nt)) E.midk(acc, cur, wr, wc, fr, fq); }
;             if constexpr (SP2) {
;             PG8_LDB(B0, 0, 0); PG8_LDB(B1, 0, 1); PG8_SCHED; PG8_LDA(At, 0, 0); PG8_STAGE(PG8_SA(1, 1), a1 + hstepA, voffA);
;             PG8_WAIT_V(8); PG8_WAIT_L(0); PG8_BAR; PG8_MMA(0, 0, At, B0); PG8_MMA(0, 1, At, B1); PG8_BAR; PG8_SCHED;
;             PG8_LDA(At, 0, 1); PG8_STAGE(PG8_SB(0, 0), b2, voffB); PG8_STAGE(PG8_SB(0, 1), b2 + hstepB, voffB); PG8_STAGE(PG8_SA(0, 0), a2, voffA);
.LBB0_1018:
	v_add_u32_e32 v142, s46, v189
	v_add_u32_e32 v158, s47, v189
	s_add_u32 s40, s20, s22
	ds_read_b128 v[130:133], v142
	ds_read_b128 v[134:137], v142 offset:1024
	ds_read_b128 v[138:141], v142 offset:2048
	ds_read_b128 v[142:145], v142 offset:3072
	ds_read_b128 v[146:149], v158
	ds_read_b128 v[150:153], v158 offset:1024
	ds_read_b128 v[154:157], v158 offset:2048
	ds_read_b128 v[158:161], v158 offset:3072
	s_addc_u32 s41, s21, s23
	s_add_u32 s40, s40, 0x21500100
	s_addc_u32 s41, s41, 0
	s_add_u32 s87, s44, s22
	s_addc_u32 s88, s45, s23
	s_cmpk_eq_i32 s22, 0x5500
	s_cselect_b32 s43, s17, s41
	s_cselect_b32 s42, s16, s40
	s_cselect_b32 s41, s11, s88
	s_cselect_b32 s40, s10, s87
	s_mov_b32 m0, s77
	v_lshl_add_u64 v[186:187], v[0:1], 0, s[22:23]
	ds_read_b128 v[162:165], v180
	ds_read_b128 v[166:169], v180 offset:1024
	ds_read_b128 v[182:185], v180 offset:2048
	ds_read_b128 v[190:193], v180 offset:3072
	ds_read_b128 v[194:197], v180 offset:4096
	ds_read_b128 v[208:211], v180 offset:5120
	ds_read_b128 v[212:215], v180 offset:6144
	ds_read_b128 v[216:219], v180 offset:7168
	global_load_lds_dwordx4 v[186:187], off
	v_lshl_add_u64 v[186:187], v[170:171], 0, s[22:23]
	s_mov_b32 m0, s78
	s_nop 0
	global_load_lds_dwordx4 v[186:187], off
	s_waitcnt vmcnt(8)
	s_waitcnt lgkmcnt(0)
	s_barrier
	s_setprio 3
	s_waitcnt lgkmcnt(0)
	v_mfma_f32_16x16x32_bf16 v[126:129], v[130:133], v[162:165], v[126:129]
	v_mfma_f32_16x16x32_bf16 v[122:125], v[138:141], v[162:165], v[122:125]
	v_mfma_f32_16x16x32_bf16 v[94:97], v[138:141], v[182:185], v[94:97]
	v_mfma_f32_16x16x32_bf16 v[98:101], v[130:133], v[182:185], v[98:101]
	v_mfma_f32_16x16x32_bf16 v[110:113], v[130:133], v[194:197], v[110:113]
	v_mfma_f32_16x16x32_bf16 v[106:109], v[138:141], v[194:197], v[106:109]
	v_mfma_f32_16x16x32_bf16 v[74:77], v[138:141], v[212:215], v[74:77]
	v_mfma_f32_16x16x32_bf16 v[78:81], v[130:133], v[212:215], v[78:81]
	v_mfma_f32_16x16x32_bf16 v[126:129], v[134:137], v[166:169], v[126:129]
	v_mfma_f32_16x16x32_bf16 v[122:125], v[142:145], v[166:169], v[122:125]
	v_mfma_f32_16x16x32_bf16 v[94:97], v[142:145], v[190:193], v[94:97]
	v_mfma_f32_16x16x32_bf16 v[98:101], v[134:137], v[190:193], v[98:101]
	v_mfma_f32_16x16x32_bf16 v[110:113], v[134:137], v[208:211], v[110:113]
	v_mfma_f32_16x16x32_bf16 v[106:109], v[142:145], v[208:211], v[106:109]
	v_mfma_f32_16x16x32_bf16 v[74:77], v[142:145], v[216:219], v[74:77]
	v_mfma_f32_16x16x32_bf16 v[78:81], v[134:137], v[216:219], v[78:81]
	s_setprio 0
	s_setprio 3
	v_mfma_f32_16x16x32_bf16 v[118:121], v[146:149], v[162:165], v[118:121]
	v_mfma_f32_16x16x32_bf16 v[114:117], v[154:157], v[162:165], v[114:117]
	v_mfma_f32_16x16x32_bf16 v[86:89], v[154:157], v[182:185], v[86:89]
	v_mfma_f32_16x16x32_bf16 v[90:93], v[146:149], v[182:185], v[90:93]
	v_mfma_f32_16x16x32_bf16 v[102:105], v[146:149], v[194:197], v[102:105]
	v_mfma_f32_16x16x32_bf16 v[82:85], v[154:157], v[194:197], v[82:85]
	v_mfma_f32_16x16x32_bf16 v[66:69], v[154:157], v[212:215], v[66:69]
	v_mfma_f32_16x16x32_bf16 v[70:73], v[146:149], v[212:215], v[70:73]
	v_mfma_f32_16x16x32_bf16 v[118:121], v[150:153], v[166:169], v[118:121]
	v_mfma_f32_16x16x32_bf16 v[114:117], v[158:161], v[166:169], v[114:117]
	v_mfma_f32_16x16x32_bf16 v[86:89], v[158:161], v[190:193], v[86:89]
	v_mfma_f32_16x16x32_bf16 v[90:93], v[150:153], v[190:193], v[90:93]
	v_mfma_f32_16x16x32_bf16 v[102:105], v[150:153], v[208:211], v[102:105]
	v_mfma_f32_16x16x32_bf16 v[82:85], v[158:161], v[208:211], v[82:85]
	v_mfma_f32_16x16x32_bf16 v[66:69], v[158:161], v[216:219], v[66:69]
	v_mfma_f32_16x16x32_bf16 v[70:73], v[150:153], v[216:219], v[70:73]
	s_setprio 0
	s_barrier
	s_mov_b32 m0, s79
	v_lshl_add_u64 v[186:187], s[40:41], 0, v[174:175]
	s_add_u32 s88, s40, 0x2b0000
	ds_read_b128 v[162:165], v180 offset:16384
	ds_read_b128 v[166:169], v180 offset:17408
	ds_read_b128 v[182:185], v180 offset:18432
	ds_read_b128 v[190:193], v180 offset:19456
	ds_read_b128 v[194:197], v180 offset:20480
	ds_read_b128 v[208:211], v180 offset:21504
	ds_read_b128 v[212:215], v180 offset:22528
	ds_read_b128 v[216:219], v180 offset:23552
	global_load_lds_dwordx4 v[186:187], off
	v_lshl_add_u64 v[198:199], s[40:41], 0, v[178:179]
	s_mov_b32 m0, s80
	s_addc_u32 s89, s41, 0
	global_load_lds_dwordx4 v[198:199], off
	v_lshl_add_u64 v[204:205], s[88:89], 0, v[174:175]
	s_mov_b32 m0, s81
	v_lshl_add_u64 v[220:221], s[42:43], 0, v[176:177]
	global_load_lds_dwordx4 v[204:205], off
	v_lshl_add_u64 v[204:205], s[88:89], 0, v[178:179]
	s_mov_b32 m0, s82
	s_nop 0
	global_load_lds_dwordx4 v[204:205], off
	v_lshl_add_u64 v[204:205], s[42:43], 0, v[172:173]
	s_mov_b32 m0, s58
	s_nop 0
	global_load_lds_dwordx4 v[204:205], off
	s_mov_b32 m0, s60
	s_nop 0
	global_load_lds_dwordx4 v[220:221], off
	s_waitcnt vmcnt(8)
	s_waitcnt lgkmcnt(0)
	s_barrier
; #define PG8_STAGE(bufoff, gbase, voff) do { _Pragma("unroll") for (int _i = 0; _i < 2; ++_i) \
;         __builtin_amdgcn_global_load_lds((const unsigned*)((const char*)(gbase) + (voff)[_i]), (PG8_LAS unsigned*)(lds + (bufoff) + ldsw + _i * 8192), 16, 0, 0); } while (0)
; #define PG8_LDA(dst, b, h) do { _Pragma("unroll") for (int m = 0; m < 4; ++m) _Pragma("unroll") for (int k = 0; k < 2; ++k) dst[m][k] = *(const PG8_LAS bf16x8*)(lds + PG8_SA(b, h) + aoff + m * 2048 + k * 1024); } while (0)
; #define PG8_LDB(dst, b, h) do { _Pragma("unroll") for (int n = 0; n < 2; ++n) _Pragma("unroll") for (int k = 0; k < 2; ++k) dst[n][k] = *(const PG8_LAS bf16x8*)(lds + PG8_SB(b, h) + boff + n * 2048 + k * 1024); } while (0)
; #define PG8_MMA(ai, bj, At, Bt) do { __builtin_amdgcn_s_setprio(3); _Pragma("unroll") for (int m = 0; m < 4; ++m) _Pragma("unroll") for (int n = 0; n < 2; ++n) _Pragma("unroll") for (int k = 0; k < 2; ++k) \
;         acc[ai][bj][m][n] = __builtin_amdgcn_mfma_f32_16x16x32_bf16(Bt[n][k], At[m][k], acc[ai][bj][m][n], 0, 0, 0); __builtin_amdgcn_s_setprio(0); } while (0)
; #define PG8_WAIT_V(n) asm volatile("s_waitcnt vmcnt(" #n ")" ::: "memory")
; #define PG8_WAIT_L(n) asm volatile("s_waitcnt lgkmcnt(" #n ")" ::: "memory")
; #define PG8_BAR __builtin_amdgcn_s_barrier()
; #define PG8_SCHED __builtin_amdgcn_sched_barrier(0)
; template <class Epi, class Sched, bool ALIGN_EPI = false, bool SP2 = false>
; __device__ __forceinline__ void gemm_phase(PG8_LAS unsigned char* lds, const Gemm g, const Sched& S, const Epi& E) {
;     ...
;             PG8_WAIT_V(8); PG8_WAIT_L(0); PG8_BAR; PG8_MMA(1, 0, At, B0); PG8_MMA(1, 1, At, B1); PG8_BAR; PG8_SCHED;
;             PG8_LDB(B0, 1, 0); PG8_LDB(B1, 1, 1); PG8_SCHED; PG8_LDA(At, 1, 0); PG8_STAGE(PG8_SA(0, 1), a2 + hstepA, voffA);
;             PG8_WAIT_V(8); PG8_WAIT_L(0); PG8_BAR; PG8_MMA(0, 0, At, B0); PG8_MMA(0, 1, At, B1); PG8_BAR; PG8_SCHED;
	s_setprio 3
	s_waitcnt lgkmcnt(0)
	v_mfma_f32_16x16x32_bf16 v[62:65], v[130:133], v[162:165], v[62:65]
	v_mfma_f32_16x16x32_bf16 v[58:61], v[138:141], v[162:165], v[58:61]
	v_mfma_f32_16x16x32_bf16 v[42:45], v[138:141], v[182:185], v[42:45]
	v_mfma_f32_16x16x32_bf16 v[46:49], v[130:133], v[182:185], v[46:49]
	v_mfma_f32_16x16x32_bf16 v[30:33], v[130:133], v[194:197], v[30:33]
	v_mfma_f32_16x16x32_bf16 v[26:29], v[138:141], v[194:197], v[26:29]
	v_mfma_f32_16x16x32_bf16 v[10:13], v[138:141], v[212:215], v[10:13]
	v_mfma_f32_16x16x32_bf16 v[14:17], v[130:133], v[212:215], v[14:17]
	v_mfma_f32_16x16x32_bf16 v[62:65], v[134:137], v[166:169], v[62:65]
	v_mfma_f32_16x16x32_bf16 v[58:61], v[142:145], v[166:169], v[58:61]
	v_mfma_f32_16x16x32_bf16 v[42:45], v[142:145], v[190:193], v[42:45]
	v_mfma_f32_16x16x32_bf16 v[46:49], v[134:137], v[190:193], v[46:49]
	v_mfma_f32_16x16x32_bf16 v[30:33], v[134:137], v[208:211], v[30:33]
	v_mfma_f32_16x16x32_bf16 v[26:29], v[142:145], v[208:211], v[26:29]
	v_mfma_f32_16x16x32_bf16 v[10:13], v[142:145], v[216:219], v[10:13]
	v_mfma_f32_16x16x32_bf16 v[14:17], v[134:137], v[216:219], v[14:17]
	s_setprio 0
	s_setprio 3
	v_mfma_f32_16x16x32_bf16 v[54:57], v[146:149], v[162:165], v[54:57]
	v_mfma_f32_16x16x32_bf16 v[50:53], v[154:157], v[162:165], v[50:53]
	v_mfma_f32_16x16x32_bf16 v[34:37], v[154:157], v[182:185], v[34:37]
	v_mfma_f32_16x16x32_bf16 v[38:41], v[146:149], v[182:185], v[38:41]
	v_mfma_f32_16x16x32_bf16 v[22:25], v[146:149], v[194:197], v[22:25]
	v_mfma_f32_16x16x32_bf16 v[18:21], v[154:157], v[194:197], v[18:21]
	v_mfma_f32_16x16x32_bf16 v[2:5], v[154:157], v[212:215], v[2:5]
	v_mfma_f32_16x16x32_bf16 v[6:9], v[146:149], v[212:215], v[6:9]
	v_mfma_f32_16x16x32_bf16 v[54:57], v[150:153], v[166:169], v[54:57]
	v_mfma_f32_16x16x32_bf16 v[50:53], v[158:161], v[166:169], v[50:53]
	v_mfma_f32_16x16x32_bf16 v[34:37], v[158:161], v[190:193], v[34:37]
	v_mfma_f32_16x16x32_bf16 v[38:41], v[150:153], v[190:193], v[38:41]
	v_mfma_f32_16x16x32_bf16 v[22:25], v[150:153], v[208:211], v[22:25]
	v_mfma_f32_16x16x32_bf16 v[18:21], v[158:161], v[208:211], v[18:21]
	v_mfma_f32_16x16x32_bf16 v[2:5], v[158:161], v[216:219], v[2:5]
	v_mfma_f32_16x16x32_bf16 v[6:9], v[150:153], v[216:219], v[6:9]
	s_setprio 0
	s_barrier
	v_add_u32_e32 v142, s52, v189
	v_add_u32_e32 v158, s53, v189
	ds_read_b128 v[130:133], v142
	ds_read_b128 v[134:137], v142 offset:1024
	ds_read_b128 v[138:141], v142 offset:2048
	ds_read_b128 v[142:145], v142 offset:3072
	ds_read_b128 v[146:149], v158
	ds_read_b128 v[150:153], v158 offset:1024
	ds_read_b128 v[154:157], v158 offset:2048
	ds_read_b128 v[158:161], v158 offset:3072
	s_add_u32 s42, s42, 0x2b0000
	s_addc_u32 s43, s43, 0
	s_mov_b32 m0, s61
	v_lshl_add_u64 v[222:223], s[42:43], 0, v[172:173]
	ds_read_b128 v[162:165], v180 offset:32768
	ds_read_b128 v[166:169], v180 offset:33792
	ds_read_b128 v[182:185], v180 offset:34816
	ds_read_b128 v[190:193], v180 offset:35840
	ds_read_b128 v[194:197], v180 offset:36864
	ds_read_b128 v[208:211], v180 offset:37888
	ds_read_b128 v[212:215], v180 offset:38912
	ds_read_b128 v[216:219], v180 offset:39936
	global_load_lds_dwordx4 v[222:223], off
	v_lshl_add_u64 v[222:223], s[42:43], 0, v[176:177]
	s_mov_b32 m0, s62
	s_nop 0
	global_load_lds_dwordx4 v[222:223], off
	s_waitcnt vmcnt(8)
	s_waitcnt lgkmcnt(0)
	s_barrier
	s_setprio 3
	s_waitcnt lgkmcnt(0)
	v_mfma_f32_16x16x32_bf16 v[126:129], v[130:133], v[162:165], v[126:129]
	v_mfma_f32_16x16x32_bf16 v[122:125], v[138:141], v[162:165], v[122:125]
	v_mfma_f32_16x16x32_bf16 v[94:97], v[138:141], v[182:185], v[94:97]
	v_mfma_f32_16x16x32_bf16 v[98:101], v[130:133], v[182:185], v[98:101]
	v_mfma_f32_16x16x32_bf16 v[110:113], v[130:133], v[194:197], v[110:113]
	v_mfma_f32_16x16x32_bf16 v[106:109], v[138:141], v[194:197], v[106:109]
	v_mfma_f32_16x16x32_bf16 v[74:77], v[138:141], v[212:215], v[74:77]
	v_mfma_f32_16x16x32_bf16 v[78:81], v[130:133], v[212:215], v[78:81]
	v_mfma_f32_16x16x32_bf16 v[126:129], v[134:137], v[166:169], v[126:129]
	v_mfma_f32_16x16x32_bf16 v[122:125], v[142:145], v[166:169], v[122:125]
	v_mfma_f32_16x16x32_bf16 v[94:97], v[142:145], v[190:193], v[94:97]
	v_mfma_f32_16x16x32_bf16 v[98:101], v[134:137], v[190:193], v[98:101]
	v_mfma_f32_16x16x32_bf16 v[110:113], v[134:137], v[208:211], v[110:113]
	v_mfma_f32_16x16x32_bf16 v[106:109], v[142:145], v[208:211], v[106:109]
	v_mfma_f32_16x16x32_bf16 v[74:77], v[142:145], v[216:219], v[74:77]
	v_mfma_f32_16x16x32_bf16 v[78:81], v[134:137], v[216:219], v[78:81]
	s_setprio 0
	s_setprio 3
	v_mfma_f32_16x16x32_bf16 v[118:121], v[146:149], v[162:165], v[118:121]
	v_mfma_f32_16x16x32_bf16 v[114:117], v[154:157], v[162:165], v[114:117]
	v_mfma_f32_16x16x32_bf16 v[86:89], v[154:157], v[182:185], v[86:89]
	v_mfma_f32_16x16x32_bf16 v[90:93], v[146:149], v[182:185], v[90:93]
	v_mfma_f32_16x16x32_bf16 v[102:105], v[146:149], v[194:197], v[102:105]
	v_mfma_f32_16x16x32_bf16 v[82:85], v[154:157], v[194:197], v[82:85]
	v_mfma_f32_16x16x32_bf16 v[66:69], v[154:157], v[212:215], v[66:69]
	v_mfma_f32_16x16x32_bf16 v[70:73], v[146:149], v[212:215], v[70:73]
	v_mfma_f32_16x16x32_bf16 v[118:121], v[150:153], v[166:169], v[118:121]
	v_mfma_f32_16x16x32_bf16 v[114:117], v[158:161], v[166:169], v[114:117]
	v_mfma_f32_16x16x32_bf16 v[86:89], v[158:161], v[190:193], v[86:89]
	v_mfma_f32_16x16x32_bf16 v[90:93], v[150:153], v[190:193], v[90:93]
	v_mfma_f32_16x16x32_bf16 v[102:105], v[150:153], v[208:211], v[102:105]
	v_mfma_f32_16x16x32_bf16 v[82:85], v[158:161], v[208:211], v[82:85]
	v_mfma_f32_16x16x32_bf16 v[66:69], v[158:161], v[216:219], v[66:69]
	v_mfma_f32_16x16x32_bf16 v[70:73], v[150:153], v[216:219], v[70:73]
	s_setprio 0
	s_barrier
; #define PG8_STAGE(bufoff, gbase, voff) do { _Pragma("unroll") for (int _i = 0; _i < 2; ++_i) \
;         __builtin_amdgcn_global_load_lds((const unsigned*)((const char*)(gbase) + (voff)[_i]), (PG8_LAS unsigned*)(lds + (bufoff) + ldsw + _i * 8192), 16, 0, 0); } while (0)
; #define PG8_LDA(dst, b, h) do { _Pragma("unroll") for (int m = 0; m < 4; ++m) _Pragma("unroll") for (int k = 0; k < 2; ++k) dst[m][k] = *(const PG8_LAS bf16x8*)(lds + PG8_SA(b, h) + aoff + m * 2048 + k * 1024); } while (0)
; #define PG8_MMA(ai, bj, At, Bt) do { __builtin_amdgcn_s_setprio(3); _Pragma("unroll") for (int m = 0; m < 4; ++m) _Pragma("unroll") for (int n = 0; n < 2; ++n) _Pragma("unroll") for (int k = 0; k < 2; ++k) \
;         acc[ai][bj][m][n] = __builtin_amdgcn_mfma_f32_16x16x32_bf16(Bt[n][k], At[m][k], acc[ai][bj][m][n], 0, 0, 0); __builtin_amdgcn_s_setprio(0); } while (0)
; #define PG8_WAIT_V(n) asm volatile("s_waitcnt vmcnt(" #n ")" ::: "memory")
; #define PG8_WAIT_L(n) asm volatile("s_waitcnt lgkmcnt(" #n ")" ::: "memory")
; #define PG8_BAR __builtin_amdgcn_s_barrier()
; #define PG8_SCHED __builtin_amdgcn_sched_barrier(0)
; template <class Epi, class Sched, bool ALIGN_EPI = false, bool SP2 = false>
; __device__ __forceinline__ void gemm_phase(PG8_LAS unsigned char* lds, const Gemm g, const Sched& S, const Epi& E) {
;     ...
;             PG8_LDA(At, 1, 1); PG8_STAGE(PG8_SB(1, 0), b3, voffB); PG8_STAGE(PG8_SB(1, 1), b3 + hstepB, voffB); PG8_STAGE(PG8_SA(1, 0), a3, voffA);
;             PG8_WAIT_V(8); PG8_WAIT_L(0); PG8_BAR; PG8_MMA(1, 0, At, B0); PG8_MMA(1, 1, At, B1); PG8_BAR; PG8_SCHED;
	s_mov_b32 m0, s83
	v_lshl_add_u64 v[186:187], v[186:187], 0, s[18:19]
	s_add_u32 s40, s40, 0x2b0080
	ds_read_b128 v[162:165], v180 offset:49152
	ds_read_b128 v[166:169], v180 offset:50176
	ds_read_b128 v[182:185], v180 offset:51200
	ds_read_b128 v[190:193], v180 offset:52224
	ds_read_b128 v[194:197], v180 offset:53248
	ds_read_b128 v[208:211], v180 offset:54272
	ds_read_b128 v[212:215], v180 offset:55296
	ds_read_b128 v[216:219], v180 offset:56320
	global_load_lds_dwordx4 v[186:187], off
	v_lshl_add_u64 v[186:187], v[198:199], 0, s[18:19]
	s_mov_b32 m0, s84
	s_addc_u32 s41, s41, 0
	global_load_lds_dwordx4 v[186:187], off
	v_lshl_add_u64 v[186:187], s[40:41], 0, v[174:175]
	s_mov_b32 m0, s85
	s_nop 0
	global_load_lds_dwordx4 v[186:187], off
	v_lshl_add_u64 v[186:187], s[40:41], 0, v[178:179]
	s_mov_b32 m0, s86
	s_nop 0
	global_load_lds_dwordx4 v[186:187], off
	v_lshl_add_u64 v[186:187], v[204:205], 0, s[18:19]
	s_mov_b32 m0, s63
	s_nop 0
	global_load_lds_dwordx4 v[186:187], off
	v_lshl_add_u64 v[186:187], v[220:221], 0, s[18:19]
	s_mov_b32 m0, s64
	s_nop 0
	global_load_lds_dwordx4 v[186:187], off
	s_waitcnt vmcnt(8)
	s_waitcnt lgkmcnt(0)
	s_barrier
	s_setprio 3
	s_waitcnt lgkmcnt(0)
	v_mfma_f32_16x16x32_bf16 v[62:65], v[130:133], v[162:165], v[62:65]
	v_mfma_f32_16x16x32_bf16 v[58:61], v[138:141], v[162:165], v[58:61]
	v_mfma_f32_16x16x32_bf16 v[42:45], v[138:141], v[182:185], v[42:45]
	v_mfma_f32_16x16x32_bf16 v[46:49], v[130:133], v[182:185], v[46:49]
	v_mfma_f32_16x16x32_bf16 v[30:33], v[130:133], v[194:197], v[30:33]
	v_mfma_f32_16x16x32_bf16 v[26:29], v[138:141], v[194:197], v[26:29]
	v_mfma_f32_16x16x32_bf16 v[10:13], v[138:141], v[212:215], v[10:13]
	v_mfma_f32_16x16x32_bf16 v[14:17], v[130:133], v[212:215], v[14:17]
	v_mfma_f32_16x16x32_bf16 v[62:65], v[134:137], v[166:169], v[62:65]
	v_mfma_f32_16x16x32_bf16 v[58:61], v[142:145], v[166:169], v[58:61]
	v_mfma_f32_16x16x32_bf16 v[42:45], v[142:145], v[190:193], v[42:45]
	v_mfma_f32_16x16x32_bf16 v[46:49], v[134:137], v[190:193], v[46:49]
	v_mfma_f32_16x16x32_bf16 v[30:33], v[134:137], v[208:211], v[30:33]
	v_mfma_f32_16x16x32_bf16 v[26:29], v[142:145], v[208:211], v[26:29]
	v_mfma_f32_16x16x32_bf16 v[10:13], v[142:145], v[216:219], v[10:13]
	v_mfma_f32_16x16x32_bf16 v[14:17], v[134:137], v[216:219], v[14:17]
	s_setprio 0
	s_setprio 3
	v_mfma_f32_16x16x32_bf16 v[54:57], v[146:149], v[162:165], v[54:57]
	v_mfma_f32_16x16x32_bf16 v[50:53], v[154:157], v[162:165], v[50:53]
	v_mfma_f32_16x16x32_bf16 v[34:37], v[154:157], v[182:185], v[34:37]
	v_mfma_f32_16x16x32_bf16 v[38:41], v[146:149], v[182:185], v[38:41]
	v_mfma_f32_16x16x32_bf16 v[22:25], v[146:149], v[194:197], v[22:25]
	v_mfma_f32_16x16x32_bf16 v[18:21], v[154:157], v[194:197], v[18:21]
	v_mfma_f32_16x16x32_bf16 v[2:5], v[154:157], v[212:215], v[2:5]
	v_mfma_f32_16x16x32_bf16 v[6:9], v[146:149], v[212:215], v[6:9]
	v_mfma_f32_16x16x32_bf16 v[54:57], v[150:153], v[166:169], v[54:57]
	v_mfma_f32_16x16x32_bf16 v[50:53], v[158:161], v[166:169], v[50:53]
	v_mfma_f32_16x16x32_bf16 v[34:37], v[158:161], v[190:193], v[34:37]
	v_mfma_f32_16x16x32_bf16 v[38:41], v[150:153], v[190:193], v[38:41]
	v_mfma_f32_16x16x32_bf16 v[22:25], v[150:153], v[208:211], v[22:25]
	v_mfma_f32_16x16x32_bf16 v[18:21], v[158:161], v[208:211], v[18:21]
	v_mfma_f32_16x16x32_bf16 v[2:5], v[158:161], v[216:219], v[2:5]
	v_mfma_f32_16x16x32_bf16 v[6:9], v[150:153], v[216:219], v[6:9]
	s_setprio 0
	s_barrier
	s_add_i32 s67, s67, 2
	s_add_u32 s22, s22, 0x100
	s_addc_u32 s23, s23, 0
	s_cmpk_gt_u32 s67, 0xa9
	s_cbranch_scc1 .LBB0_1021
